# v52 with pair order srcB-major (4 consecutive same-accumulator pairs share the srcB fragment pair) in all four GEMM loops
# speedup vs baseline: 1.0147x; 1.0020x over previous
; #define PG8_STAGE(bufoff, gbase, voff) do { _Pragma("unroll") for (int _i = 0; _i < 2; ++_i) \
;         __builtin_amdgcn_global_load_lds((const unsigned*)((const char*)(gbase) + (voff)[_i]), (PG8_LAS unsigned*)(lds + (bufoff) + ldsw + _i * 8192), 16, 0, 0); } while (0)
; #define PG8_LDA(dst, b, h) do { _Pragma("unroll") for (int m = 0; m < 4; ++m) _Pragma("unroll") for (int k = 0; k < 2; ++k) dst[m][k] = *(const PG8_LAS bf16x8*)(lds + PG8_SA(b, h) + aoff + m * 2048 + k * 1024); } while (0)
; #define PG8_LDB(dst, b, h) do { _Pragma("unroll") for (int n = 0; n < 2; ++n) _Pragma("unroll") for (int k = 0; k < 2; ++k) dst[n][k] = *(const PG8_LAS bf16x8*)(lds + PG8_SB(b, h) + boff + n * 2048 + k * 1024); } while (0)
; #define PG8_MMA(ai, bj, At, Bt) do { __builtin_amdgcn_s_setprio(1); _Pragma("unroll") for (int m = 0; m < 4; ++m) _Pragma("unroll") for (int n = 0; n < 2; ++n) _Pragma("unroll") for (int k = 0; k < 2; ++k) \
;         acc[ai][bj][m][n] = __builtin_amdgcn_mfma_f32_16x16x32_bf16(Bt[n][k], At[m][k], acc[ai][bj][m][n], 0, 0, 0); __builtin_amdgcn_s_setprio(0); } while (0)
; template <class Epi, class Sched, bool ALIGN_EPI = false, bool SP2 = false>
; __device__ __forceinline__ void gemm_phase(PG8_LAS unsigned char* lds, const Gemm g, const Sched& S, const Epi& E) {
;     ...
;         for (int t = 0; t < nt; t += 2) {
;             const bool last = (t == nt - 2);
;             const char* a1 = cA + (size_t)(t + 1) * kstep;
;             const char* a2 = last ? nA : cA + (size_t)(t + 2) * kstep; const char* b2 = last ? nB : cB + (size_t)(t + 2) * kstep;
;             const char* a3 = a2 + kstep; const char* b3 = b2 + kstep;
;             if (last && has_next) S.a_ready(nxt);
;             if constexpr (Epi::MIDK) { if (t == (nt >> 1)) { E.midk(acc, wr, fr); asm volatile("s_waitcnt lgkmcnt(0)" ::: "memory"); } }
;             if constexpr (SP2) {
;             PG8_LDB(B0, 0, 0); PG8_LDB(B1, 0, 1); PG8_SCHED; PG8_LDA(At, 0, 0); PG8_STAGE(PG8_SA(1, 1), a1 + hstep, voffA);
;             PG8_WAIT_V(8); PG8_WAIT_L(0); PG8_BAR; PG8_MMA(0, 0, At, B0); PG8_MMA(0, 1, At, B1); PG8_BAR; PG8_SCHED;
;             PG8_LDA(At, 0, 1); PG8_STAGE(PG8_SB(0, 0), b2, voffB); PG8_STAGE(PG8_SB(0, 1), b2 + hstep, voffB); PG8_STAGE(PG8_SA(0, 0), a2, voffA);
;             PG8_WAIT_V(8); PG8_WAIT_L(0); PG8_BAR; PG8_MMA(1, 0, At, B0); PG8_MMA(1, 1, At, B1); PG8_BAR; PG8_SCHED;
.LBB0_349:
	ds_read_b128 v[150:153], v169
	ds_read_b128 v[154:157], v169 offset:1024
	ds_read_b128 v[158:161], v169 offset:2048
	ds_read_b128 v[162:165], v169 offset:3072
	ds_read_b128 v[174:177], v170
	ds_read_b128 v[178:181], v170 offset:1024
	ds_read_b128 v[182:185], v170 offset:2048
	ds_read_b128 v[186:189], v170 offset:3072
	s_add_u32 s0, s88, 0xfff00080
	s_addc_u32 s1, s89, -1
	s_cmp_eq_u32 s23, 60
	s_cselect_b32 s93, s51, s1
	s_cselect_b32 s92, s50, s0
	s_cselect_b32 s91, s53, s21
	s_cselect_b32 s90, s52, s9
	ds_read_b128 v[190:193], v171
	ds_read_b128 v[196:199], v171 offset:1024
	ds_read_b128 v[200:203], v171 offset:2048
	ds_read_b128 v[204:207], v171 offset:3072
	ds_read_b128 v[208:211], v171 offset:4096
	ds_read_b128 v[212:215], v171 offset:5120
	ds_read_b128 v[220:223], v171 offset:6144
	ds_read_b128 v[224:227], v171 offset:7168
	s_add_u32 s0, s88, 0xfff00000
	s_addc_u32 s1, s89, -1
	s_add_i32 m0, s27, 0x8000
	s_nop 0
	global_load_lds_dwordx4 v134, s[0:1]
	s_add_i32 m0, s27, 0xa000
	s_nop 0
	global_load_lds_dwordx4 v138, s[0:1]
	s_add_i32 m0, s27, 0xc000
	s_nop 0
	global_load_lds_dwordx4 v134, s[88:89]
	s_add_i32 m0, s27, 0xe000
	s_nop 0
	global_load_lds_dwordx4 v138, s[88:89]
	s_waitcnt lgkmcnt(0)
	s_setprio 1
	v_mfma_f32_16x16x32_bf16 v[38:41], v[150:153], v[190:193], v[38:41]
	v_mfma_f32_16x16x32_bf16 v[38:41], v[154:157], v[196:199], v[38:41]
	v_mfma_f32_16x16x32_bf16 v[30:33], v[158:161], v[190:193], v[30:33]
	v_mfma_f32_16x16x32_bf16 v[30:33], v[162:165], v[196:199], v[30:33]
	v_mfma_f32_16x16x32_bf16 v[50:53], v[174:177], v[190:193], v[50:53]
	v_mfma_f32_16x16x32_bf16 v[50:53], v[178:181], v[196:199], v[50:53]
	v_mfma_f32_16x16x32_bf16 v[46:49], v[182:185], v[190:193], v[46:49]
	v_mfma_f32_16x16x32_bf16 v[46:49], v[186:189], v[196:199], v[46:49]
	v_mfma_f32_16x16x32_bf16 v[130:133], v[150:153], v[200:203], v[130:133]
	v_mfma_f32_16x16x32_bf16 v[130:133], v[154:157], v[204:207], v[130:133]
	v_mfma_f32_16x16x32_bf16 v[126:129], v[158:161], v[200:203], v[126:129]
	v_mfma_f32_16x16x32_bf16 v[126:129], v[162:165], v[204:207], v[126:129]
	v_mfma_f32_16x16x32_bf16 v[122:125], v[174:177], v[200:203], v[122:125]
	v_mfma_f32_16x16x32_bf16 v[122:125], v[178:181], v[204:207], v[122:125]
	v_mfma_f32_16x16x32_bf16 v[118:121], v[182:185], v[200:203], v[118:121]
	v_mfma_f32_16x16x32_bf16 v[118:121], v[186:189], v[204:207], v[118:121]
	v_mfma_f32_16x16x32_bf16 v[114:117], v[150:153], v[208:211], v[114:117]
	v_mfma_f32_16x16x32_bf16 v[114:117], v[154:157], v[212:215], v[114:117]
	v_mfma_f32_16x16x32_bf16 v[110:113], v[158:161], v[208:211], v[110:113]
	v_mfma_f32_16x16x32_bf16 v[110:113], v[162:165], v[212:215], v[110:113]
	v_mfma_f32_16x16x32_bf16 v[106:109], v[174:177], v[208:211], v[106:109]
	v_mfma_f32_16x16x32_bf16 v[106:109], v[178:181], v[212:215], v[106:109]
	v_mfma_f32_16x16x32_bf16 v[102:105], v[182:185], v[208:211], v[102:105]
	v_mfma_f32_16x16x32_bf16 v[102:105], v[186:189], v[212:215], v[102:105]
	v_mfma_f32_16x16x32_bf16 v[98:101], v[150:153], v[220:223], v[98:101]
	v_mfma_f32_16x16x32_bf16 v[98:101], v[154:157], v[224:227], v[98:101]
	v_mfma_f32_16x16x32_bf16 v[94:97], v[158:161], v[220:223], v[94:97]
	v_mfma_f32_16x16x32_bf16 v[94:97], v[162:165], v[224:227], v[94:97]
	v_mfma_f32_16x16x32_bf16 v[90:93], v[174:177], v[220:223], v[90:93]
	v_mfma_f32_16x16x32_bf16 v[90:93], v[178:181], v[224:227], v[90:93]
	v_mfma_f32_16x16x32_bf16 v[86:89], v[182:185], v[220:223], v[86:89]
	v_mfma_f32_16x16x32_bf16 v[86:89], v[186:189], v[224:227], v[86:89]
	s_setprio 0
	s_waitcnt vmcnt(8)
	s_barrier
	ds_read_b128 v[190:193], v171 offset:16384
	ds_read_b128 v[196:199], v171 offset:17408
	ds_read_b128 v[200:203], v171 offset:18432
	ds_read_b128 v[204:207], v171 offset:19456
	ds_read_b128 v[208:211], v171 offset:20480
	ds_read_b128 v[212:215], v171 offset:21504
	ds_read_b128 v[220:223], v171 offset:22528
	ds_read_b128 v[224:227], v171 offset:23552
	s_add_u32 vcc_lo, s90, 0x100000
	s_addc_u32 vcc_hi, s91, 0
	s_add_i32 m0, s27, 0x10000
	s_nop 0
	global_load_lds_dwordx4 v136, s[90:91]
	s_add_i32 m0, s27, 0x12000
	s_nop 0
	global_load_lds_dwordx4 v140, s[90:91]
	s_add_i32 m0, s27, 0x14000
	s_nop 0
	global_load_lds_dwordx4 v136, vcc
	s_add_i32 m0, s27, 0x16000
	s_nop 0
	global_load_lds_dwordx4 v140, vcc
	s_waitcnt lgkmcnt(0)
	s_setprio 1
	v_mfma_f32_16x16x32_bf16 v[82:85], v[150:153], v[190:193], v[82:85]
	v_mfma_f32_16x16x32_bf16 v[82:85], v[154:157], v[196:199], v[82:85]
	v_mfma_f32_16x16x32_bf16 v[78:81], v[158:161], v[190:193], v[78:81]
	v_mfma_f32_16x16x32_bf16 v[78:81], v[162:165], v[196:199], v[78:81]
	v_mfma_f32_16x16x32_bf16 v[74:77], v[174:177], v[190:193], v[74:77]
	v_mfma_f32_16x16x32_bf16 v[74:77], v[178:181], v[196:199], v[74:77]
	v_mfma_f32_16x16x32_bf16 v[70:73], v[182:185], v[190:193], v[70:73]
	v_mfma_f32_16x16x32_bf16 v[70:73], v[186:189], v[196:199], v[70:73]
	v_mfma_f32_16x16x32_bf16 v[66:69], v[150:153], v[200:203], v[66:69]
	v_mfma_f32_16x16x32_bf16 v[66:69], v[154:157], v[204:207], v[66:69]
	v_mfma_f32_16x16x32_bf16 v[62:65], v[158:161], v[200:203], v[62:65]
	v_mfma_f32_16x16x32_bf16 v[62:65], v[162:165], v[204:207], v[62:65]
	v_mfma_f32_16x16x32_bf16 v[58:61], v[174:177], v[200:203], v[58:61]
	v_mfma_f32_16x16x32_bf16 v[58:61], v[178:181], v[204:207], v[58:61]
	v_mfma_f32_16x16x32_bf16 v[54:57], v[182:185], v[200:203], v[54:57]
	v_mfma_f32_16x16x32_bf16 v[54:57], v[186:189], v[204:207], v[54:57]
	v_mfma_f32_16x16x32_bf16 v[42:45], v[150:153], v[208:211], v[42:45]
	v_mfma_f32_16x16x32_bf16 v[42:45], v[154:157], v[212:215], v[42:45]
	v_mfma_f32_16x16x32_bf16 v[34:37], v[158:161], v[208:211], v[34:37]
	v_mfma_f32_16x16x32_bf16 v[34:37], v[162:165], v[212:215], v[34:37]
	v_mfma_f32_16x16x32_bf16 v[26:29], v[174:177], v[208:211], v[26:29]
	v_mfma_f32_16x16x32_bf16 v[26:29], v[178:181], v[212:215], v[26:29]
	v_mfma_f32_16x16x32_bf16 v[22:25], v[182:185], v[208:211], v[22:25]
	v_mfma_f32_16x16x32_bf16 v[22:25], v[186:189], v[212:215], v[22:25]
	v_mfma_f32_16x16x32_bf16 v[18:21], v[150:153], v[220:223], v[18:21]
	v_mfma_f32_16x16x32_bf16 v[18:21], v[154:157], v[224:227], v[18:21]
	v_mfma_f32_16x16x32_bf16 v[14:17], v[158:161], v[220:223], v[14:17]
	v_mfma_f32_16x16x32_bf16 v[14:17], v[162:165], v[224:227], v[14:17]
	v_mfma_f32_16x16x32_bf16 v[10:13], v[174:177], v[220:223], v[10:13]
	v_mfma_f32_16x16x32_bf16 v[10:13], v[178:181], v[224:227], v[10:13]
	v_mfma_f32_16x16x32_bf16 v[4:7], v[182:185], v[220:223], v[6:9]
	v_mfma_f32_16x16x32_bf16 v[4:7], v[186:189], v[224:227], v[4:7]
	s_setprio 0
	s_waitcnt vmcnt(6)
	s_barrier
; #define PG8_STAGE(bufoff, gbase, voff) do { _Pragma("unroll") for (int _i = 0; _i < 2; ++_i) \
;         __builtin_amdgcn_global_load_lds((const unsigned*)((const char*)(gbase) + (voff)[_i]), (PG8_LAS unsigned*)(lds + (bufoff) + ldsw + _i * 8192), 16, 0, 0); } while (0)
; #define PG8_LDA(dst, b, h) do { _Pragma("unroll") for (int m = 0; m < 4; ++m) _Pragma("unroll") for (int k = 0; k < 2; ++k) dst[m][k] = *(const PG8_LAS bf16x8*)(lds + PG8_SA(b, h) + aoff + m * 2048 + k * 1024); } while (0)
; #define PG8_LDB(dst, b, h) do { _Pragma("unroll") for (int n = 0; n < 2; ++n) _Pragma("unroll") for (int k = 0; k < 2; ++k) dst[n][k] = *(const PG8_LAS bf16x8*)(lds + PG8_SB(b, h) + boff + n * 2048 + k * 1024); } while (0)
; #define PG8_MMA(ai, bj, At, Bt) do { __builtin_amdgcn_s_setprio(1); _Pragma("unroll") for (int m = 0; m < 4; ++m) _Pragma("unroll") for (int n = 0; n < 2; ++n) _Pragma("unroll") for (int k = 0; k < 2; ++k) \
;         acc[ai][bj][m][n] = __builtin_amdgcn_mfma_f32_16x16x32_bf16(Bt[n][k], At[m][k], acc[ai][bj][m][n], 0, 0, 0); __builtin_amdgcn_s_setprio(0); } while (0)
; #define PG8_WAIT_V(n) asm volatile("s_waitcnt vmcnt(" #n ")" ::: "memory")
; #define PG8_WAIT_L(n) asm volatile("s_waitcnt lgkmcnt(" #n ")" ::: "memory")
; #define PG8_BAR __builtin_amdgcn_s_barrier()
; #define PG8_SCHED __builtin_amdgcn_sched_barrier(0)
; template <class Epi, class Sched, bool ALIGN_EPI = false, bool SP2 = false>
; __device__ __forceinline__ void gemm_phase(PG8_LAS unsigned char* lds, const Gemm g, const Sched& S, const Epi& E) {
;     ...
;             PG8_LDB(B0, 1, 0); PG8_LDB(B1, 1, 1); PG8_SCHED; PG8_LDA(At, 1, 0); PG8_STAGE(PG8_SA(0, 1), a2 + hstep, voffA);
;             PG8_WAIT_V(8); PG8_WAIT_L(0); PG8_BAR; PG8_MMA(0, 0, At, B0); PG8_MMA(0, 1, At, B1); PG8_BAR; PG8_SCHED;
;             PG8_LDA(At, 1, 1); PG8_STAGE(PG8_SB(1, 0), b3, voffB); PG8_STAGE(PG8_SB(1, 1), b3 + hstep, voffB); PG8_STAGE(PG8_SA(1, 0), a3, voffA);
;             PG8_WAIT_V(8); PG8_WAIT_L(0); PG8_BAR; PG8_MMA(1, 0, At, B0); PG8_MMA(1, 1, At, B1); PG8_BAR; PG8_SCHED;
	s_add_i32 s0, 0, 0x18000
	v_add_u32_e32 v3, s0, v167
	s_add_i32 s1, 0, 0x1c000
	ds_read_b128 v[150:153], v3
	ds_read_b128 v[154:157], v3 offset:1024
	ds_read_b128 v[158:161], v3 offset:2048
	ds_read_b128 v[162:165], v3 offset:3072
	v_add_u32_e32 v3, s1, v167
	ds_read_b128 v[174:177], v3
	ds_read_b128 v[178:181], v3 offset:1024
	ds_read_b128 v[182:185], v3 offset:2048
	ds_read_b128 v[186:189], v3 offset:3072
	ds_read_b128 v[190:193], v171 offset:32768
	ds_read_b128 v[196:199], v171 offset:33792
	ds_read_b128 v[200:203], v171 offset:34816
	ds_read_b128 v[204:207], v171 offset:35840
	ds_read_b128 v[208:211], v171 offset:36864
	ds_read_b128 v[212:215], v171 offset:37888
	ds_read_b128 v[220:223], v171 offset:38912
	ds_read_b128 v[224:227], v171 offset:39936
	s_add_u32 vcc_lo, s92, 0x100000
	s_addc_u32 vcc_hi, s93, 0
	s_mov_b32 m0, s27
	s_nop 0
	global_load_lds_dwordx4 v134, s[92:93]
	s_add_i32 m0, s27, 0x2000
	s_nop 0
	global_load_lds_dwordx4 v138, s[92:93]
	s_add_i32 m0, s27, 0x4000
	s_nop 0
	global_load_lds_dwordx4 v134, vcc
	s_add_i32 m0, s27, 0x6000
	s_nop 0
	global_load_lds_dwordx4 v138, vcc
	s_waitcnt lgkmcnt(0)
	s_setprio 1
	v_mfma_f32_16x16x32_bf16 v[38:41], v[150:153], v[190:193], v[38:41]
	v_mfma_f32_16x16x32_bf16 v[38:41], v[154:157], v[196:199], v[38:41]
	v_mfma_f32_16x16x32_bf16 v[30:33], v[158:161], v[190:193], v[30:33]
	v_mfma_f32_16x16x32_bf16 v[30:33], v[162:165], v[196:199], v[30:33]
	v_mfma_f32_16x16x32_bf16 v[50:53], v[174:177], v[190:193], v[50:53]
	v_mfma_f32_16x16x32_bf16 v[50:53], v[178:181], v[196:199], v[50:53]
	v_mfma_f32_16x16x32_bf16 v[46:49], v[182:185], v[190:193], v[46:49]
	v_mfma_f32_16x16x32_bf16 v[46:49], v[186:189], v[196:199], v[46:49]
	v_mfma_f32_16x16x32_bf16 v[130:133], v[150:153], v[200:203], v[130:133]
	v_mfma_f32_16x16x32_bf16 v[130:133], v[154:157], v[204:207], v[130:133]
	v_mfma_f32_16x16x32_bf16 v[126:129], v[158:161], v[200:203], v[126:129]
	v_mfma_f32_16x16x32_bf16 v[126:129], v[162:165], v[204:207], v[126:129]
	v_mfma_f32_16x16x32_bf16 v[122:125], v[174:177], v[200:203], v[122:125]
	v_mfma_f32_16x16x32_bf16 v[122:125], v[178:181], v[204:207], v[122:125]
	v_mfma_f32_16x16x32_bf16 v[118:121], v[182:185], v[200:203], v[118:121]
	v_mfma_f32_16x16x32_bf16 v[118:121], v[186:189], v[204:207], v[118:121]
	v_mfma_f32_16x16x32_bf16 v[114:117], v[150:153], v[208:211], v[114:117]
	v_mfma_f32_16x16x32_bf16 v[114:117], v[154:157], v[212:215], v[114:117]
	v_mfma_f32_16x16x32_bf16 v[110:113], v[158:161], v[208:211], v[110:113]
	v_mfma_f32_16x16x32_bf16 v[110:113], v[162:165], v[212:215], v[110:113]
	v_mfma_f32_16x16x32_bf16 v[106:109], v[174:177], v[208:211], v[106:109]
	v_mfma_f32_16x16x32_bf16 v[106:109], v[178:181], v[212:215], v[106:109]
	v_mfma_f32_16x16x32_bf16 v[102:105], v[182:185], v[208:211], v[102:105]
	v_mfma_f32_16x16x32_bf16 v[102:105], v[186:189], v[212:215], v[102:105]
	v_mfma_f32_16x16x32_bf16 v[98:101], v[150:153], v[220:223], v[98:101]
	v_mfma_f32_16x16x32_bf16 v[98:101], v[154:157], v[224:227], v[98:101]
	v_mfma_f32_16x16x32_bf16 v[94:97], v[158:161], v[220:223], v[94:97]
	v_mfma_f32_16x16x32_bf16 v[94:97], v[162:165], v[224:227], v[94:97]
	v_mfma_f32_16x16x32_bf16 v[90:93], v[174:177], v[220:223], v[90:93]
	v_mfma_f32_16x16x32_bf16 v[90:93], v[178:181], v[224:227], v[90:93]
	v_mfma_f32_16x16x32_bf16 v[86:89], v[182:185], v[220:223], v[86:89]
	v_mfma_f32_16x16x32_bf16 v[86:89], v[186:189], v[224:227], v[86:89]
	s_setprio 0
	s_waitcnt vmcnt(8)
	s_barrier
	ds_read_b128 v[190:193], v171 offset:49152
	ds_read_b128 v[196:199], v171 offset:50176
	ds_read_b128 v[200:203], v171 offset:51200
	ds_read_b128 v[204:207], v171 offset:52224
	ds_read_b128 v[208:211], v171 offset:53248
	ds_read_b128 v[212:215], v171 offset:54272
	ds_read_b128 v[220:223], v171 offset:55296
	ds_read_b128 v[224:227], v171 offset:56320
	s_add_u32 s0, s90, 0x80
	s_addc_u32 s1, s91, 0
	s_add_u32 vcc_lo, s0, 0x100000
	s_addc_u32 vcc_hi, s1, 0
	s_add_i32 m0, s27, 0x18000
	s_nop 0
	global_load_lds_dwordx4 v136, s[0:1]
	s_add_i32 m0, s27, 0x1a000
	s_nop 0
	global_load_lds_dwordx4 v140, s[0:1]
	s_add_i32 m0, s27, 0x1c000
	s_nop 0
	global_load_lds_dwordx4 v136, vcc
	s_add_i32 m0, s27, 0x1e000
	s_nop 0
	global_load_lds_dwordx4 v140, vcc
	s_waitcnt lgkmcnt(0)
	s_setprio 1
	v_mfma_f32_16x16x32_bf16 v[82:85], v[150:153], v[190:193], v[82:85]
	v_mfma_f32_16x16x32_bf16 v[82:85], v[154:157], v[196:199], v[82:85]
	v_mfma_f32_16x16x32_bf16 v[78:81], v[158:161], v[190:193], v[78:81]
	v_mfma_f32_16x16x32_bf16 v[78:81], v[162:165], v[196:199], v[78:81]
	v_mfma_f32_16x16x32_bf16 v[74:77], v[174:177], v[190:193], v[74:77]
	v_mfma_f32_16x16x32_bf16 v[74:77], v[178:181], v[196:199], v[74:77]
	v_mfma_f32_16x16x32_bf16 v[70:73], v[182:185], v[190:193], v[70:73]
	v_mfma_f32_16x16x32_bf16 v[70:73], v[186:189], v[196:199], v[70:73]
	v_mfma_f32_16x16x32_bf16 v[66:69], v[150:153], v[200:203], v[66:69]
	v_mfma_f32_16x16x32_bf16 v[66:69], v[154:157], v[204:207], v[66:69]
	v_mfma_f32_16x16x32_bf16 v[62:65], v[158:161], v[200:203], v[62:65]
	v_mfma_f32_16x16x32_bf16 v[62:65], v[162:165], v[204:207], v[62:65]
	v_mfma_f32_16x16x32_bf16 v[58:61], v[174:177], v[200:203], v[58:61]
	v_mfma_f32_16x16x32_bf16 v[58:61], v[178:181], v[204:207], v[58:61]
	v_mfma_f32_16x16x32_bf16 v[54:57], v[182:185], v[200:203], v[54:57]
	v_mfma_f32_16x16x32_bf16 v[54:57], v[186:189], v[204:207], v[54:57]
	v_mfma_f32_16x16x32_bf16 v[42:45], v[150:153], v[208:211], v[42:45]
	v_mfma_f32_16x16x32_bf16 v[42:45], v[154:157], v[212:215], v[42:45]
	v_mfma_f32_16x16x32_bf16 v[34:37], v[158:161], v[208:211], v[34:37]
	v_mfma_f32_16x16x32_bf16 v[34:37], v[162:165], v[212:215], v[34:37]
	v_mfma_f32_16x16x32_bf16 v[26:29], v[174:177], v[208:211], v[26:29]
	v_mfma_f32_16x16x32_bf16 v[26:29], v[178:181], v[212:215], v[26:29]
	v_mfma_f32_16x16x32_bf16 v[22:25], v[182:185], v[208:211], v[22:25]
	v_mfma_f32_16x16x32_bf16 v[22:25], v[186:189], v[212:215], v[22:25]
	v_mfma_f32_16x16x32_bf16 v[18:21], v[150:153], v[220:223], v[18:21]
	v_mfma_f32_16x16x32_bf16 v[18:21], v[154:157], v[224:227], v[18:21]
	v_mfma_f32_16x16x32_bf16 v[14:17], v[158:161], v[220:223], v[14:17]
	v_mfma_f32_16x16x32_bf16 v[14:17], v[162:165], v[224:227], v[14:17]
	v_mfma_f32_16x16x32_bf16 v[8:11], v[174:177], v[220:223], v[10:13]
	v_mfma_f32_16x16x32_bf16 v[10:13], v[178:181], v[224:227], v[8:11]
	v_mfma_f32_16x16x32_bf16 v[4:7], v[182:185], v[220:223], v[4:7]
	v_mfma_f32_16x16x32_bf16 v[6:9], v[186:189], v[224:227], v[4:7]
	s_setprio 0
	s_waitcnt vmcnt(6)
	s_barrier
	s_add_i32 s23, s23, 2
	s_add_u32 s88, s88, 0x100
	s_addc_u32 s89, s89, 0
	s_add_u32 s9, s9, 0x100
	s_addc_u32 s21, s21, 0
	s_cmp_gt_u32 s23, 61
	s_cbranch_scc0 .LBB0_349
	s_branch .Lip_exit
; #define PG8_STAGE(bufoff, gbase, voff) do { _Pragma("unroll") for (int _i = 0; _i < 2; ++_i) \
;         __builtin_amdgcn_global_load_lds((const unsigned*)((const char*)(gbase) + (voff)[_i]), (PG8_LAS unsigned*)(lds + (bufoff) + ldsw + _i * 8192), 16, 0, 0); } while (0)
; #define PG8_LDA(dst, b, h) do { _Pragma("unroll") for (int m = 0; m < 4; ++m) _Pragma("unroll") for (int k = 0; k < 2; ++k) dst[m][k] = *(const PG8_LAS bf16x8*)(lds + PG8_SA(b, h) + aoff + m * 2048 + k * 1024); } while (0)
; #define PG8_LDB(dst, b, h) do { _Pragma("unroll") for (int n = 0; n < 2; ++n) _Pragma("unroll") for (int k = 0; k < 2; ++k) dst[n][k] = *(const PG8_LAS bf16x8*)(lds + PG8_SB(b, h) + boff + n * 2048 + k * 1024); } while (0)
; #define PG8_MMA(ai, bj, At, Bt) do { __builtin_amdgcn_s_setprio(1); _Pragma("unroll") for (int m = 0; m < 4; ++m) _Pragma("unroll") for (int n = 0; n < 2; ++n) _Pragma("unroll") for (int k = 0; k < 2; ++k) \
;         acc[ai][bj][m][n] = __builtin_amdgcn_mfma_f32_16x16x32_bf16(Bt[n][k], At[m][k], acc[ai][bj][m][n], 0, 0, 0); __builtin_amdgcn_s_setprio(0); } while (0)
; #define PG8_WAIT_V(n) asm volatile("s_waitcnt vmcnt(" #n ")" ::: "memory")
; #define PG8_WAIT_L(n) asm volatile("s_waitcnt lgkmcnt(" #n ")" ::: "memory")
; #define PG8_BAR __builtin_amdgcn_s_barrier()
; #define PG8_SCHED __builtin_amdgcn_sched_barrier(0)
; template <class Epi, class Sched, bool ALIGN_EPI = false, bool SP2 = false>
; __device__ __forceinline__ void gemm_phase(PG8_LAS unsigned char* lds, const Gemm g, const Sched& S, const Epi& E) {
;     ...
;             if constexpr (SP2) {
;             PG8_LDB(B0, 0, 0); PG8_LDB(B1, 0, 1); PG8_SCHED; PG8_LDA(At, 0, 0); PG8_STAGE(PG8_SA(1, 1), a1 + hstep, voffA);
;             PG8_WAIT_V(8); PG8_WAIT_L(0); PG8_BAR; PG8_MMA(0, 0, At, B0); PG8_MMA(0, 1, At, B1); PG8_BAR; PG8_SCHED;
.Lip_h1:
	ds_read_b128 v[150:153], v169
	ds_read_b128 v[154:157], v169 offset:1024
	ds_read_b128 v[158:161], v169 offset:2048
	ds_read_b128 v[162:165], v169 offset:3072
	ds_read_b128 v[174:177], v170
	ds_read_b128 v[178:181], v170 offset:1024
	ds_read_b128 v[182:185], v170 offset:2048
	ds_read_b128 v[186:189], v170 offset:3072
	s_add_u32 s0, s88, 0xfff00080
	s_addc_u32 s1, s89, -1
	s_cmp_eq_u32 s23, 60
	s_cselect_b32 s93, s51, s1
	s_cselect_b32 s92, s50, s0
	s_cselect_b32 s91, s53, s21
	s_cselect_b32 s90, s52, s9
	ds_read_b128 v[190:193], v171
	ds_read_b128 v[196:199], v171 offset:1024
	ds_read_b128 v[200:203], v171 offset:2048
	ds_read_b128 v[204:207], v171 offset:3072
	ds_read_b128 v[208:211], v171 offset:4096
	ds_read_b128 v[212:215], v171 offset:5120
	ds_read_b128 v[220:223], v171 offset:6144
	ds_read_b128 v[224:227], v171 offset:7168
	s_add_u32 s0, s88, 0xfff00000
	s_addc_u32 s1, s89, -1
	s_add_i32 m0, s27, 0x8000
	s_nop 0
	global_load_lds_dwordx4 v134, s[0:1]
	s_add_i32 m0, s27, 0xa000
	s_nop 0
	global_load_lds_dwordx4 v138, s[0:1]
	s_add_i32 m0, s27, 0xc000
	s_nop 0
	global_load_lds_dwordx4 v134, s[88:89]
	s_add_i32 m0, s27, 0xe000
	s_nop 0
	global_load_lds_dwordx4 v138, s[88:89]
	s_sleep 2
	s_waitcnt lgkmcnt(0)
	s_waitcnt vmcnt(8)
	s_barrier
	s_setprio 2
	v_mfma_f32_16x16x32_bf16 v[38:41], v[150:153], v[190:193], v[38:41]
	v_mfma_f32_16x16x32_bf16 v[38:41], v[154:157], v[196:199], v[38:41]
	v_mfma_f32_16x16x32_bf16 v[30:33], v[158:161], v[190:193], v[30:33]
	v_mfma_f32_16x16x32_bf16 v[30:33], v[162:165], v[196:199], v[30:33]
	v_mfma_f32_16x16x32_bf16 v[50:53], v[174:177], v[190:193], v[50:53]
	v_mfma_f32_16x16x32_bf16 v[50:53], v[178:181], v[196:199], v[50:53]
	v_mfma_f32_16x16x32_bf16 v[46:49], v[182:185], v[190:193], v[46:49]
	v_mfma_f32_16x16x32_bf16 v[46:49], v[186:189], v[196:199], v[46:49]
	v_mfma_f32_16x16x32_bf16 v[130:133], v[150:153], v[200:203], v[130:133]
	v_mfma_f32_16x16x32_bf16 v[130:133], v[154:157], v[204:207], v[130:133]
	v_mfma_f32_16x16x32_bf16 v[126:129], v[158:161], v[200:203], v[126:129]
	v_mfma_f32_16x16x32_bf16 v[126:129], v[162:165], v[204:207], v[126:129]
	v_mfma_f32_16x16x32_bf16 v[122:125], v[174:177], v[200:203], v[122:125]
	v_mfma_f32_16x16x32_bf16 v[122:125], v[178:181], v[204:207], v[122:125]
	v_mfma_f32_16x16x32_bf16 v[118:121], v[182:185], v[200:203], v[118:121]
	v_mfma_f32_16x16x32_bf16 v[118:121], v[186:189], v[204:207], v[118:121]
	v_mfma_f32_16x16x32_bf16 v[114:117], v[150:153], v[208:211], v[114:117]
	v_mfma_f32_16x16x32_bf16 v[114:117], v[154:157], v[212:215], v[114:117]
	v_mfma_f32_16x16x32_bf16 v[110:113], v[158:161], v[208:211], v[110:113]
	v_mfma_f32_16x16x32_bf16 v[110:113], v[162:165], v[212:215], v[110:113]
	v_mfma_f32_16x16x32_bf16 v[106:109], v[174:177], v[208:211], v[106:109]
	v_mfma_f32_16x16x32_bf16 v[106:109], v[178:181], v[212:215], v[106:109]
	v_mfma_f32_16x16x32_bf16 v[102:105], v[182:185], v[208:211], v[102:105]
	v_mfma_f32_16x16x32_bf16 v[102:105], v[186:189], v[212:215], v[102:105]
	v_mfma_f32_16x16x32_bf16 v[98:101], v[150:153], v[220:223], v[98:101]
	v_mfma_f32_16x16x32_bf16 v[98:101], v[154:157], v[224:227], v[98:101]
	v_mfma_f32_16x16x32_bf16 v[94:97], v[158:161], v[220:223], v[94:97]
	v_mfma_f32_16x16x32_bf16 v[94:97], v[162:165], v[224:227], v[94:97]
	v_mfma_f32_16x16x32_bf16 v[90:93], v[174:177], v[220:223], v[90:93]
	v_mfma_f32_16x16x32_bf16 v[90:93], v[178:181], v[224:227], v[90:93]
	v_mfma_f32_16x16x32_bf16 v[86:89], v[182:185], v[220:223], v[86:89]
	v_mfma_f32_16x16x32_bf16 v[86:89], v[186:189], v[224:227], v[86:89]
	s_setprio 0
	ds_read_b128 v[190:193], v171 offset:16384
	ds_read_b128 v[196:199], v171 offset:17408
	ds_read_b128 v[200:203], v171 offset:18432
	ds_read_b128 v[204:207], v171 offset:19456
	ds_read_b128 v[208:211], v171 offset:20480
	ds_read_b128 v[212:215], v171 offset:21504
	ds_read_b128 v[220:223], v171 offset:22528
	ds_read_b128 v[224:227], v171 offset:23552
	s_add_u32 vcc_lo, s90, 0x100000
	s_addc_u32 vcc_hi, s91, 0
	s_add_i32 m0, s27, 0x10000
	s_nop 0
	global_load_lds_dwordx4 v136, s[90:91]
	s_add_i32 m0, s27, 0x12000
	s_nop 0
	global_load_lds_dwordx4 v140, s[90:91]
	s_add_i32 m0, s27, 0x14000
	s_nop 0
	global_load_lds_dwordx4 v136, vcc
	s_add_i32 m0, s27, 0x16000
	s_nop 0
	global_load_lds_dwordx4 v140, vcc
	s_sleep 2
	s_waitcnt lgkmcnt(0)
	s_waitcnt vmcnt(6)
	s_barrier
; #define PG8_STAGE(bufoff, gbase, voff) do { _Pragma("unroll") for (int _i = 0; _i < 2; ++_i) \
;         __builtin_amdgcn_global_load_lds((const unsigned*)((const char*)(gbase) + (voff)[_i]), (PG8_LAS unsigned*)(lds + (bufoff) + ldsw + _i * 8192), 16, 0, 0); } while (0)
; #define PG8_LDA(dst, b, h) do { _Pragma("unroll") for (int m = 0; m < 4; ++m) _Pragma("unroll") for (int k = 0; k < 2; ++k) dst[m][k] = *(const PG8_LAS bf16x8*)(lds + PG8_SA(b, h) + aoff + m * 2048 + k * 1024); } while (0)
; #define PG8_LDB(dst, b, h) do { _Pragma("unroll") for (int n = 0; n < 2; ++n) _Pragma("unroll") for (int k = 0; k < 2; ++k) dst[n][k] = *(const PG8_LAS bf16x8*)(lds + PG8_SB(b, h) + boff + n * 2048 + k * 1024); } while (0)
; #define PG8_MMA(ai, bj, At, Bt) do { __builtin_amdgcn_s_setprio(1); _Pragma("unroll") for (int m = 0; m < 4; ++m) _Pragma("unroll") for (int n = 0; n < 2; ++n) _Pragma("unroll") for (int k = 0; k < 2; ++k) \
;         acc[ai][bj][m][n] = __builtin_amdgcn_mfma_f32_16x16x32_bf16(Bt[n][k], At[m][k], acc[ai][bj][m][n], 0, 0, 0); __builtin_amdgcn_s_setprio(0); } while (0)
; #define PG8_WAIT_V(n) asm volatile("s_waitcnt vmcnt(" #n ")" ::: "memory")
; #define PG8_WAIT_L(n) asm volatile("s_waitcnt lgkmcnt(" #n ")" ::: "memory")
; #define PG8_BAR __builtin_amdgcn_s_barrier()
; #define PG8_SCHED __builtin_amdgcn_sched_barrier(0)
; template <class Epi, class Sched, bool ALIGN_EPI = false, bool SP2 = false>
; __device__ __forceinline__ void gemm_phase(PG8_LAS unsigned char* lds, const Gemm g, const Sched& S, const Epi& E) {
;     ...
;             PG8_WAIT_V(8); PG8_WAIT_L(0); PG8_BAR; PG8_MMA(0, 0, At, B0); PG8_MMA(0, 1, At, B1); PG8_BAR; PG8_SCHED;
;             PG8_LDA(At, 0, 1); PG8_STAGE(PG8_SB(0, 0), b2, voffB); PG8_STAGE(PG8_SB(0, 1), b2 + hstep, voffB); PG8_STAGE(PG8_SA(0, 0), a2, voffA);
;             PG8_WAIT_V(8); PG8_WAIT_L(0); PG8_BAR; PG8_MMA(1, 0, At, B0); PG8_MMA(1, 1, At, B1); PG8_BAR; PG8_SCHED;
;             PG8_LDB(B0, 1, 0); PG8_LDB(B1, 1, 1); PG8_SCHED; PG8_LDA(At, 1, 0); PG8_STAGE(PG8_SA(0, 1), a2 + hstep, voffA);
	s_setprio 2
	v_mfma_f32_16x16x32_bf16 v[82:85], v[150:153], v[190:193], v[82:85]
	v_mfma_f32_16x16x32_bf16 v[82:85], v[154:157], v[196:199], v[82:85]
	v_mfma_f32_16x16x32_bf16 v[78:81], v[158:161], v[190:193], v[78:81]
	v_mfma_f32_16x16x32_bf16 v[78:81], v[162:165], v[196:199], v[78:81]
	v_mfma_f32_16x16x32_bf16 v[74:77], v[174:177], v[190:193], v[74:77]
	v_mfma_f32_16x16x32_bf16 v[74:77], v[178:181], v[196:199], v[74:77]
	v_mfma_f32_16x16x32_bf16 v[70:73], v[182:185], v[190:193], v[70:73]
	v_mfma_f32_16x16x32_bf16 v[70:73], v[186:189], v[196:199], v[70:73]
	v_mfma_f32_16x16x32_bf16 v[66:69], v[150:153], v[200:203], v[66:69]
	v_mfma_f32_16x16x32_bf16 v[66:69], v[154:157], v[204:207], v[66:69]
	v_mfma_f32_16x16x32_bf16 v[62:65], v[158:161], v[200:203], v[62:65]
	v_mfma_f32_16x16x32_bf16 v[62:65], v[162:165], v[204:207], v[62:65]
	v_mfma_f32_16x16x32_bf16 v[58:61], v[174:177], v[200:203], v[58:61]
	v_mfma_f32_16x16x32_bf16 v[58:61], v[178:181], v[204:207], v[58:61]
	v_mfma_f32_16x16x32_bf16 v[54:57], v[182:185], v[200:203], v[54:57]
	v_mfma_f32_16x16x32_bf16 v[54:57], v[186:189], v[204:207], v[54:57]
	v_mfma_f32_16x16x32_bf16 v[42:45], v[150:153], v[208:211], v[42:45]
	v_mfma_f32_16x16x32_bf16 v[42:45], v[154:157], v[212:215], v[42:45]
	v_mfma_f32_16x16x32_bf16 v[34:37], v[158:161], v[208:211], v[34:37]
	v_mfma_f32_16x16x32_bf16 v[34:37], v[162:165], v[212:215], v[34:37]
	v_mfma_f32_16x16x32_bf16 v[26:29], v[174:177], v[208:211], v[26:29]
	v_mfma_f32_16x16x32_bf16 v[26:29], v[178:181], v[212:215], v[26:29]
	v_mfma_f32_16x16x32_bf16 v[22:25], v[182:185], v[208:211], v[22:25]
	v_mfma_f32_16x16x32_bf16 v[22:25], v[186:189], v[212:215], v[22:25]
	v_mfma_f32_16x16x32_bf16 v[18:21], v[150:153], v[220:223], v[18:21]
	v_mfma_f32_16x16x32_bf16 v[18:21], v[154:157], v[224:227], v[18:21]
	v_mfma_f32_16x16x32_bf16 v[14:17], v[158:161], v[220:223], v[14:17]
	v_mfma_f32_16x16x32_bf16 v[14:17], v[162:165], v[224:227], v[14:17]
	v_mfma_f32_16x16x32_bf16 v[10:13], v[174:177], v[220:223], v[10:13]
	v_mfma_f32_16x16x32_bf16 v[10:13], v[178:181], v[224:227], v[10:13]
	v_mfma_f32_16x16x32_bf16 v[4:7], v[182:185], v[220:223], v[6:9]
	v_mfma_f32_16x16x32_bf16 v[4:7], v[186:189], v[224:227], v[4:7]
	s_setprio 0
	s_add_i32 s0, 0, 0x18000
	v_add_u32_e32 v3, s0, v167
	s_add_i32 s1, 0, 0x1c000
	ds_read_b128 v[150:153], v3
	ds_read_b128 v[154:157], v3 offset:1024
	ds_read_b128 v[158:161], v3 offset:2048
	ds_read_b128 v[162:165], v3 offset:3072
	v_add_u32_e32 v3, s1, v167
	ds_read_b128 v[174:177], v3
	ds_read_b128 v[178:181], v3 offset:1024
	ds_read_b128 v[182:185], v3 offset:2048
	ds_read_b128 v[186:189], v3 offset:3072
	ds_read_b128 v[190:193], v171 offset:32768
	ds_read_b128 v[196:199], v171 offset:33792
	ds_read_b128 v[200:203], v171 offset:34816
	ds_read_b128 v[204:207], v171 offset:35840
	ds_read_b128 v[208:211], v171 offset:36864
	ds_read_b128 v[212:215], v171 offset:37888
	ds_read_b128 v[220:223], v171 offset:38912
	ds_read_b128 v[224:227], v171 offset:39936
	s_add_u32 vcc_lo, s92, 0x100000
	s_addc_u32 vcc_hi, s93, 0
	s_mov_b32 m0, s27
	s_nop 0
	global_load_lds_dwordx4 v134, s[92:93]
	s_add_i32 m0, s27, 0x2000
	s_nop 0
	global_load_lds_dwordx4 v138, s[92:93]
	s_add_i32 m0, s27, 0x4000
	s_nop 0
	global_load_lds_dwordx4 v134, vcc
	s_add_i32 m0, s27, 0x6000
	s_nop 0
	global_load_lds_dwordx4 v138, vcc
	s_sleep 2
	s_waitcnt lgkmcnt(0)
	s_waitcnt vmcnt(8)
	s_barrier
; #define PG8_BAR __builtin_amdgcn_s_barrier()
; template <class Epi, class Sched, bool ALIGN_EPI = false, bool SP2 = false>
; __device__ __forceinline__ void gemm_phase(PG8_LAS unsigned char* lds, const Gemm g, const Sched& S, const Epi& E) {
;     ...
;     Unit cur, nxt; int ui = 0;
;     if (!S.next(0, cur)) return;
;     f32x4 acc[2][2][4][2];
; #pragma unroll
;     for (int a = 0; a < 2; ++a)
; #pragma unroll
;         for (int b = 0; b < 2; ++b)
; #pragma unroll
;             for (int m = 0; m < 4; ++m)
; #pragma unroll
;                 for (int n = 0; n < 2; ++n) acc[a][b][m][n] = (f32x4){0.f, 0.f, 0.f, 0.f};
;     bf16x8 At[4][2], B0[2][2], B1[2][2];
;     const char* cA; const char* cB; S.bases(cur, g, tstep, cA, cB);
;     S.a_ready(cur);
;     if constexpr (SP2) {
;         PG8_STAGE(PG8_SB(0, 0), cB, voffB); PG8_STAGE(PG8_SB(0, 1), cB + hstep, voffB); PG8_STAGE(PG8_SA(0, 0), cA, voffA); PG8_STAGE(PG8_SA(0, 1), cA + hstep, voffA);
;         if (wr == 1) PG8_BAR;
;         PG8_WAIT_V(2); PG8_BAR;
;         PG8_STAGE(PG8_SB(1, 0), cB + kstep, voffB); PG8_STAGE(PG8_SA(1, 0), cA + kstep, voffA); PG8_STAGE(PG8_SB(1, 1), cB + hstep + kstep, voffB);
;         PG8_WAIT_V(6); PG8_BAR;
;     } else {
;         PG8_STAGE(PG8_SB(0, 0), cB, voffB); PG8_STAGE(PG8_SA(0, 0), cA, voffA); PG8_STAGE(PG8_SB(0, 1), cB + hstep, voffB); PG8_STAGE(PG8_SA(0, 1), cA + hstep, voffA);
;         if (wr == 1) PG8_BAR;
;         PG8_WAIT_V(4); PG8_BAR;
;         PG8_STAGE(PG8_SB(1, 0), cB + kstep, voffB); PG8_STAGE(PG8_SA(1, 0), cA + kstep, voffA); PG8_STAGE(PG8_SB(1, 1), cB + hstep + kstep, voffB);
;         PG8_WAIT_V(6); PG8_BAR;
;     }
;     for (;;) {
;         const bool has_next = S.next(ui + 1, nxt);
;         const char* nA = cA; const char* nB = cB; if (has_next) S.bases(nxt, g, tstep, nA, nB);
;         for (int t = 0; t < nt; t += 2) {
;             const bool last = (t == nt - 2);
;             const char* a1 = cA + (size_t)(t + 1) * kstep;
;             const char* a2 = last ? nA : cA + (size_t)(t + 2) * kstep; const char* b2 = last ? nB : cB + (size_t)(t + 2) * kstep;
;             const char* a3 = a2 + kstep; const char* b3 = b2 + kstep;
;             if (last && has_next) S.a_ready(nxt);
;             if constexpr (Epi::MIDK) { if (t == (nt >> 1)) { E.midk(acc, wr, fr); asm volatile("s_waitcnt lgkmcnt(0)" ::: "memory"); } }
;             if constexpr (SP2) {
	s_setprio 2
	v_mfma_f32_16x16x32_bf16 v[38:41], v[150:153], v[190:193], v[38:41]
	v_mfma_f32_16x16x32_bf16 v[38:41], v[154:157], v[196:199], v[38:41]
	v_mfma_f32_16x16x32_bf16 v[30:33], v[158:161], v[190:193], v[30:33]
	v_mfma_f32_16x16x32_bf16 v[30:33], v[162:165], v[196:199], v[30:33]
	v_mfma_f32_16x16x32_bf16 v[50:53], v[174:177], v[190:193], v[50:53]
	v_mfma_f32_16x16x32_bf16 v[50:53], v[178:181], v[196:199], v[50:53]
	v_mfma_f32_16x16x32_bf16 v[46:49], v[182:185], v[190:193], v[46:49]
	v_mfma_f32_16x16x32_bf16 v[46:49], v[186:189], v[196:199], v[46:49]
	v_mfma_f32_16x16x32_bf16 v[130:133], v[150:153], v[200:203], v[130:133]
	v_mfma_f32_16x16x32_bf16 v[130:133], v[154:157], v[204:207], v[130:133]
	v_mfma_f32_16x16x32_bf16 v[126:129], v[158:161], v[200:203], v[126:129]
	v_mfma_f32_16x16x32_bf16 v[126:129], v[162:165], v[204:207], v[126:129]
	v_mfma_f32_16x16x32_bf16 v[122:125], v[174:177], v[200:203], v[122:125]
	v_mfma_f32_16x16x32_bf16 v[122:125], v[178:181], v[204:207], v[122:125]
	v_mfma_f32_16x16x32_bf16 v[118:121], v[182:185], v[200:203], v[118:121]
	v_mfma_f32_16x16x32_bf16 v[118:121], v[186:189], v[204:207], v[118:121]
	v_mfma_f32_16x16x32_bf16 v[114:117], v[150:153], v[208:211], v[114:117]
	v_mfma_f32_16x16x32_bf16 v[114:117], v[154:157], v[212:215], v[114:117]
	v_mfma_f32_16x16x32_bf16 v[110:113], v[158:161], v[208:211], v[110:113]
	v_mfma_f32_16x16x32_bf16 v[110:113], v[162:165], v[212:215], v[110:113]
	v_mfma_f32_16x16x32_bf16 v[106:109], v[174:177], v[208:211], v[106:109]
	v_mfma_f32_16x16x32_bf16 v[106:109], v[178:181], v[212:215], v[106:109]
	v_mfma_f32_16x16x32_bf16 v[102:105], v[182:185], v[208:211], v[102:105]
	v_mfma_f32_16x16x32_bf16 v[102:105], v[186:189], v[212:215], v[102:105]
	v_mfma_f32_16x16x32_bf16 v[98:101], v[150:153], v[220:223], v[98:101]
	v_mfma_f32_16x16x32_bf16 v[98:101], v[154:157], v[224:227], v[98:101]
	v_mfma_f32_16x16x32_bf16 v[94:97], v[158:161], v[220:223], v[94:97]
	v_mfma_f32_16x16x32_bf16 v[94:97], v[162:165], v[224:227], v[94:97]
	v_mfma_f32_16x16x32_bf16 v[90:93], v[174:177], v[220:223], v[90:93]
	v_mfma_f32_16x16x32_bf16 v[90:93], v[178:181], v[224:227], v[90:93]
	v_mfma_f32_16x16x32_bf16 v[86:89], v[182:185], v[220:223], v[86:89]
	v_mfma_f32_16x16x32_bf16 v[86:89], v[186:189], v[224:227], v[86:89]
	s_setprio 0
	ds_read_b128 v[190:193], v171 offset:49152
	ds_read_b128 v[196:199], v171 offset:50176
	ds_read_b128 v[200:203], v171 offset:51200
	ds_read_b128 v[204:207], v171 offset:52224
	ds_read_b128 v[208:211], v171 offset:53248
	ds_read_b128 v[212:215], v171 offset:54272
	ds_read_b128 v[220:223], v171 offset:55296
	ds_read_b128 v[224:227], v171 offset:56320
	s_add_u32 s0, s90, 0x80
	s_addc_u32 s1, s91, 0
	s_add_u32 vcc_lo, s0, 0x100000
	s_addc_u32 vcc_hi, s1, 0
	s_add_i32 m0, s27, 0x18000
	s_nop 0
	global_load_lds_dwordx4 v136, s[0:1]
	s_add_i32 m0, s27, 0x1a000
	s_nop 0
	global_load_lds_dwordx4 v140, s[0:1]
	s_add_i32 m0, s27, 0x1c000
	s_nop 0
	global_load_lds_dwordx4 v136, vcc
	s_add_i32 m0, s27, 0x1e000
	s_nop 0
	global_load_lds_dwordx4 v140, vcc
	s_sleep 2
	s_waitcnt lgkmcnt(0)
	s_waitcnt vmcnt(6)
	s_barrier
	s_setprio 2
	v_mfma_f32_16x16x32_bf16 v[82:85], v[150:153], v[190:193], v[82:85]
	v_mfma_f32_16x16x32_bf16 v[82:85], v[154:157], v[196:199], v[82:85]
	v_mfma_f32_16x16x32_bf16 v[78:81], v[158:161], v[190:193], v[78:81]
	v_mfma_f32_16x16x32_bf16 v[78:81], v[162:165], v[196:199], v[78:81]
	v_mfma_f32_16x16x32_bf16 v[74:77], v[174:177], v[190:193], v[74:77]
	v_mfma_f32_16x16x32_bf16 v[74:77], v[178:181], v[196:199], v[74:77]
	v_mfma_f32_16x16x32_bf16 v[70:73], v[182:185], v[190:193], v[70:73]
	v_mfma_f32_16x16x32_bf16 v[70:73], v[186:189], v[196:199], v[70:73]
	v_mfma_f32_16x16x32_bf16 v[66:69], v[150:153], v[200:203], v[66:69]
	v_mfma_f32_16x16x32_bf16 v[66:69], v[154:157], v[204:207], v[66:69]
	v_mfma_f32_16x16x32_bf16 v[62:65], v[158:161], v[200:203], v[62:65]
	v_mfma_f32_16x16x32_bf16 v[62:65], v[162:165], v[204:207], v[62:65]
	v_mfma_f32_16x16x32_bf16 v[58:61], v[174:177], v[200:203], v[58:61]
	v_mfma_f32_16x16x32_bf16 v[58:61], v[178:181], v[204:207], v[58:61]
	v_mfma_f32_16x16x32_bf16 v[54:57], v[182:185], v[200:203], v[54:57]
	v_mfma_f32_16x16x32_bf16 v[54:57], v[186:189], v[204:207], v[54:57]
	v_mfma_f32_16x16x32_bf16 v[42:45], v[150:153], v[208:211], v[42:45]
	v_mfma_f32_16x16x32_bf16 v[42:45], v[154:157], v[212:215], v[42:45]
	v_mfma_f32_16x16x32_bf16 v[34:37], v[158:161], v[208:211], v[34:37]
	v_mfma_f32_16x16x32_bf16 v[34:37], v[162:165], v[212:215], v[34:37]
	v_mfma_f32_16x16x32_bf16 v[26:29], v[174:177], v[208:211], v[26:29]
	v_mfma_f32_16x16x32_bf16 v[26:29], v[178:181], v[212:215], v[26:29]
	v_mfma_f32_16x16x32_bf16 v[22:25], v[182:185], v[208:211], v[22:25]
	v_mfma_f32_16x16x32_bf16 v[22:25], v[186:189], v[212:215], v[22:25]
	v_mfma_f32_16x16x32_bf16 v[18:21], v[150:153], v[220:223], v[18:21]
	v_mfma_f32_16x16x32_bf16 v[18:21], v[154:157], v[224:227], v[18:21]
	v_mfma_f32_16x16x32_bf16 v[14:17], v[158:161], v[220:223], v[14:17]
	v_mfma_f32_16x16x32_bf16 v[14:17], v[162:165], v[224:227], v[14:17]
	v_mfma_f32_16x16x32_bf16 v[8:11], v[174:177], v[220:223], v[10:13]
	v_mfma_f32_16x16x32_bf16 v[10:13], v[178:181], v[224:227], v[8:11]
	v_mfma_f32_16x16x32_bf16 v[4:7], v[182:185], v[220:223], v[4:7]
	v_mfma_f32_16x16x32_bf16 v[6:9], v[186:189], v[224:227], v[4:7]
	s_setprio 0
	s_add_i32 s23, s23, 2
	s_add_u32 s88, s88, 0x100
	s_addc_u32 s89, s89, 0
	s_add_u32 s9, s9, 0x100
	s_addc_u32 s21, s21, 0
	s_cmp_gt_u32 s23, 61
	s_cbranch_scc0 .Lip_h1

; #define PG8_BAR __builtin_amdgcn_s_barrier()
; template <class Epi, class Sched, bool ALIGN_EPI = false, bool SP2 = false>
; __device__ __forceinline__ void gemm_phase(PG8_LAS unsigned char* lds, const Gemm g, const Sched& S, const Epi& E) {
;     ...
;     Unit cur, nxt; int ui = 0;
;     if (!S.next(0, cur)) return;
;     f32x4 acc[2][2][4][2];
; #pragma unroll
;     for (int a = 0; a < 2; ++a)
; #pragma unroll
;         for (int b = 0; b < 2; ++b)
; #pragma unroll
;             for (int m = 0; m < 4; ++m)
; #pragma unroll
;                 for (int n = 0; n < 2; ++n) acc[a][b][m][n] = (f32x4){0.f, 0.f, 0.f, 0.f};
;     bf16x8 At[4][2], B0[2][2], B1[2][2];
;     const char* cA; const char* cB; S.bases(cur, g, tstep, cA, cB);
;     S.a_ready(cur);
;     if constexpr (SP2) {
;         PG8_STAGE(PG8_SB(0, 0), cB, voffB); PG8_STAGE(PG8_SB(0, 1), cB + hstep, voffB); PG8_STAGE(PG8_SA(0, 0), cA, voffA); PG8_STAGE(PG8_SA(0, 1), cA + hstep, voffA);
;         if (wr == 1) PG8_BAR;
;         PG8_WAIT_V(2); PG8_BAR;
;         PG8_STAGE(PG8_SB(1, 0), cB + kstep, voffB); PG8_STAGE(PG8_SA(1, 0), cA + kstep, voffA); PG8_STAGE(PG8_SB(1, 1), cB + hstep + kstep, voffB);
;         PG8_WAIT_V(6); PG8_BAR;
;     } else {
;         PG8_STAGE(PG8_SB(0, 0), cB, voffB); PG8_STAGE(PG8_SA(0, 0), cA, voffA); PG8_STAGE(PG8_SB(0, 1), cB + hstep, voffB); PG8_STAGE(PG8_SA(0, 1), cA + hstep, voffA);
;         if (wr == 1) PG8_BAR;
;         PG8_WAIT_V(4); PG8_BAR;
;         PG8_STAGE(PG8_SB(1, 0), cB + kstep, voffB); PG8_STAGE(PG8_SA(1, 0), cA + kstep, voffA); PG8_STAGE(PG8_SB(1, 1), cB + hstep + kstep, voffB);
;         PG8_WAIT_V(6); PG8_BAR;
;     }
;     for (;;) {
;         const bool has_next = S.next(ui + 1, nxt);
;         const char* nA = cA; const char* nB = cB; if (has_next) S.bases(nxt, g, tstep, nA, nB);
;         for (int t = 0; t < nt; t += 2) {
;             const bool last = (t == nt - 2);
;             const char* a1 = cA + (size_t)(t + 1) * kstep;
;             const char* a2 = last ? nA : cA + (size_t)(t + 2) * kstep; const char* b2 = last ? nB : cB + (size_t)(t + 2) * kstep;
;             const char* a3 = a2 + kstep; const char* b3 = b2 + kstep;
;             if (last && has_next) S.a_ready(nxt);
;             if constexpr (Epi::MIDK) { if (t == (nt >> 1)) { E.midk(acc, wr, fr); asm volatile("s_waitcnt lgkmcnt(0)" ::: "memory"); } }
;             if constexpr (SP2) {
.LBB0_911:
	v_add_u32_e32 v3, s83, v219
	ds_read_b128 v[98:101], v3
	ds_read_b128 v[102:105], v3 offset:1024
	ds_read_b128 v[106:109], v3 offset:2048
	ds_read_b128 v[166:169], v3 offset:3072
	v_add_u32_e32 v3, s86, v219
	s_add_u32 s62, s58, s60
	ds_read_b128 v[170:173], v3
	ds_read_b128 v[174:177], v3 offset:1024
	ds_read_b128 v[178:181], v3 offset:2048
	ds_read_b128 v[182:185], v3 offset:3072
	s_addc_u32 s63, s59, s61
	s_add_u32 s62, s62, 0x100
	s_addc_u32 s63, s63, 0
	s_add_u32 s93, s90, s60
	s_addc_u32 s94, s91, s61
	s_cmpk_eq_i32 s60, 0x1f00
	s_cselect_b32 s65, s19, s63
	s_cselect_b32 s64, s21, s62
	s_cselect_b32 s63, s53, s94
	s_cselect_b32 s62, s57, s93
	v_lshl_add_u64 v[4:5], v[94:95], 0, s[60:61]
	s_add_i32 m0, s24, 0xc000
	ds_read_b128 v[186:189], v244
	ds_read_b128 v[190:193], v244 offset:1024
	ds_read_b128 v[196:199], v244 offset:2048
	ds_read_b128 v[200:203], v244 offset:3072
	ds_read_b128 v[204:207], v244 offset:4096
	ds_read_b128 v[208:211], v244 offset:5120
	ds_read_b128 v[212:215], v244 offset:6144
	ds_read_b128 v[246:249], v244 offset:7168
	global_load_lds_dwordx4 v[4:5], off
	v_lshl_add_u64 v[4:5], v[96:97], 0, s[60:61]
	s_add_i32 m0, s24, 0xe000
	s_nop 0
	global_load_lds_dwordx4 v[4:5], off
	s_waitcnt vmcnt(8)
	s_waitcnt lgkmcnt(0)
	s_barrier
	s_setprio 1
	s_waitcnt lgkmcnt(0)
	v_mfma_f32_16x16x32_bf16 v[146:149], v[98:101], v[186:189], v[146:149]
	v_mfma_f32_16x16x32_bf16 v[146:149], v[102:105], v[190:193], v[146:149]
	v_mfma_f32_16x16x32_bf16 v[142:145], v[106:109], v[186:189], v[142:145]
	v_mfma_f32_16x16x32_bf16 v[142:145], v[166:169], v[190:193], v[142:145]
	v_mfma_f32_16x16x32_bf16 v[66:69], v[170:173], v[186:189], v[66:69]
	v_mfma_f32_16x16x32_bf16 v[66:69], v[174:177], v[190:193], v[66:69]
	v_mfma_f32_16x16x32_bf16 v[62:65], v[178:181], v[186:189], v[62:65]
	v_mfma_f32_16x16x32_bf16 v[62:65], v[182:185], v[190:193], v[62:65]
	v_mfma_f32_16x16x32_bf16 v[138:141], v[98:101], v[196:199], v[138:141]
	v_mfma_f32_16x16x32_bf16 v[138:141], v[102:105], v[200:203], v[138:141]
	v_mfma_f32_16x16x32_bf16 v[134:137], v[106:109], v[196:199], v[134:137]
	v_mfma_f32_16x16x32_bf16 v[134:137], v[166:169], v[200:203], v[134:137]
	v_mfma_f32_16x16x32_bf16 v[58:61], v[170:173], v[196:199], v[58:61]
	v_mfma_f32_16x16x32_bf16 v[58:61], v[174:177], v[200:203], v[58:61]
	v_mfma_f32_16x16x32_bf16 v[54:57], v[178:181], v[196:199], v[54:57]
	v_mfma_f32_16x16x32_bf16 v[54:57], v[182:185], v[200:203], v[54:57]
	s_setprio 0
	s_setprio 1
	v_mfma_f32_16x16x32_bf16 v[130:133], v[98:101], v[204:207], v[130:133]
	v_mfma_f32_16x16x32_bf16 v[130:133], v[102:105], v[208:211], v[130:133]
	v_mfma_f32_16x16x32_bf16 v[126:129], v[106:109], v[204:207], v[126:129]
	v_mfma_f32_16x16x32_bf16 v[126:129], v[166:169], v[208:211], v[126:129]
	v_mfma_f32_16x16x32_bf16 v[50:53], v[170:173], v[204:207], v[50:53]
	v_mfma_f32_16x16x32_bf16 v[50:53], v[174:177], v[208:211], v[50:53]
	v_mfma_f32_16x16x32_bf16 v[46:49], v[178:181], v[204:207], v[46:49]
	v_mfma_f32_16x16x32_bf16 v[46:49], v[182:185], v[208:211], v[46:49]
	v_mfma_f32_16x16x32_bf16 v[122:125], v[98:101], v[212:215], v[122:125]
	v_mfma_f32_16x16x32_bf16 v[122:125], v[102:105], v[246:249], v[122:125]
	v_mfma_f32_16x16x32_bf16 v[118:121], v[106:109], v[212:215], v[118:121]
	v_mfma_f32_16x16x32_bf16 v[118:121], v[166:169], v[246:249], v[118:121]
	v_mfma_f32_16x16x32_bf16 v[42:45], v[170:173], v[212:215], v[42:45]
	v_mfma_f32_16x16x32_bf16 v[42:45], v[174:177], v[246:249], v[42:45]
	v_mfma_f32_16x16x32_bf16 v[38:41], v[178:181], v[212:215], v[38:41]
	v_mfma_f32_16x16x32_bf16 v[38:41], v[182:185], v[246:249], v[38:41]
	s_setprio 0
	s_barrier
	s_add_i32 s93, s83, s2
	v_lshl_add_u64 v[216:217], s[62:63], 0, v[152:153]
	s_mov_b32 m0, s93
	ds_read_b128 v[186:189], v244 offset:16384
	ds_read_b128 v[190:193], v244 offset:17408
	ds_read_b128 v[196:199], v244 offset:18432
	ds_read_b128 v[200:203], v244 offset:19456
	ds_read_b128 v[204:207], v244 offset:20480
	ds_read_b128 v[208:211], v244 offset:21504
	ds_read_b128 v[212:215], v244 offset:22528
	ds_read_b128 v[246:249], v244 offset:23552
	global_load_lds_dwordx4 v[216:217], off
	s_add_i32 m0, s93, 0x2000
	s_add_u32 s94, s62, 0x100000
	v_lshl_add_u64 v[250:251], s[62:63], 0, v[156:157]
	s_addc_u32 s95, s63, 0
	s_add_i32 s93, s86, s2
	global_load_lds_dwordx4 v[250:251], off
	v_lshl_add_u64 v[4:5], s[94:95], 0, v[152:153]
	s_mov_b32 m0, s93
	v_lshl_add_u64 v[252:253], s[64:65], 0, v[150:151]
	global_load_lds_dwordx4 v[4:5], off
	v_lshl_add_u64 v[4:5], s[94:95], 0, v[156:157]
	s_add_i32 m0, s93, 0x2000
	v_lshl_add_u64 v[222:223], s[64:65], 0, v[154:155]
	global_load_lds_dwordx4 v[4:5], off
	s_mov_b32 m0, s24
	s_nop 0
	global_load_lds_dwordx4 v[252:253], off
	s_mov_b32 m0, s25
	s_nop 0
	global_load_lds_dwordx4 v[222:223], off
	s_waitcnt vmcnt(8)
	s_waitcnt lgkmcnt(0)
	s_barrier
; #define PG8_BAR __builtin_amdgcn_s_barrier()
; template <class Epi, class Sched, bool ALIGN_EPI = false, bool SP2 = false>
; __device__ __forceinline__ void gemm_phase(PG8_LAS unsigned char* lds, const Gemm g, const Sched& S, const Epi& E) {
;     ...
;     Unit cur, nxt; int ui = 0;
;     if (!S.next(0, cur)) return;
;     f32x4 acc[2][2][4][2];
; #pragma unroll
;     for (int a = 0; a < 2; ++a)
; #pragma unroll
;         for (int b = 0; b < 2; ++b)
; #pragma unroll
;             for (int m = 0; m < 4; ++m)
; #pragma unroll
;                 for (int n = 0; n < 2; ++n) acc[a][b][m][n] = (f32x4){0.f, 0.f, 0.f, 0.f};
;     bf16x8 At[4][2], B0[2][2], B1[2][2];
;     const char* cA; const char* cB; S.bases(cur, g, tstep, cA, cB);
;     S.a_ready(cur);
;     if constexpr (SP2) {
;         PG8_STAGE(PG8_SB(0, 0), cB, voffB); PG8_STAGE(PG8_SB(0, 1), cB + hstep, voffB); PG8_STAGE(PG8_SA(0, 0), cA, voffA); PG8_STAGE(PG8_SA(0, 1), cA + hstep, voffA);
;         if (wr == 1) PG8_BAR;
;         PG8_WAIT_V(2); PG8_BAR;
;         PG8_STAGE(PG8_SB(1, 0), cB + kstep, voffB); PG8_STAGE(PG8_SA(1, 0), cA + kstep, voffA); PG8_STAGE(PG8_SB(1, 1), cB + hstep + kstep, voffB);
;         PG8_WAIT_V(6); PG8_BAR;
;     } else {
;         PG8_STAGE(PG8_SB(0, 0), cB, voffB); PG8_STAGE(PG8_SA(0, 0), cA, voffA); PG8_STAGE(PG8_SB(0, 1), cB + hstep, voffB); PG8_STAGE(PG8_SA(0, 1), cA + hstep, voffA);
;         if (wr == 1) PG8_BAR;
;         PG8_WAIT_V(4); PG8_BAR;
;         PG8_STAGE(PG8_SB(1, 0), cB + kstep, voffB); PG8_STAGE(PG8_SA(1, 0), cA + kstep, voffA); PG8_STAGE(PG8_SB(1, 1), cB + hstep + kstep, voffB);
;         PG8_WAIT_V(6); PG8_BAR;
;     }
;     for (;;) {
;         const bool has_next = S.next(ui + 1, nxt);
;         const char* nA = cA; const char* nB = cB; if (has_next) S.bases(nxt, g, tstep, nA, nB);
;         for (int t = 0; t < nt; t += 2) {
;             const bool last = (t == nt - 2);
;             const char* a1 = cA + (size_t)(t + 1) * kstep;
;             const char* a2 = last ? nA : cA + (size_t)(t + 2) * kstep; const char* b2 = last ? nB : cB + (size_t)(t + 2) * kstep;
;             const char* a3 = a2 + kstep; const char* b3 = b2 + kstep;
;             if (last && has_next) S.a_ready(nxt);
;             if constexpr (Epi::MIDK) { if (t == (nt >> 1)) { E.midk(acc, wr, fr); asm volatile("s_waitcnt lgkmcnt(0)" ::: "memory"); } }
;             if constexpr (SP2) {
	s_setprio 1
	s_waitcnt lgkmcnt(0)
	v_mfma_f32_16x16x32_bf16 v[114:117], v[98:101], v[186:189], v[114:117]
	v_mfma_f32_16x16x32_bf16 v[114:117], v[102:105], v[190:193], v[114:117]
	v_mfma_f32_16x16x32_bf16 v[110:113], v[106:109], v[186:189], v[110:113]
	v_mfma_f32_16x16x32_bf16 v[110:113], v[166:169], v[190:193], v[110:113]
	v_mfma_f32_16x16x32_bf16 v[34:37], v[170:173], v[186:189], v[34:37]
	v_mfma_f32_16x16x32_bf16 v[34:37], v[174:177], v[190:193], v[34:37]
	v_mfma_f32_16x16x32_bf16 v[30:33], v[178:181], v[186:189], v[30:33]
	v_mfma_f32_16x16x32_bf16 v[30:33], v[182:185], v[190:193], v[30:33]
	v_mfma_f32_16x16x32_bf16 v[90:93], v[98:101], v[196:199], v[90:93]
	v_mfma_f32_16x16x32_bf16 v[90:93], v[102:105], v[200:203], v[90:93]
	v_mfma_f32_16x16x32_bf16 v[86:89], v[106:109], v[196:199], v[86:89]
	v_mfma_f32_16x16x32_bf16 v[86:89], v[166:169], v[200:203], v[86:89]
	v_mfma_f32_16x16x32_bf16 v[26:29], v[170:173], v[196:199], v[26:29]
	v_mfma_f32_16x16x32_bf16 v[26:29], v[174:177], v[200:203], v[26:29]
	v_mfma_f32_16x16x32_bf16 v[22:25], v[178:181], v[196:199], v[22:25]
	v_mfma_f32_16x16x32_bf16 v[22:25], v[182:185], v[200:203], v[22:25]
	s_setprio 0
	s_setprio 1
	v_mfma_f32_16x16x32_bf16 v[82:85], v[98:101], v[204:207], v[82:85]
	v_mfma_f32_16x16x32_bf16 v[82:85], v[102:105], v[208:211], v[82:85]
	v_mfma_f32_16x16x32_bf16 v[78:81], v[106:109], v[204:207], v[78:81]
	v_mfma_f32_16x16x32_bf16 v[78:81], v[166:169], v[208:211], v[78:81]
	v_mfma_f32_16x16x32_bf16 v[18:21], v[170:173], v[204:207], v[18:21]
	v_mfma_f32_16x16x32_bf16 v[18:21], v[174:177], v[208:211], v[18:21]
	v_mfma_f32_16x16x32_bf16 v[14:17], v[178:181], v[204:207], v[14:17]
	v_mfma_f32_16x16x32_bf16 v[14:17], v[182:185], v[208:211], v[14:17]
	v_mfma_f32_16x16x32_bf16 v[74:77], v[98:101], v[212:215], v[74:77]
	v_mfma_f32_16x16x32_bf16 v[74:77], v[102:105], v[246:249], v[74:77]
	v_mfma_f32_16x16x32_bf16 v[70:73], v[106:109], v[212:215], v[70:73]
	v_mfma_f32_16x16x32_bf16 v[70:73], v[166:169], v[246:249], v[70:73]
	v_mfma_f32_16x16x32_bf16 v[10:13], v[170:173], v[212:215], v[10:13]
	v_mfma_f32_16x16x32_bf16 v[10:13], v[174:177], v[246:249], v[10:13]
	v_mfma_f32_16x16x32_bf16 v[4:7], v[178:181], v[212:215], v[6:9]
	v_mfma_f32_16x16x32_bf16 v[4:7], v[182:185], v[246:249], v[4:7]
	s_setprio 0
	s_barrier
	s_add_i32 s93, 0, 0x18000
	v_add_u32_e32 v3, s93, v219
	s_add_i32 s94, 0, 0x1c000
	ds_read_b128 v[98:101], v3
	ds_read_b128 v[102:105], v3 offset:1024
	ds_read_b128 v[106:109], v3 offset:2048
	ds_read_b128 v[166:169], v3 offset:3072
	v_add_u32_e32 v3, s94, v219
	ds_read_b128 v[170:173], v3
	ds_read_b128 v[174:177], v3 offset:1024
	ds_read_b128 v[178:181], v3 offset:2048
	ds_read_b128 v[182:185], v3 offset:3072
	s_add_u32 s64, s64, 0x100000
	s_addc_u32 s65, s65, 0
	s_mov_b32 m0, s26
	v_lshl_add_u64 v[8:9], s[64:65], 0, v[150:151]
	ds_read_b128 v[186:189], v244 offset:32768
	ds_read_b128 v[190:193], v244 offset:33792
	ds_read_b128 v[196:199], v244 offset:34816
	ds_read_b128 v[200:203], v244 offset:35840
	ds_read_b128 v[204:207], v244 offset:36864
	ds_read_b128 v[208:211], v244 offset:37888
	ds_read_b128 v[212:215], v244 offset:38912
	ds_read_b128 v[246:249], v244 offset:39936
	global_load_lds_dwordx4 v[8:9], off
	v_lshl_add_u64 v[8:9], s[64:65], 0, v[154:155]
	s_mov_b32 m0, s27
	s_nop 0
	global_load_lds_dwordx4 v[8:9], off
	s_waitcnt vmcnt(8)
	s_waitcnt lgkmcnt(0)
	s_barrier
	s_setprio 1
	s_waitcnt lgkmcnt(0)
	v_mfma_f32_16x16x32_bf16 v[146:149], v[98:101], v[186:189], v[146:149]
	v_mfma_f32_16x16x32_bf16 v[146:149], v[102:105], v[190:193], v[146:149]
	v_mfma_f32_16x16x32_bf16 v[142:145], v[106:109], v[186:189], v[142:145]
	v_mfma_f32_16x16x32_bf16 v[142:145], v[166:169], v[190:193], v[142:145]
	v_mfma_f32_16x16x32_bf16 v[66:69], v[170:173], v[186:189], v[66:69]
	v_mfma_f32_16x16x32_bf16 v[66:69], v[174:177], v[190:193], v[66:69]
	v_mfma_f32_16x16x32_bf16 v[62:65], v[178:181], v[186:189], v[62:65]
	v_mfma_f32_16x16x32_bf16 v[62:65], v[182:185], v[190:193], v[62:65]
	v_mfma_f32_16x16x32_bf16 v[138:141], v[98:101], v[196:199], v[138:141]
	v_mfma_f32_16x16x32_bf16 v[138:141], v[102:105], v[200:203], v[138:141]
	v_mfma_f32_16x16x32_bf16 v[134:137], v[106:109], v[196:199], v[134:137]
	v_mfma_f32_16x16x32_bf16 v[134:137], v[166:169], v[200:203], v[134:137]
	v_mfma_f32_16x16x32_bf16 v[58:61], v[170:173], v[196:199], v[58:61]
	v_mfma_f32_16x16x32_bf16 v[58:61], v[174:177], v[200:203], v[58:61]
	v_mfma_f32_16x16x32_bf16 v[54:57], v[178:181], v[196:199], v[54:57]
	v_mfma_f32_16x16x32_bf16 v[54:57], v[182:185], v[200:203], v[54:57]
	s_setprio 0
	s_setprio 1
	v_mfma_f32_16x16x32_bf16 v[130:133], v[98:101], v[204:207], v[130:133]
	v_mfma_f32_16x16x32_bf16 v[130:133], v[102:105], v[208:211], v[130:133]
	v_mfma_f32_16x16x32_bf16 v[126:129], v[106:109], v[204:207], v[126:129]
	v_mfma_f32_16x16x32_bf16 v[126:129], v[166:169], v[208:211], v[126:129]
	v_mfma_f32_16x16x32_bf16 v[50:53], v[170:173], v[204:207], v[50:53]
	v_mfma_f32_16x16x32_bf16 v[50:53], v[174:177], v[208:211], v[50:53]
	v_mfma_f32_16x16x32_bf16 v[46:49], v[178:181], v[204:207], v[46:49]
	v_mfma_f32_16x16x32_bf16 v[46:49], v[182:185], v[208:211], v[46:49]
	v_mfma_f32_16x16x32_bf16 v[122:125], v[98:101], v[212:215], v[122:125]
	v_mfma_f32_16x16x32_bf16 v[122:125], v[102:105], v[246:249], v[122:125]
	v_mfma_f32_16x16x32_bf16 v[118:121], v[106:109], v[212:215], v[118:121]
	v_mfma_f32_16x16x32_bf16 v[118:121], v[166:169], v[246:249], v[118:121]
	v_mfma_f32_16x16x32_bf16 v[42:45], v[170:173], v[212:215], v[42:45]
	v_mfma_f32_16x16x32_bf16 v[42:45], v[174:177], v[246:249], v[42:45]
	v_mfma_f32_16x16x32_bf16 v[38:41], v[178:181], v[212:215], v[38:41]
	v_mfma_f32_16x16x32_bf16 v[38:41], v[182:185], v[246:249], v[38:41]
	s_setprio 0
	s_barrier
; #define PG8_BAR __builtin_amdgcn_s_barrier()
; template <class Epi, class Sched, bool ALIGN_EPI = false, bool SP2 = false>
; __device__ __forceinline__ void gemm_phase(PG8_LAS unsigned char* lds, const Gemm g, const Sched& S, const Epi& E) {
;     ...
;     Unit cur, nxt; int ui = 0;
;     if (!S.next(0, cur)) return;
;     f32x4 acc[2][2][4][2];
; #pragma unroll
;     for (int a = 0; a < 2; ++a)
; #pragma unroll
;         for (int b = 0; b < 2; ++b)
; #pragma unroll
;             for (int m = 0; m < 4; ++m)
; #pragma unroll
;                 for (int n = 0; n < 2; ++n) acc[a][b][m][n] = (f32x4){0.f, 0.f, 0.f, 0.f};
;     bf16x8 At[4][2], B0[2][2], B1[2][2];
;     const char* cA; const char* cB; S.bases(cur, g, tstep, cA, cB);
;     S.a_ready(cur);
;     if constexpr (SP2) {
;         PG8_STAGE(PG8_SB(0, 0), cB, voffB); PG8_STAGE(PG8_SB(0, 1), cB + hstep, voffB); PG8_STAGE(PG8_SA(0, 0), cA, voffA); PG8_STAGE(PG8_SA(0, 1), cA + hstep, voffA);
;         if (wr == 1) PG8_BAR;
;         PG8_WAIT_V(2); PG8_BAR;
;         PG8_STAGE(PG8_SB(1, 0), cB + kstep, voffB); PG8_STAGE(PG8_SA(1, 0), cA + kstep, voffA); PG8_STAGE(PG8_SB(1, 1), cB + hstep + kstep, voffB);
;         PG8_WAIT_V(6); PG8_BAR;
;     } else {
;         PG8_STAGE(PG8_SB(0, 0), cB, voffB); PG8_STAGE(PG8_SA(0, 0), cA, voffA); PG8_STAGE(PG8_SB(0, 1), cB + hstep, voffB); PG8_STAGE(PG8_SA(0, 1), cA + hstep, voffA);
;         if (wr == 1) PG8_BAR;
;         PG8_WAIT_V(4); PG8_BAR;
;         PG8_STAGE(PG8_SB(1, 0), cB + kstep, voffB); PG8_STAGE(PG8_SA(1, 0), cA + kstep, voffA); PG8_STAGE(PG8_SB(1, 1), cB + hstep + kstep, voffB);
;         PG8_WAIT_V(6); PG8_BAR;
;     }
;     for (;;) {
;         const bool has_next = S.next(ui + 1, nxt);
;         const char* nA = cA; const char* nB = cB; if (has_next) S.bases(nxt, g, tstep, nA, nB);
;         for (int t = 0; t < nt; t += 2) {
;             const bool last = (t == nt - 2);
;             const char* a1 = cA + (size_t)(t + 1) * kstep;
;             const char* a2 = last ? nA : cA + (size_t)(t + 2) * kstep; const char* b2 = last ? nB : cB + (size_t)(t + 2) * kstep;
;             const char* a3 = a2 + kstep; const char* b3 = b2 + kstep;
;             if (last && has_next) S.a_ready(nxt);
;             if constexpr (Epi::MIDK) { if (t == (nt >> 1)) { E.midk(acc, wr, fr); asm volatile("s_waitcnt lgkmcnt(0)" ::: "memory"); } }
;             if constexpr (SP2) {
	s_add_i32 s64, s93, s2
	v_lshl_add_u64 v[8:9], v[216:217], 0, s[14:15]
	s_mov_b32 m0, s64
	ds_read_b128 v[186:189], v244 offset:49152
	ds_read_b128 v[190:193], v244 offset:50176
	ds_read_b128 v[196:199], v244 offset:51200
	ds_read_b128 v[200:203], v244 offset:52224
	ds_read_b128 v[204:207], v244 offset:53248
	ds_read_b128 v[208:211], v244 offset:54272
	ds_read_b128 v[212:215], v244 offset:55296
	ds_read_b128 v[246:249], v244 offset:56320
	global_load_lds_dwordx4 v[8:9], off
	s_add_i32 m0, s64, 0x2000
	s_add_u32 s62, s62, 0x100080
	v_lshl_add_u64 v[8:9], v[250:251], 0, s[14:15]
	s_addc_u32 s63, s63, 0
	s_add_i32 s64, s94, s2
	global_load_lds_dwordx4 v[8:9], off
	v_lshl_add_u64 v[8:9], s[62:63], 0, v[152:153]
	s_mov_b32 m0, s64
	s_nop 0
	global_load_lds_dwordx4 v[8:9], off
	v_lshl_add_u64 v[8:9], s[62:63], 0, v[156:157]
	s_add_i32 m0, s64, 0x2000
	s_nop 0
	global_load_lds_dwordx4 v[8:9], off
	v_lshl_add_u64 v[8:9], v[252:253], 0, s[14:15]
	s_mov_b32 m0, s66
	s_nop 0
	global_load_lds_dwordx4 v[8:9], off
	v_lshl_add_u64 v[8:9], v[222:223], 0, s[14:15]
	s_mov_b32 m0, s67
	s_nop 0
	global_load_lds_dwordx4 v[8:9], off
	s_waitcnt vmcnt(8)
	s_waitcnt lgkmcnt(0)
	s_barrier
	s_setprio 1
	s_waitcnt lgkmcnt(0)
	v_mfma_f32_16x16x32_bf16 v[114:117], v[98:101], v[186:189], v[114:117]
	v_mfma_f32_16x16x32_bf16 v[114:117], v[102:105], v[190:193], v[114:117]
	v_mfma_f32_16x16x32_bf16 v[110:113], v[106:109], v[186:189], v[110:113]
	v_mfma_f32_16x16x32_bf16 v[110:113], v[166:169], v[190:193], v[110:113]
	v_mfma_f32_16x16x32_bf16 v[34:37], v[170:173], v[186:189], v[34:37]
	v_mfma_f32_16x16x32_bf16 v[34:37], v[174:177], v[190:193], v[34:37]
	v_mfma_f32_16x16x32_bf16 v[30:33], v[178:181], v[186:189], v[30:33]
	v_mfma_f32_16x16x32_bf16 v[30:33], v[182:185], v[190:193], v[30:33]
	v_mfma_f32_16x16x32_bf16 v[90:93], v[98:101], v[196:199], v[90:93]
	v_mfma_f32_16x16x32_bf16 v[90:93], v[102:105], v[200:203], v[90:93]
	v_mfma_f32_16x16x32_bf16 v[86:89], v[106:109], v[196:199], v[86:89]
	v_mfma_f32_16x16x32_bf16 v[86:89], v[166:169], v[200:203], v[86:89]
	v_mfma_f32_16x16x32_bf16 v[26:29], v[170:173], v[196:199], v[26:29]
	v_mfma_f32_16x16x32_bf16 v[26:29], v[174:177], v[200:203], v[26:29]
	v_mfma_f32_16x16x32_bf16 v[22:25], v[178:181], v[196:199], v[22:25]
	v_mfma_f32_16x16x32_bf16 v[22:25], v[182:185], v[200:203], v[22:25]
	s_setprio 0
	s_setprio 1
	v_mfma_f32_16x16x32_bf16 v[82:85], v[98:101], v[204:207], v[82:85]
	v_mfma_f32_16x16x32_bf16 v[82:85], v[102:105], v[208:211], v[82:85]
	v_mfma_f32_16x16x32_bf16 v[78:81], v[106:109], v[204:207], v[78:81]
	v_mfma_f32_16x16x32_bf16 v[78:81], v[166:169], v[208:211], v[78:81]
	v_mfma_f32_16x16x32_bf16 v[18:21], v[170:173], v[204:207], v[18:21]
	v_mfma_f32_16x16x32_bf16 v[18:21], v[174:177], v[208:211], v[18:21]
	v_mfma_f32_16x16x32_bf16 v[14:17], v[178:181], v[204:207], v[14:17]
	v_mfma_f32_16x16x32_bf16 v[14:17], v[182:185], v[208:211], v[14:17]
	v_mfma_f32_16x16x32_bf16 v[74:77], v[98:101], v[212:215], v[74:77]
	v_mfma_f32_16x16x32_bf16 v[74:77], v[102:105], v[246:249], v[74:77]
	v_mfma_f32_16x16x32_bf16 v[70:73], v[106:109], v[212:215], v[70:73]
	v_mfma_f32_16x16x32_bf16 v[70:73], v[166:169], v[246:249], v[70:73]
	v_mfma_f32_16x16x32_bf16 v[8:11], v[170:173], v[212:215], v[10:13]
	v_mfma_f32_16x16x32_bf16 v[10:13], v[174:177], v[246:249], v[8:11]
	v_mfma_f32_16x16x32_bf16 v[4:7], v[178:181], v[212:215], v[4:7]
	v_mfma_f32_16x16x32_bf16 v[6:9], v[182:185], v[246:249], v[4:7]
	s_setprio 0
	s_barrier
	s_add_i32 s92, s92, 2
	s_add_u32 s60, s60, 0x100
	s_addc_u32 s61, s61, 0
	s_cmp_gt_u32 s92, 61
	s_cbranch_scc1 .LBB0_914

; #define PG8_BAR __builtin_amdgcn_s_barrier()
; template <class Epi, class Sched, bool ALIGN_EPI = false, bool SP2 = false>
; __device__ __forceinline__ void gemm_phase(PG8_LAS unsigned char* lds, const Gemm g, const Sched& S, const Epi& E) {
;     ...
;     Unit cur, nxt; int ui = 0;
;     if (!S.next(0, cur)) return;
;     f32x4 acc[2][2][4][2];
; #pragma unroll
;     for (int a = 0; a < 2; ++a)
; #pragma unroll
;         for (int b = 0; b < 2; ++b)
; #pragma unroll
;             for (int m = 0; m < 4; ++m)
; #pragma unroll
;                 for (int n = 0; n < 2; ++n) acc[a][b][m][n] = (f32x4){0.f, 0.f, 0.f, 0.f};
;     bf16x8 At[4][2], B0[2][2], B1[2][2];
;     const char* cA; const char* cB; S.bases(cur, g, tstep, cA, cB);
;     S.a_ready(cur);
;     if constexpr (SP2) {
;         PG8_STAGE(PG8_SB(0, 0), cB, voffB); PG8_STAGE(PG8_SB(0, 1), cB + hstep, voffB); PG8_STAGE(PG8_SA(0, 0), cA, voffA); PG8_STAGE(PG8_SA(0, 1), cA + hstep, voffA);
;         if (wr == 1) PG8_BAR;
;         PG8_WAIT_V(2); PG8_BAR;
;         PG8_STAGE(PG8_SB(1, 0), cB + kstep, voffB); PG8_STAGE(PG8_SA(1, 0), cA + kstep, voffA); PG8_STAGE(PG8_SB(1, 1), cB + hstep + kstep, voffB);
;         PG8_WAIT_V(6); PG8_BAR;
;     } else {
;         PG8_STAGE(PG8_SB(0, 0), cB, voffB); PG8_STAGE(PG8_SA(0, 0), cA, voffA); PG8_STAGE(PG8_SB(0, 1), cB + hstep, voffB); PG8_STAGE(PG8_SA(0, 1), cA + hstep, voffA);
;         if (wr == 1) PG8_BAR;
;         PG8_WAIT_V(4); PG8_BAR;
;         PG8_STAGE(PG8_SB(1, 0), cB + kstep, voffB); PG8_STAGE(PG8_SA(1, 0), cA + kstep, voffA); PG8_STAGE(PG8_SB(1, 1), cB + hstep + kstep, voffB);
;         PG8_WAIT_V(6); PG8_BAR;
;     }
;     for (;;) {
;         const bool has_next = S.next(ui + 1, nxt);
;         const char* nA = cA; const char* nB = cB; if (has_next) S.bases(nxt, g, tstep, nA, nB);
;         for (int t = 0; t < nt; t += 2) {
;             const bool last = (t == nt - 2);
;             const char* a1 = cA + (size_t)(t + 1) * kstep;
;             const char* a2 = last ? nA : cA + (size_t)(t + 2) * kstep; const char* b2 = last ? nB : cB + (size_t)(t + 2) * kstep;
;             const char* a3 = a2 + kstep; const char* b3 = b2 + kstep;
;             if (last && has_next) S.a_ready(nxt);
;             if constexpr (Epi::MIDK) { if (t == (nt >> 1)) { E.midk(acc, wr, fr); asm volatile("s_waitcnt lgkmcnt(0)" ::: "memory"); } }
;             if constexpr (SP2) {
.LBB0_1251:
	ds_read_b128 v[130:133], v177
	ds_read_b128 v[134:137], v177 offset:1024
	ds_read_b128 v[138:141], v177 offset:2048
	ds_read_b128 v[142:145], v177 offset:3072
	ds_read_b128 v[162:165], v178
	ds_read_b128 v[180:183], v178 offset:1024
	ds_read_b128 v[184:187], v178 offset:2048
	ds_read_b128 v[188:191], v178 offset:3072
	s_add_u32 s40, s36, 0xfff00080
	s_addc_u32 s41, s37, -1
	s_cmp_eq_u32 s58, 60
	s_cselect_b32 s43, s15, s41
	s_cselect_b32 s42, s17, s40
	s_cselect_b32 s41, s54, s57
	s_cselect_b32 s40, s55, s56
	ds_read_b128 v[196:199], v179
	ds_read_b128 v[200:203], v179 offset:1024
	ds_read_b128 v[204:207], v179 offset:2048
	ds_read_b128 v[208:211], v179 offset:3072
	ds_read_b128 v[212:215], v179 offset:4096
	ds_read_b128 v[220:223], v179 offset:5120
	ds_read_b128 v[224:227], v179 offset:6144
	ds_read_b128 v[228:231], v179 offset:7168
	s_add_i32 m0, s24, 0xc000
	s_nop 0
	global_load_lds_dwordx4 v146, s[36:37]
	s_add_i32 m0, s24, 0xe000
	s_nop 0
	global_load_lds_dwordx4 v150, s[36:37]
	s_waitcnt lgkmcnt(0)
	s_setprio 1
	v_mfma_f32_16x16x32_bf16 v[126:129], v[130:133], v[196:199], v[126:129]
	v_mfma_f32_16x16x32_bf16 v[126:129], v[134:137], v[200:203], v[126:129]
	v_mfma_f32_16x16x32_bf16 v[122:125], v[138:141], v[196:199], v[122:125]
	v_mfma_f32_16x16x32_bf16 v[122:125], v[142:145], v[200:203], v[122:125]
	v_mfma_f32_16x16x32_bf16 v[118:121], v[162:165], v[196:199], v[118:121]
	v_mfma_f32_16x16x32_bf16 v[118:121], v[180:183], v[200:203], v[118:121]
	v_mfma_f32_16x16x32_bf16 v[114:117], v[184:187], v[196:199], v[114:117]
	v_mfma_f32_16x16x32_bf16 v[114:117], v[188:191], v[200:203], v[114:117]
	v_mfma_f32_16x16x32_bf16 v[110:113], v[130:133], v[204:207], v[110:113]
	v_mfma_f32_16x16x32_bf16 v[110:113], v[134:137], v[208:211], v[110:113]
	v_mfma_f32_16x16x32_bf16 v[106:109], v[138:141], v[204:207], v[106:109]
	v_mfma_f32_16x16x32_bf16 v[106:109], v[142:145], v[208:211], v[106:109]
	v_mfma_f32_16x16x32_bf16 v[102:105], v[162:165], v[204:207], v[102:105]
	v_mfma_f32_16x16x32_bf16 v[102:105], v[180:183], v[208:211], v[102:105]
	v_mfma_f32_16x16x32_bf16 v[98:101], v[184:187], v[204:207], v[98:101]
	v_mfma_f32_16x16x32_bf16 v[98:101], v[188:191], v[208:211], v[98:101]
	v_mfma_f32_16x16x32_bf16 v[94:97], v[130:133], v[212:215], v[94:97]
	v_mfma_f32_16x16x32_bf16 v[94:97], v[134:137], v[220:223], v[94:97]
	v_mfma_f32_16x16x32_bf16 v[90:93], v[138:141], v[212:215], v[90:93]
	v_mfma_f32_16x16x32_bf16 v[90:93], v[142:145], v[220:223], v[90:93]
	v_mfma_f32_16x16x32_bf16 v[86:89], v[162:165], v[212:215], v[86:89]
	v_mfma_f32_16x16x32_bf16 v[86:89], v[180:183], v[220:223], v[86:89]
	v_mfma_f32_16x16x32_bf16 v[82:85], v[184:187], v[212:215], v[82:85]
	v_mfma_f32_16x16x32_bf16 v[82:85], v[188:191], v[220:223], v[82:85]
	v_mfma_f32_16x16x32_bf16 v[78:81], v[130:133], v[224:227], v[78:81]
	v_mfma_f32_16x16x32_bf16 v[78:81], v[134:137], v[228:231], v[78:81]
	v_mfma_f32_16x16x32_bf16 v[74:77], v[138:141], v[224:227], v[74:77]
	v_mfma_f32_16x16x32_bf16 v[74:77], v[142:145], v[228:231], v[74:77]
	v_mfma_f32_16x16x32_bf16 v[70:73], v[162:165], v[224:227], v[70:73]
	v_mfma_f32_16x16x32_bf16 v[70:73], v[180:183], v[228:231], v[70:73]
	v_mfma_f32_16x16x32_bf16 v[66:69], v[184:187], v[224:227], v[66:69]
	v_mfma_f32_16x16x32_bf16 v[66:69], v[188:191], v[228:231], v[66:69]
	s_setprio 0
	s_waitcnt vmcnt(8)
	s_barrier
	ds_read_b128 v[196:199], v179 offset:16384
	ds_read_b128 v[200:203], v179 offset:17408
	ds_read_b128 v[204:207], v179 offset:18432
	ds_read_b128 v[208:211], v179 offset:19456
	ds_read_b128 v[212:215], v179 offset:20480
	ds_read_b128 v[220:223], v179 offset:21504
	ds_read_b128 v[224:227], v179 offset:22528
	ds_read_b128 v[228:231], v179 offset:23552
	s_add_u32 vcc_lo, s40, 0x100000
	s_addc_u32 vcc_hi, s41, 0
	s_add_i32 m0, s24, 0x10000
	s_nop 0
	global_load_lds_dwordx4 v148, s[40:41]
	s_add_i32 m0, s24, 0x12000
	s_nop 0
	global_load_lds_dwordx4 v152, s[40:41]
	s_add_i32 m0, s24, 0x14000
	s_nop 0
	global_load_lds_dwordx4 v148, vcc
	s_add_i32 m0, s24, 0x16000
	s_nop 0
	global_load_lds_dwordx4 v152, vcc
	s_mov_b32 m0, s24
	s_nop 0
	global_load_lds_dwordx4 v146, s[42:43]
	s_add_i32 m0, s24, 0x2000
	s_nop 0
	global_load_lds_dwordx4 v150, s[42:43]
	s_waitcnt lgkmcnt(0)
	s_setprio 1
	v_mfma_f32_16x16x32_bf16 v[62:65], v[130:133], v[196:199], v[62:65]
	v_mfma_f32_16x16x32_bf16 v[62:65], v[134:137], v[200:203], v[62:65]
	v_mfma_f32_16x16x32_bf16 v[58:61], v[138:141], v[196:199], v[58:61]
	v_mfma_f32_16x16x32_bf16 v[58:61], v[142:145], v[200:203], v[58:61]
	v_mfma_f32_16x16x32_bf16 v[54:57], v[162:165], v[196:199], v[54:57]
	v_mfma_f32_16x16x32_bf16 v[54:57], v[180:183], v[200:203], v[54:57]
	v_mfma_f32_16x16x32_bf16 v[50:53], v[184:187], v[196:199], v[50:53]
	v_mfma_f32_16x16x32_bf16 v[50:53], v[188:191], v[200:203], v[50:53]
	v_mfma_f32_16x16x32_bf16 v[46:49], v[130:133], v[204:207], v[46:49]
	v_mfma_f32_16x16x32_bf16 v[46:49], v[134:137], v[208:211], v[46:49]
	v_mfma_f32_16x16x32_bf16 v[42:45], v[138:141], v[204:207], v[42:45]
	v_mfma_f32_16x16x32_bf16 v[42:45], v[142:145], v[208:211], v[42:45]
	v_mfma_f32_16x16x32_bf16 v[38:41], v[162:165], v[204:207], v[38:41]
	v_mfma_f32_16x16x32_bf16 v[38:41], v[180:183], v[208:211], v[38:41]
	v_mfma_f32_16x16x32_bf16 v[34:37], v[184:187], v[204:207], v[34:37]
	v_mfma_f32_16x16x32_bf16 v[34:37], v[188:191], v[208:211], v[34:37]
	v_mfma_f32_16x16x32_bf16 v[30:33], v[130:133], v[212:215], v[30:33]
	v_mfma_f32_16x16x32_bf16 v[30:33], v[134:137], v[220:223], v[30:33]
	v_mfma_f32_16x16x32_bf16 v[26:29], v[138:141], v[212:215], v[26:29]
	v_mfma_f32_16x16x32_bf16 v[26:29], v[142:145], v[220:223], v[26:29]
	v_mfma_f32_16x16x32_bf16 v[22:25], v[162:165], v[212:215], v[22:25]
	v_mfma_f32_16x16x32_bf16 v[22:25], v[180:183], v[220:223], v[22:25]
	v_mfma_f32_16x16x32_bf16 v[18:21], v[184:187], v[212:215], v[18:21]
	v_mfma_f32_16x16x32_bf16 v[18:21], v[188:191], v[220:223], v[18:21]
	v_mfma_f32_16x16x32_bf16 v[14:17], v[130:133], v[224:227], v[14:17]
	v_mfma_f32_16x16x32_bf16 v[14:17], v[134:137], v[228:231], v[14:17]
	v_mfma_f32_16x16x32_bf16 v[10:13], v[138:141], v[224:227], v[10:13]
	v_mfma_f32_16x16x32_bf16 v[10:13], v[142:145], v[228:231], v[10:13]
	v_mfma_f32_16x16x32_bf16 v[6:9], v[162:165], v[224:227], v[6:9]
	v_mfma_f32_16x16x32_bf16 v[6:9], v[180:183], v[228:231], v[6:9]
	v_mfma_f32_16x16x32_bf16 v[2:5], v[184:187], v[224:227], v[2:5]
	v_mfma_f32_16x16x32_bf16 v[2:5], v[188:191], v[228:231], v[2:5]
	s_setprio 0
	s_waitcnt vmcnt(8)
	s_barrier
; #define PG8_BAR __builtin_amdgcn_s_barrier()
; template <class Epi, class Sched, bool ALIGN_EPI = false, bool SP2 = false>
; __device__ __forceinline__ void gemm_phase(PG8_LAS unsigned char* lds, const Gemm g, const Sched& S, const Epi& E) {
;     ...
;     Unit cur, nxt; int ui = 0;
;     if (!S.next(0, cur)) return;
;     f32x4 acc[2][2][4][2];
; #pragma unroll
;     for (int a = 0; a < 2; ++a)
; #pragma unroll
;         for (int b = 0; b < 2; ++b)
; #pragma unroll
;             for (int m = 0; m < 4; ++m)
; #pragma unroll
;                 for (int n = 0; n < 2; ++n) acc[a][b][m][n] = (f32x4){0.f, 0.f, 0.f, 0.f};
;     bf16x8 At[4][2], B0[2][2], B1[2][2];
;     const char* cA; const char* cB; S.bases(cur, g, tstep, cA, cB);
;     S.a_ready(cur);
;     if constexpr (SP2) {
;         PG8_STAGE(PG8_SB(0, 0), cB, voffB); PG8_STAGE(PG8_SB(0, 1), cB + hstep, voffB); PG8_STAGE(PG8_SA(0, 0), cA, voffA); PG8_STAGE(PG8_SA(0, 1), cA + hstep, voffA);
;         if (wr == 1) PG8_BAR;
;         PG8_WAIT_V(2); PG8_BAR;
;         PG8_STAGE(PG8_SB(1, 0), cB + kstep, voffB); PG8_STAGE(PG8_SA(1, 0), cA + kstep, voffA); PG8_STAGE(PG8_SB(1, 1), cB + hstep + kstep, voffB);
;         PG8_WAIT_V(6); PG8_BAR;
;     } else {
;         PG8_STAGE(PG8_SB(0, 0), cB, voffB); PG8_STAGE(PG8_SA(0, 0), cA, voffA); PG8_STAGE(PG8_SB(0, 1), cB + hstep, voffB); PG8_STAGE(PG8_SA(0, 1), cA + hstep, voffA);
;         if (wr == 1) PG8_BAR;
;         PG8_WAIT_V(4); PG8_BAR;
;         PG8_STAGE(PG8_SB(1, 0), cB + kstep, voffB); PG8_STAGE(PG8_SA(1, 0), cA + kstep, voffA); PG8_STAGE(PG8_SB(1, 1), cB + hstep + kstep, voffB);
;         PG8_WAIT_V(6); PG8_BAR;
;     }
;     for (;;) {
;         const bool has_next = S.next(ui + 1, nxt);
;         const char* nA = cA; const char* nB = cB; if (has_next) S.bases(nxt, g, tstep, nA, nB);
;         for (int t = 0; t < nt; t += 2) {
;             const bool last = (t == nt - 2);
;             const char* a1 = cA + (size_t)(t + 1) * kstep;
;             const char* a2 = last ? nA : cA + (size_t)(t + 2) * kstep; const char* b2 = last ? nB : cB + (size_t)(t + 2) * kstep;
;             const char* a3 = a2 + kstep; const char* b3 = b2 + kstep;
;             if (last && has_next) S.a_ready(nxt);
;             if constexpr (Epi::MIDK) { if (t == (nt >> 1)) { E.midk(acc, wr, fr); asm volatile("s_waitcnt lgkmcnt(0)" ::: "memory"); } }
;             if constexpr (SP2) {
	s_add_i32 s59, 0, 0x18000
	s_add_i32 s60, 0, 0x1c000
	v_add_u32_e32 v142, s59, v166
	v_add_u32_e32 v188, s60, v166
	ds_read_b128 v[130:133], v142
	ds_read_b128 v[134:137], v142 offset:1024
	ds_read_b128 v[138:141], v142 offset:2048
	ds_read_b128 v[142:145], v142 offset:3072
	ds_read_b128 v[162:165], v188
	ds_read_b128 v[180:183], v188 offset:1024
	ds_read_b128 v[184:187], v188 offset:2048
	ds_read_b128 v[188:191], v188 offset:3072
	ds_read_b128 v[196:199], v179 offset:32768
	ds_read_b128 v[200:203], v179 offset:33792
	ds_read_b128 v[204:207], v179 offset:34816
	ds_read_b128 v[208:211], v179 offset:35840
	ds_read_b128 v[212:215], v179 offset:36864
	ds_read_b128 v[220:223], v179 offset:37888
	ds_read_b128 v[224:227], v179 offset:38912
	ds_read_b128 v[228:231], v179 offset:39936
	s_add_u32 vcc_lo, s42, 0x100000
	s_addc_u32 vcc_hi, s43, 0
	s_add_i32 m0, s24, 0x4000
	s_nop 0
	global_load_lds_dwordx4 v146, vcc
	s_add_i32 m0, s24, 0x6000
	s_nop 0
	global_load_lds_dwordx4 v150, vcc
	s_waitcnt lgkmcnt(0)
	s_setprio 1
	v_mfma_f32_16x16x32_bf16 v[126:129], v[130:133], v[196:199], v[126:129]
	v_mfma_f32_16x16x32_bf16 v[126:129], v[134:137], v[200:203], v[126:129]
	v_mfma_f32_16x16x32_bf16 v[122:125], v[138:141], v[196:199], v[122:125]
	v_mfma_f32_16x16x32_bf16 v[122:125], v[142:145], v[200:203], v[122:125]
	v_mfma_f32_16x16x32_bf16 v[118:121], v[162:165], v[196:199], v[118:121]
	v_mfma_f32_16x16x32_bf16 v[118:121], v[180:183], v[200:203], v[118:121]
	v_mfma_f32_16x16x32_bf16 v[114:117], v[184:187], v[196:199], v[114:117]
	v_mfma_f32_16x16x32_bf16 v[114:117], v[188:191], v[200:203], v[114:117]
	v_mfma_f32_16x16x32_bf16 v[110:113], v[130:133], v[204:207], v[110:113]
	v_mfma_f32_16x16x32_bf16 v[110:113], v[134:137], v[208:211], v[110:113]
	v_mfma_f32_16x16x32_bf16 v[106:109], v[138:141], v[204:207], v[106:109]
	v_mfma_f32_16x16x32_bf16 v[106:109], v[142:145], v[208:211], v[106:109]
	v_mfma_f32_16x16x32_bf16 v[102:105], v[162:165], v[204:207], v[102:105]
	v_mfma_f32_16x16x32_bf16 v[102:105], v[180:183], v[208:211], v[102:105]
	v_mfma_f32_16x16x32_bf16 v[98:101], v[184:187], v[204:207], v[98:101]
	v_mfma_f32_16x16x32_bf16 v[98:101], v[188:191], v[208:211], v[98:101]
	v_mfma_f32_16x16x32_bf16 v[94:97], v[130:133], v[212:215], v[94:97]
	v_mfma_f32_16x16x32_bf16 v[94:97], v[134:137], v[220:223], v[94:97]
	v_mfma_f32_16x16x32_bf16 v[90:93], v[138:141], v[212:215], v[90:93]
	v_mfma_f32_16x16x32_bf16 v[90:93], v[142:145], v[220:223], v[90:93]
	v_mfma_f32_16x16x32_bf16 v[86:89], v[162:165], v[212:215], v[86:89]
	v_mfma_f32_16x16x32_bf16 v[86:89], v[180:183], v[220:223], v[86:89]
	v_mfma_f32_16x16x32_bf16 v[82:85], v[184:187], v[212:215], v[82:85]
	v_mfma_f32_16x16x32_bf16 v[82:85], v[188:191], v[220:223], v[82:85]
	v_mfma_f32_16x16x32_bf16 v[78:81], v[130:133], v[224:227], v[78:81]
	v_mfma_f32_16x16x32_bf16 v[78:81], v[134:137], v[228:231], v[78:81]
	v_mfma_f32_16x16x32_bf16 v[74:77], v[138:141], v[224:227], v[74:77]
	v_mfma_f32_16x16x32_bf16 v[74:77], v[142:145], v[228:231], v[74:77]
	v_mfma_f32_16x16x32_bf16 v[70:73], v[162:165], v[224:227], v[70:73]
	v_mfma_f32_16x16x32_bf16 v[70:73], v[180:183], v[228:231], v[70:73]
	v_mfma_f32_16x16x32_bf16 v[66:69], v[184:187], v[224:227], v[66:69]
	v_mfma_f32_16x16x32_bf16 v[66:69], v[188:191], v[228:231], v[66:69]
	s_setprio 0
	s_waitcnt vmcnt(8)
	s_barrier
	ds_read_b128 v[196:199], v179 offset:49152
	ds_read_b128 v[200:203], v179 offset:50176
	ds_read_b128 v[204:207], v179 offset:51200
	ds_read_b128 v[208:211], v179 offset:52224
	ds_read_b128 v[212:215], v179 offset:53248
	ds_read_b128 v[220:223], v179 offset:54272
	ds_read_b128 v[224:227], v179 offset:55296
	ds_read_b128 v[228:231], v179 offset:56320
	s_add_u32 s60, s40, 0x80
	s_addc_u32 s61, s41, 0
	s_add_u32 vcc_lo, s60, 0x100000
	s_addc_u32 vcc_hi, s61, 0
	s_add_i32 m0, s24, 0x18000
	s_nop 0
	global_load_lds_dwordx4 v148, s[60:61]
	s_add_i32 m0, s24, 0x1a000
	s_nop 0
	global_load_lds_dwordx4 v152, s[60:61]
	s_add_i32 m0, s24, 0x1c000
	s_nop 0
	global_load_lds_dwordx4 v148, vcc
	s_add_i32 m0, s24, 0x1e000
	s_nop 0
	global_load_lds_dwordx4 v152, vcc
	s_add_u32 s60, s42, 0x80
	s_addc_u32 s61, s43, 0
	s_add_i32 m0, s24, 0x8000
	s_nop 0
	global_load_lds_dwordx4 v146, s[60:61]
	s_add_i32 m0, s24, 0xa000
	s_nop 0
	global_load_lds_dwordx4 v150, s[60:61]
	s_waitcnt lgkmcnt(0)
	s_setprio 1
	v_mfma_f32_16x16x32_bf16 v[62:65], v[130:133], v[196:199], v[62:65]
	v_mfma_f32_16x16x32_bf16 v[62:65], v[134:137], v[200:203], v[62:65]
	v_mfma_f32_16x16x32_bf16 v[58:61], v[138:141], v[196:199], v[58:61]
	v_mfma_f32_16x16x32_bf16 v[58:61], v[142:145], v[200:203], v[58:61]
	v_mfma_f32_16x16x32_bf16 v[54:57], v[162:165], v[196:199], v[54:57]
	v_mfma_f32_16x16x32_bf16 v[54:57], v[180:183], v[200:203], v[54:57]
	v_mfma_f32_16x16x32_bf16 v[50:53], v[184:187], v[196:199], v[50:53]
	v_mfma_f32_16x16x32_bf16 v[50:53], v[188:191], v[200:203], v[50:53]
	v_mfma_f32_16x16x32_bf16 v[46:49], v[130:133], v[204:207], v[46:49]
	v_mfma_f32_16x16x32_bf16 v[46:49], v[134:137], v[208:211], v[46:49]
	v_mfma_f32_16x16x32_bf16 v[42:45], v[138:141], v[204:207], v[42:45]
	v_mfma_f32_16x16x32_bf16 v[42:45], v[142:145], v[208:211], v[42:45]
	v_mfma_f32_16x16x32_bf16 v[38:41], v[162:165], v[204:207], v[38:41]
	v_mfma_f32_16x16x32_bf16 v[38:41], v[180:183], v[208:211], v[38:41]
	v_mfma_f32_16x16x32_bf16 v[34:37], v[184:187], v[204:207], v[34:37]
	v_mfma_f32_16x16x32_bf16 v[34:37], v[188:191], v[208:211], v[34:37]
	v_mfma_f32_16x16x32_bf16 v[30:33], v[130:133], v[212:215], v[30:33]
	v_mfma_f32_16x16x32_bf16 v[30:33], v[134:137], v[220:223], v[30:33]
	v_mfma_f32_16x16x32_bf16 v[26:29], v[138:141], v[212:215], v[26:29]
	v_mfma_f32_16x16x32_bf16 v[26:29], v[142:145], v[220:223], v[26:29]
	v_mfma_f32_16x16x32_bf16 v[22:25], v[162:165], v[212:215], v[22:25]
	v_mfma_f32_16x16x32_bf16 v[22:25], v[180:183], v[220:223], v[22:25]
	v_mfma_f32_16x16x32_bf16 v[18:21], v[184:187], v[212:215], v[18:21]
	v_mfma_f32_16x16x32_bf16 v[18:21], v[188:191], v[220:223], v[18:21]
	v_mfma_f32_16x16x32_bf16 v[14:17], v[130:133], v[224:227], v[14:17]
	v_mfma_f32_16x16x32_bf16 v[14:17], v[134:137], v[228:231], v[14:17]
	v_mfma_f32_16x16x32_bf16 v[10:13], v[138:141], v[224:227], v[10:13]
	v_mfma_f32_16x16x32_bf16 v[10:13], v[142:145], v[228:231], v[10:13]
	v_mfma_f32_16x16x32_bf16 v[6:9], v[162:165], v[224:227], v[6:9]
	v_mfma_f32_16x16x32_bf16 v[6:9], v[180:183], v[228:231], v[6:9]
	v_mfma_f32_16x16x32_bf16 v[2:5], v[184:187], v[224:227], v[2:5]
	v_mfma_f32_16x16x32_bf16 v[2:5], v[188:191], v[228:231], v[2:5]
	s_setprio 0
	s_waitcnt vmcnt(8)
	s_barrier
	s_add_i32 s58, s58, 2
	s_add_u32 s36, s36, 0x100
	s_addc_u32 s37, s37, 0
	s_add_u32 s56, s56, 0x100
	s_addc_u32 s57, s57, 0
	s_cmp_gt_u32 s58, 61
	s_cbranch_scc0 .LBB0_1251
	s_branch .Lf1_exit
; #define PG8_BAR __builtin_amdgcn_s_barrier()
; template <class Epi, class Sched, bool ALIGN_EPI = false, bool SP2 = false>
; __device__ __forceinline__ void gemm_phase(PG8_LAS unsigned char* lds, const Gemm g, const Sched& S, const Epi& E) {
;     ...
;     Unit cur, nxt; int ui = 0;
;     if (!S.next(0, cur)) return;
;     f32x4 acc[2][2][4][2];
; #pragma unroll
;     for (int a = 0; a < 2; ++a)
; #pragma unroll
;         for (int b = 0; b < 2; ++b)
; #pragma unroll
;             for (int m = 0; m < 4; ++m)
; #pragma unroll
;                 for (int n = 0; n < 2; ++n) acc[a][b][m][n] = (f32x4){0.f, 0.f, 0.f, 0.f};
;     bf16x8 At[4][2], B0[2][2], B1[2][2];
;     const char* cA; const char* cB; S.bases(cur, g, tstep, cA, cB);
;     S.a_ready(cur);
;     if constexpr (SP2) {
;         PG8_STAGE(PG8_SB(0, 0), cB, voffB); PG8_STAGE(PG8_SB(0, 1), cB + hstep, voffB); PG8_STAGE(PG8_SA(0, 0), cA, voffA); PG8_STAGE(PG8_SA(0, 1), cA + hstep, voffA);
;         if (wr == 1) PG8_BAR;
;         PG8_WAIT_V(2); PG8_BAR;
;         PG8_STAGE(PG8_SB(1, 0), cB + kstep, voffB); PG8_STAGE(PG8_SA(1, 0), cA + kstep, voffA); PG8_STAGE(PG8_SB(1, 1), cB + hstep + kstep, voffB);
;         PG8_WAIT_V(6); PG8_BAR;
;     } else {
;         PG8_STAGE(PG8_SB(0, 0), cB, voffB); PG8_STAGE(PG8_SA(0, 0), cA, voffA); PG8_STAGE(PG8_SB(0, 1), cB + hstep, voffB); PG8_STAGE(PG8_SA(0, 1), cA + hstep, voffA);
;         if (wr == 1) PG8_BAR;
;         PG8_WAIT_V(4); PG8_BAR;
;         PG8_STAGE(PG8_SB(1, 0), cB + kstep, voffB); PG8_STAGE(PG8_SA(1, 0), cA + kstep, voffA); PG8_STAGE(PG8_SB(1, 1), cB + hstep + kstep, voffB);
;         PG8_WAIT_V(6); PG8_BAR;
;     }
;     for (;;) {
;         const bool has_next = S.next(ui + 1, nxt);
;         const char* nA = cA; const char* nB = cB; if (has_next) S.bases(nxt, g, tstep, nA, nB);
;         for (int t = 0; t < nt; t += 2) {
;             const bool last = (t == nt - 2);
;             const char* a1 = cA + (size_t)(t + 1) * kstep;
;             const char* a2 = last ? nA : cA + (size_t)(t + 2) * kstep; const char* b2 = last ? nB : cB + (size_t)(t + 2) * kstep;
;             const char* a3 = a2 + kstep; const char* b3 = b2 + kstep;
;             if (last && has_next) S.a_ready(nxt);
;             if constexpr (Epi::MIDK) { if (t == (nt >> 1)) { E.midk(acc, wr, fr); asm volatile("s_waitcnt lgkmcnt(0)" ::: "memory"); } }
;             if constexpr (SP2) {
.Lf1_h1:
	ds_read_b128 v[130:133], v177
	ds_read_b128 v[134:137], v177 offset:1024
	ds_read_b128 v[138:141], v177 offset:2048
	ds_read_b128 v[142:145], v177 offset:3072
	ds_read_b128 v[162:165], v178
	ds_read_b128 v[180:183], v178 offset:1024
	ds_read_b128 v[184:187], v178 offset:2048
	ds_read_b128 v[188:191], v178 offset:3072
	s_add_u32 s40, s36, 0xfff00080
	s_addc_u32 s41, s37, -1
	s_cmp_eq_u32 s58, 60
	s_cselect_b32 s43, s15, s41
	s_cselect_b32 s42, s17, s40
	s_cselect_b32 s41, s54, s57
	s_cselect_b32 s40, s55, s56
	ds_read_b128 v[196:199], v179
	ds_read_b128 v[200:203], v179 offset:1024
	ds_read_b128 v[204:207], v179 offset:2048
	ds_read_b128 v[208:211], v179 offset:3072
	ds_read_b128 v[212:215], v179 offset:4096
	ds_read_b128 v[220:223], v179 offset:5120
	ds_read_b128 v[224:227], v179 offset:6144
	ds_read_b128 v[228:231], v179 offset:7168
	s_add_i32 m0, s24, 0xc000
	s_nop 0
	global_load_lds_dwordx4 v146, s[36:37]
	s_add_i32 m0, s24, 0xe000
	s_nop 0
	global_load_lds_dwordx4 v150, s[36:37]
	s_sleep 2
	s_waitcnt lgkmcnt(0)
	s_waitcnt vmcnt(8)
	s_barrier
	s_setprio 2
	v_mfma_f32_16x16x32_bf16 v[126:129], v[130:133], v[196:199], v[126:129]
	v_mfma_f32_16x16x32_bf16 v[126:129], v[134:137], v[200:203], v[126:129]
	v_mfma_f32_16x16x32_bf16 v[122:125], v[138:141], v[196:199], v[122:125]
	v_mfma_f32_16x16x32_bf16 v[122:125], v[142:145], v[200:203], v[122:125]
	v_mfma_f32_16x16x32_bf16 v[118:121], v[162:165], v[196:199], v[118:121]
	v_mfma_f32_16x16x32_bf16 v[118:121], v[180:183], v[200:203], v[118:121]
	v_mfma_f32_16x16x32_bf16 v[114:117], v[184:187], v[196:199], v[114:117]
	v_mfma_f32_16x16x32_bf16 v[114:117], v[188:191], v[200:203], v[114:117]
	v_mfma_f32_16x16x32_bf16 v[110:113], v[130:133], v[204:207], v[110:113]
	v_mfma_f32_16x16x32_bf16 v[110:113], v[134:137], v[208:211], v[110:113]
	v_mfma_f32_16x16x32_bf16 v[106:109], v[138:141], v[204:207], v[106:109]
	v_mfma_f32_16x16x32_bf16 v[106:109], v[142:145], v[208:211], v[106:109]
	v_mfma_f32_16x16x32_bf16 v[102:105], v[162:165], v[204:207], v[102:105]
	v_mfma_f32_16x16x32_bf16 v[102:105], v[180:183], v[208:211], v[102:105]
	v_mfma_f32_16x16x32_bf16 v[98:101], v[184:187], v[204:207], v[98:101]
	v_mfma_f32_16x16x32_bf16 v[98:101], v[188:191], v[208:211], v[98:101]
	v_mfma_f32_16x16x32_bf16 v[94:97], v[130:133], v[212:215], v[94:97]
	v_mfma_f32_16x16x32_bf16 v[94:97], v[134:137], v[220:223], v[94:97]
	v_mfma_f32_16x16x32_bf16 v[90:93], v[138:141], v[212:215], v[90:93]
	v_mfma_f32_16x16x32_bf16 v[90:93], v[142:145], v[220:223], v[90:93]
	v_mfma_f32_16x16x32_bf16 v[86:89], v[162:165], v[212:215], v[86:89]
	v_mfma_f32_16x16x32_bf16 v[86:89], v[180:183], v[220:223], v[86:89]
	v_mfma_f32_16x16x32_bf16 v[82:85], v[184:187], v[212:215], v[82:85]
	v_mfma_f32_16x16x32_bf16 v[82:85], v[188:191], v[220:223], v[82:85]
	v_mfma_f32_16x16x32_bf16 v[78:81], v[130:133], v[224:227], v[78:81]
	v_mfma_f32_16x16x32_bf16 v[78:81], v[134:137], v[228:231], v[78:81]
	v_mfma_f32_16x16x32_bf16 v[74:77], v[138:141], v[224:227], v[74:77]
	v_mfma_f32_16x16x32_bf16 v[74:77], v[142:145], v[228:231], v[74:77]
	v_mfma_f32_16x16x32_bf16 v[70:73], v[162:165], v[224:227], v[70:73]
	v_mfma_f32_16x16x32_bf16 v[70:73], v[180:183], v[228:231], v[70:73]
	v_mfma_f32_16x16x32_bf16 v[66:69], v[184:187], v[224:227], v[66:69]
	v_mfma_f32_16x16x32_bf16 v[66:69], v[188:191], v[228:231], v[66:69]
	s_setprio 0
	ds_read_b128 v[196:199], v179 offset:16384
	ds_read_b128 v[200:203], v179 offset:17408
	ds_read_b128 v[204:207], v179 offset:18432
	ds_read_b128 v[208:211], v179 offset:19456
	ds_read_b128 v[212:215], v179 offset:20480
	ds_read_b128 v[220:223], v179 offset:21504
	ds_read_b128 v[224:227], v179 offset:22528
	ds_read_b128 v[228:231], v179 offset:23552
	s_add_u32 vcc_lo, s40, 0x100000
	s_addc_u32 vcc_hi, s41, 0
	s_add_i32 m0, s24, 0x10000
	s_nop 0
	global_load_lds_dwordx4 v148, s[40:41]
	s_add_i32 m0, s24, 0x12000
	s_nop 0
	global_load_lds_dwordx4 v152, s[40:41]
	s_add_i32 m0, s24, 0x14000
	s_nop 0
	global_load_lds_dwordx4 v148, vcc
	s_add_i32 m0, s24, 0x16000
	s_nop 0
	global_load_lds_dwordx4 v152, vcc
	s_mov_b32 m0, s24
	s_nop 0
	global_load_lds_dwordx4 v146, s[42:43]
	s_add_i32 m0, s24, 0x2000
	s_nop 0
	global_load_lds_dwordx4 v150, s[42:43]
	s_sleep 2
	s_waitcnt lgkmcnt(0)
	s_waitcnt vmcnt(8)
	s_barrier
; #define PG8_BAR __builtin_amdgcn_s_barrier()
; template <class Epi, class Sched, bool ALIGN_EPI = false, bool SP2 = false>
; __device__ __forceinline__ void gemm_phase(PG8_LAS unsigned char* lds, const Gemm g, const Sched& S, const Epi& E) {
;     ...
;     Unit cur, nxt; int ui = 0;
;     if (!S.next(0, cur)) return;
;     f32x4 acc[2][2][4][2];
; #pragma unroll
;     for (int a = 0; a < 2; ++a)
; #pragma unroll
;         for (int b = 0; b < 2; ++b)
; #pragma unroll
;             for (int m = 0; m < 4; ++m)
; #pragma unroll
;                 for (int n = 0; n < 2; ++n) acc[a][b][m][n] = (f32x4){0.f, 0.f, 0.f, 0.f};
;     bf16x8 At[4][2], B0[2][2], B1[2][2];
;     const char* cA; const char* cB; S.bases(cur, g, tstep, cA, cB);
;     S.a_ready(cur);
;     if constexpr (SP2) {
;         PG8_STAGE(PG8_SB(0, 0), cB, voffB); PG8_STAGE(PG8_SB(0, 1), cB + hstep, voffB); PG8_STAGE(PG8_SA(0, 0), cA, voffA); PG8_STAGE(PG8_SA(0, 1), cA + hstep, voffA);
;         if (wr == 1) PG8_BAR;
;         PG8_WAIT_V(2); PG8_BAR;
;         PG8_STAGE(PG8_SB(1, 0), cB + kstep, voffB); PG8_STAGE(PG8_SA(1, 0), cA + kstep, voffA); PG8_STAGE(PG8_SB(1, 1), cB + hstep + kstep, voffB);
;         PG8_WAIT_V(6); PG8_BAR;
;     } else {
;         PG8_STAGE(PG8_SB(0, 0), cB, voffB); PG8_STAGE(PG8_SA(0, 0), cA, voffA); PG8_STAGE(PG8_SB(0, 1), cB + hstep, voffB); PG8_STAGE(PG8_SA(0, 1), cA + hstep, voffA);
;         if (wr == 1) PG8_BAR;
;         PG8_WAIT_V(4); PG8_BAR;
;         PG8_STAGE(PG8_SB(1, 0), cB + kstep, voffB); PG8_STAGE(PG8_SA(1, 0), cA + kstep, voffA); PG8_STAGE(PG8_SB(1, 1), cB + hstep + kstep, voffB);
;         PG8_WAIT_V(6); PG8_BAR;
;     }
;     for (;;) {
;         const bool has_next = S.next(ui + 1, nxt);
;         const char* nA = cA; const char* nB = cB; if (has_next) S.bases(nxt, g, tstep, nA, nB);
;         for (int t = 0; t < nt; t += 2) {
;             const bool last = (t == nt - 2);
;             const char* a1 = cA + (size_t)(t + 1) * kstep;
;             const char* a2 = last ? nA : cA + (size_t)(t + 2) * kstep; const char* b2 = last ? nB : cB + (size_t)(t + 2) * kstep;
;             const char* a3 = a2 + kstep; const char* b3 = b2 + kstep;
;             if (last && has_next) S.a_ready(nxt);
;             if constexpr (Epi::MIDK) { if (t == (nt >> 1)) { E.midk(acc, wr, fr); asm volatile("s_waitcnt lgkmcnt(0)" ::: "memory"); } }
;             if constexpr (SP2) {
	s_setprio 2
	v_mfma_f32_16x16x32_bf16 v[62:65], v[130:133], v[196:199], v[62:65]
	v_mfma_f32_16x16x32_bf16 v[62:65], v[134:137], v[200:203], v[62:65]
	v_mfma_f32_16x16x32_bf16 v[58:61], v[138:141], v[196:199], v[58:61]
	v_mfma_f32_16x16x32_bf16 v[58:61], v[142:145], v[200:203], v[58:61]
	v_mfma_f32_16x16x32_bf16 v[54:57], v[162:165], v[196:199], v[54:57]
	v_mfma_f32_16x16x32_bf16 v[54:57], v[180:183], v[200:203], v[54:57]
	v_mfma_f32_16x16x32_bf16 v[50:53], v[184:187], v[196:199], v[50:53]
	v_mfma_f32_16x16x32_bf16 v[50:53], v[188:191], v[200:203], v[50:53]
	v_mfma_f32_16x16x32_bf16 v[46:49], v[130:133], v[204:207], v[46:49]
	v_mfma_f32_16x16x32_bf16 v[46:49], v[134:137], v[208:211], v[46:49]
	v_mfma_f32_16x16x32_bf16 v[42:45], v[138:141], v[204:207], v[42:45]
	v_mfma_f32_16x16x32_bf16 v[42:45], v[142:145], v[208:211], v[42:45]
	v_mfma_f32_16x16x32_bf16 v[38:41], v[162:165], v[204:207], v[38:41]
	v_mfma_f32_16x16x32_bf16 v[38:41], v[180:183], v[208:211], v[38:41]
	v_mfma_f32_16x16x32_bf16 v[34:37], v[184:187], v[204:207], v[34:37]
	v_mfma_f32_16x16x32_bf16 v[34:37], v[188:191], v[208:211], v[34:37]
	v_mfma_f32_16x16x32_bf16 v[30:33], v[130:133], v[212:215], v[30:33]
	v_mfma_f32_16x16x32_bf16 v[30:33], v[134:137], v[220:223], v[30:33]
	v_mfma_f32_16x16x32_bf16 v[26:29], v[138:141], v[212:215], v[26:29]
	v_mfma_f32_16x16x32_bf16 v[26:29], v[142:145], v[220:223], v[26:29]
	v_mfma_f32_16x16x32_bf16 v[22:25], v[162:165], v[212:215], v[22:25]
	v_mfma_f32_16x16x32_bf16 v[22:25], v[180:183], v[220:223], v[22:25]
	v_mfma_f32_16x16x32_bf16 v[18:21], v[184:187], v[212:215], v[18:21]
	v_mfma_f32_16x16x32_bf16 v[18:21], v[188:191], v[220:223], v[18:21]
	v_mfma_f32_16x16x32_bf16 v[14:17], v[130:133], v[224:227], v[14:17]
	v_mfma_f32_16x16x32_bf16 v[14:17], v[134:137], v[228:231], v[14:17]
	v_mfma_f32_16x16x32_bf16 v[10:13], v[138:141], v[224:227], v[10:13]
	v_mfma_f32_16x16x32_bf16 v[10:13], v[142:145], v[228:231], v[10:13]
	v_mfma_f32_16x16x32_bf16 v[6:9], v[162:165], v[224:227], v[6:9]
	v_mfma_f32_16x16x32_bf16 v[6:9], v[180:183], v[228:231], v[6:9]
	v_mfma_f32_16x16x32_bf16 v[2:5], v[184:187], v[224:227], v[2:5]
	v_mfma_f32_16x16x32_bf16 v[2:5], v[188:191], v[228:231], v[2:5]
	s_setprio 0
	s_add_i32 s59, 0, 0x18000
	s_add_i32 s60, 0, 0x1c000
	v_add_u32_e32 v142, s59, v166
	v_add_u32_e32 v188, s60, v166
	ds_read_b128 v[130:133], v142
	ds_read_b128 v[134:137], v142 offset:1024
	ds_read_b128 v[138:141], v142 offset:2048
	ds_read_b128 v[142:145], v142 offset:3072
	ds_read_b128 v[162:165], v188
	ds_read_b128 v[180:183], v188 offset:1024
	ds_read_b128 v[184:187], v188 offset:2048
	ds_read_b128 v[188:191], v188 offset:3072
	ds_read_b128 v[196:199], v179 offset:32768
	ds_read_b128 v[200:203], v179 offset:33792
	ds_read_b128 v[204:207], v179 offset:34816
	ds_read_b128 v[208:211], v179 offset:35840
	ds_read_b128 v[212:215], v179 offset:36864
	ds_read_b128 v[220:223], v179 offset:37888
	ds_read_b128 v[224:227], v179 offset:38912
	ds_read_b128 v[228:231], v179 offset:39936
	s_add_u32 vcc_lo, s42, 0x100000
	s_addc_u32 vcc_hi, s43, 0
	s_add_i32 m0, s24, 0x4000
	s_nop 0
	global_load_lds_dwordx4 v146, vcc
	s_add_i32 m0, s24, 0x6000
	s_nop 0
	global_load_lds_dwordx4 v150, vcc
	s_sleep 2
	s_waitcnt lgkmcnt(0)
	s_waitcnt vmcnt(8)
	s_barrier
; #define PG8_BAR __builtin_amdgcn_s_barrier()
; template <class Epi, class Sched, bool ALIGN_EPI = false, bool SP2 = false>
; __device__ __forceinline__ void gemm_phase(PG8_LAS unsigned char* lds, const Gemm g, const Sched& S, const Epi& E) {
;     ...
;     Unit cur, nxt; int ui = 0;
;     if (!S.next(0, cur)) return;
;     f32x4 acc[2][2][4][2];
; #pragma unroll
;     for (int a = 0; a < 2; ++a)
; #pragma unroll
;         for (int b = 0; b < 2; ++b)
; #pragma unroll
;             for (int m = 0; m < 4; ++m)
; #pragma unroll
;                 for (int n = 0; n < 2; ++n) acc[a][b][m][n] = (f32x4){0.f, 0.f, 0.f, 0.f};
;     bf16x8 At[4][2], B0[2][2], B1[2][2];
;     const char* cA; const char* cB; S.bases(cur, g, tstep, cA, cB);
;     S.a_ready(cur);
;     if constexpr (SP2) {
;         PG8_STAGE(PG8_SB(0, 0), cB, voffB); PG8_STAGE(PG8_SB(0, 1), cB + hstep, voffB); PG8_STAGE(PG8_SA(0, 0), cA, voffA); PG8_STAGE(PG8_SA(0, 1), cA + hstep, voffA);
;         if (wr == 1) PG8_BAR;
;         PG8_WAIT_V(2); PG8_BAR;
;         PG8_STAGE(PG8_SB(1, 0), cB + kstep, voffB); PG8_STAGE(PG8_SA(1, 0), cA + kstep, voffA); PG8_STAGE(PG8_SB(1, 1), cB + hstep + kstep, voffB);
;         PG8_WAIT_V(6); PG8_BAR;
;     } else {
;         PG8_STAGE(PG8_SB(0, 0), cB, voffB); PG8_STAGE(PG8_SA(0, 0), cA, voffA); PG8_STAGE(PG8_SB(0, 1), cB + hstep, voffB); PG8_STAGE(PG8_SA(0, 1), cA + hstep, voffA);
;         if (wr == 1) PG8_BAR;
;         PG8_WAIT_V(4); PG8_BAR;
;         PG8_STAGE(PG8_SB(1, 0), cB + kstep, voffB); PG8_STAGE(PG8_SA(1, 0), cA + kstep, voffA); PG8_STAGE(PG8_SB(1, 1), cB + hstep + kstep, voffB);
;         PG8_WAIT_V(6); PG8_BAR;
;     }
;     for (;;) {
;         const bool has_next = S.next(ui + 1, nxt);
;         const char* nA = cA; const char* nB = cB; if (has_next) S.bases(nxt, g, tstep, nA, nB);
;         for (int t = 0; t < nt; t += 2) {
;             const bool last = (t == nt - 2);
;             const char* a1 = cA + (size_t)(t + 1) * kstep;
;             const char* a2 = last ? nA : cA + (size_t)(t + 2) * kstep; const char* b2 = last ? nB : cB + (size_t)(t + 2) * kstep;
;             const char* a3 = a2 + kstep; const char* b3 = b2 + kstep;
;             if (last && has_next) S.a_ready(nxt);
;             if constexpr (Epi::MIDK) { if (t == (nt >> 1)) { E.midk(acc, wr, fr); asm volatile("s_waitcnt lgkmcnt(0)" ::: "memory"); } }
;             if constexpr (SP2) {
	s_setprio 2
	v_mfma_f32_16x16x32_bf16 v[126:129], v[130:133], v[196:199], v[126:129]
	v_mfma_f32_16x16x32_bf16 v[126:129], v[134:137], v[200:203], v[126:129]
	v_mfma_f32_16x16x32_bf16 v[122:125], v[138:141], v[196:199], v[122:125]
	v_mfma_f32_16x16x32_bf16 v[122:125], v[142:145], v[200:203], v[122:125]
	v_mfma_f32_16x16x32_bf16 v[118:121], v[162:165], v[196:199], v[118:121]
	v_mfma_f32_16x16x32_bf16 v[118:121], v[180:183], v[200:203], v[118:121]
	v_mfma_f32_16x16x32_bf16 v[114:117], v[184:187], v[196:199], v[114:117]
	v_mfma_f32_16x16x32_bf16 v[114:117], v[188:191], v[200:203], v[114:117]
	v_mfma_f32_16x16x32_bf16 v[110:113], v[130:133], v[204:207], v[110:113]
	v_mfma_f32_16x16x32_bf16 v[110:113], v[134:137], v[208:211], v[110:113]
	v_mfma_f32_16x16x32_bf16 v[106:109], v[138:141], v[204:207], v[106:109]
	v_mfma_f32_16x16x32_bf16 v[106:109], v[142:145], v[208:211], v[106:109]
	v_mfma_f32_16x16x32_bf16 v[102:105], v[162:165], v[204:207], v[102:105]
	v_mfma_f32_16x16x32_bf16 v[102:105], v[180:183], v[208:211], v[102:105]
	v_mfma_f32_16x16x32_bf16 v[98:101], v[184:187], v[204:207], v[98:101]
	v_mfma_f32_16x16x32_bf16 v[98:101], v[188:191], v[208:211], v[98:101]
	v_mfma_f32_16x16x32_bf16 v[94:97], v[130:133], v[212:215], v[94:97]
	v_mfma_f32_16x16x32_bf16 v[94:97], v[134:137], v[220:223], v[94:97]
	v_mfma_f32_16x16x32_bf16 v[90:93], v[138:141], v[212:215], v[90:93]
	v_mfma_f32_16x16x32_bf16 v[90:93], v[142:145], v[220:223], v[90:93]
	v_mfma_f32_16x16x32_bf16 v[86:89], v[162:165], v[212:215], v[86:89]
	v_mfma_f32_16x16x32_bf16 v[86:89], v[180:183], v[220:223], v[86:89]
	v_mfma_f32_16x16x32_bf16 v[82:85], v[184:187], v[212:215], v[82:85]
	v_mfma_f32_16x16x32_bf16 v[82:85], v[188:191], v[220:223], v[82:85]
	v_mfma_f32_16x16x32_bf16 v[78:81], v[130:133], v[224:227], v[78:81]
	v_mfma_f32_16x16x32_bf16 v[78:81], v[134:137], v[228:231], v[78:81]
	v_mfma_f32_16x16x32_bf16 v[74:77], v[138:141], v[224:227], v[74:77]
	v_mfma_f32_16x16x32_bf16 v[74:77], v[142:145], v[228:231], v[74:77]
	v_mfma_f32_16x16x32_bf16 v[70:73], v[162:165], v[224:227], v[70:73]
	v_mfma_f32_16x16x32_bf16 v[70:73], v[180:183], v[228:231], v[70:73]
	v_mfma_f32_16x16x32_bf16 v[66:69], v[184:187], v[224:227], v[66:69]
	v_mfma_f32_16x16x32_bf16 v[66:69], v[188:191], v[228:231], v[66:69]
	s_setprio 0
	ds_read_b128 v[196:199], v179 offset:49152
	ds_read_b128 v[200:203], v179 offset:50176
	ds_read_b128 v[204:207], v179 offset:51200
	ds_read_b128 v[208:211], v179 offset:52224
	ds_read_b128 v[212:215], v179 offset:53248
	ds_read_b128 v[220:223], v179 offset:54272
	ds_read_b128 v[224:227], v179 offset:55296
	ds_read_b128 v[228:231], v179 offset:56320
	s_add_u32 s60, s40, 0x80
	s_addc_u32 s61, s41, 0
	s_add_u32 vcc_lo, s60, 0x100000
	s_addc_u32 vcc_hi, s61, 0
	s_add_i32 m0, s24, 0x18000
	s_nop 0
	global_load_lds_dwordx4 v148, s[60:61]
	s_add_i32 m0, s24, 0x1a000
	s_nop 0
	global_load_lds_dwordx4 v152, s[60:61]
	s_add_i32 m0, s24, 0x1c000
	s_nop 0
	global_load_lds_dwordx4 v148, vcc
	s_add_i32 m0, s24, 0x1e000
	s_nop 0
	global_load_lds_dwordx4 v152, vcc
	s_add_u32 s60, s42, 0x80
	s_addc_u32 s61, s43, 0
	s_add_i32 m0, s24, 0x8000
	s_nop 0
	global_load_lds_dwordx4 v146, s[60:61]
	s_add_i32 m0, s24, 0xa000
	s_nop 0
	global_load_lds_dwordx4 v150, s[60:61]
	s_sleep 2
	s_waitcnt lgkmcnt(0)
	s_waitcnt vmcnt(8)
	s_barrier
	s_setprio 2
	v_mfma_f32_16x16x32_bf16 v[62:65], v[130:133], v[196:199], v[62:65]
	v_mfma_f32_16x16x32_bf16 v[62:65], v[134:137], v[200:203], v[62:65]
	v_mfma_f32_16x16x32_bf16 v[58:61], v[138:141], v[196:199], v[58:61]
	v_mfma_f32_16x16x32_bf16 v[58:61], v[142:145], v[200:203], v[58:61]
	v_mfma_f32_16x16x32_bf16 v[54:57], v[162:165], v[196:199], v[54:57]
	v_mfma_f32_16x16x32_bf16 v[54:57], v[180:183], v[200:203], v[54:57]
	v_mfma_f32_16x16x32_bf16 v[50:53], v[184:187], v[196:199], v[50:53]
	v_mfma_f32_16x16x32_bf16 v[50:53], v[188:191], v[200:203], v[50:53]
	v_mfma_f32_16x16x32_bf16 v[46:49], v[130:133], v[204:207], v[46:49]
	v_mfma_f32_16x16x32_bf16 v[46:49], v[134:137], v[208:211], v[46:49]
	v_mfma_f32_16x16x32_bf16 v[42:45], v[138:141], v[204:207], v[42:45]
	v_mfma_f32_16x16x32_bf16 v[42:45], v[142:145], v[208:211], v[42:45]
	v_mfma_f32_16x16x32_bf16 v[38:41], v[162:165], v[204:207], v[38:41]
	v_mfma_f32_16x16x32_bf16 v[38:41], v[180:183], v[208:211], v[38:41]
	v_mfma_f32_16x16x32_bf16 v[34:37], v[184:187], v[204:207], v[34:37]
	v_mfma_f32_16x16x32_bf16 v[34:37], v[188:191], v[208:211], v[34:37]
	v_mfma_f32_16x16x32_bf16 v[30:33], v[130:133], v[212:215], v[30:33]
	v_mfma_f32_16x16x32_bf16 v[30:33], v[134:137], v[220:223], v[30:33]
	v_mfma_f32_16x16x32_bf16 v[26:29], v[138:141], v[212:215], v[26:29]
	v_mfma_f32_16x16x32_bf16 v[26:29], v[142:145], v[220:223], v[26:29]
	v_mfma_f32_16x16x32_bf16 v[22:25], v[162:165], v[212:215], v[22:25]
	v_mfma_f32_16x16x32_bf16 v[22:25], v[180:183], v[220:223], v[22:25]
	v_mfma_f32_16x16x32_bf16 v[18:21], v[184:187], v[212:215], v[18:21]
	v_mfma_f32_16x16x32_bf16 v[18:21], v[188:191], v[220:223], v[18:21]
	v_mfma_f32_16x16x32_bf16 v[14:17], v[130:133], v[224:227], v[14:17]
	v_mfma_f32_16x16x32_bf16 v[14:17], v[134:137], v[228:231], v[14:17]
	v_mfma_f32_16x16x32_bf16 v[10:13], v[138:141], v[224:227], v[10:13]
	v_mfma_f32_16x16x32_bf16 v[10:13], v[142:145], v[228:231], v[10:13]
	v_mfma_f32_16x16x32_bf16 v[6:9], v[162:165], v[224:227], v[6:9]
	v_mfma_f32_16x16x32_bf16 v[6:9], v[180:183], v[228:231], v[6:9]
	v_mfma_f32_16x16x32_bf16 v[2:5], v[184:187], v[224:227], v[2:5]
	v_mfma_f32_16x16x32_bf16 v[2:5], v[188:191], v[228:231], v[2:5]
	s_setprio 0
	s_add_i32 s58, s58, 2
	s_add_u32 s36, s36, 0x100
	s_addc_u32 s37, s37, 0
	s_add_u32 s56, s56, 0x100
	s_addc_u32 s57, s57, 0
	s_cmp_gt_u32 s58, 61
	s_cbranch_scc0 .Lf1_h1

; #define PG8_BAR __builtin_amdgcn_s_barrier()
; template <class Epi, class Sched, bool ALIGN_EPI = false, bool SP2 = false>
; __device__ __forceinline__ void gemm_phase(PG8_LAS unsigned char* lds, const Gemm g, const Sched& S, const Epi& E) {
;     ...
;     Unit cur, nxt; int ui = 0;
;     if (!S.next(0, cur)) return;
;     f32x4 acc[2][2][4][2];
; #pragma unroll
;     for (int a = 0; a < 2; ++a)
; #pragma unroll
;         for (int b = 0; b < 2; ++b)
; #pragma unroll
;             for (int m = 0; m < 4; ++m)
; #pragma unroll
;                 for (int n = 0; n < 2; ++n) acc[a][b][m][n] = (f32x4){0.f, 0.f, 0.f, 0.f};
;     bf16x8 At[4][2], B0[2][2], B1[2][2];
;     const char* cA; const char* cB; S.bases(cur, g, tstep, cA, cB);
;     S.a_ready(cur);
;     if constexpr (SP2) {
;         PG8_STAGE(PG8_SB(0, 0), cB, voffB); PG8_STAGE(PG8_SB(0, 1), cB + hstep, voffB); PG8_STAGE(PG8_SA(0, 0), cA, voffA); PG8_STAGE(PG8_SA(0, 1), cA + hstep, voffA);
;         if (wr == 1) PG8_BAR;
;         PG8_WAIT_V(2); PG8_BAR;
;         PG8_STAGE(PG8_SB(1, 0), cB + kstep, voffB); PG8_STAGE(PG8_SA(1, 0), cA + kstep, voffA); PG8_STAGE(PG8_SB(1, 1), cB + hstep + kstep, voffB);
;         PG8_WAIT_V(6); PG8_BAR;
;     } else {
;         PG8_STAGE(PG8_SB(0, 0), cB, voffB); PG8_STAGE(PG8_SA(0, 0), cA, voffA); PG8_STAGE(PG8_SB(0, 1), cB + hstep, voffB); PG8_STAGE(PG8_SA(0, 1), cA + hstep, voffA);
;         if (wr == 1) PG8_BAR;
;         PG8_WAIT_V(4); PG8_BAR;
;         PG8_STAGE(PG8_SB(1, 0), cB + kstep, voffB); PG8_STAGE(PG8_SA(1, 0), cA + kstep, voffA); PG8_STAGE(PG8_SB(1, 1), cB + hstep + kstep, voffB);
;         PG8_WAIT_V(6); PG8_BAR;
;     }
;     for (;;) {
;         const bool has_next = S.next(ui + 1, nxt);
;         const char* nA = cA; const char* nB = cB; if (has_next) S.bases(nxt, g, tstep, nA, nB);
;         for (int t = 0; t < nt; t += 2) {
;             const bool last = (t == nt - 2);
;             const char* a1 = cA + (size_t)(t + 1) * kstep;
;             const char* a2 = last ? nA : cA + (size_t)(t + 2) * kstep; const char* b2 = last ? nB : cB + (size_t)(t + 2) * kstep;
;             const char* a3 = a2 + kstep; const char* b3 = b2 + kstep;
;             if (last && has_next) S.a_ready(nxt);
;             if constexpr (Epi::MIDK) { if (t == (nt >> 1)) { E.midk(acc, wr, fr); asm volatile("s_waitcnt lgkmcnt(0)" ::: "memory"); } }
;             if constexpr (SP2) {
.LBB0_1321:
	ds_read_b128 v[128:131], v156
	ds_read_b128 v[132:135], v156 offset:1024
	ds_read_b128 v[150:153], v156 offset:2048
	ds_read_b128 v[162:165], v156 offset:3072
	ds_read_b128 v[166:169], v157
	ds_read_b128 v[170:173], v157 offset:1024
	ds_read_b128 v[174:177], v157 offset:2048
	ds_read_b128 v[178:181], v157 offset:3072
	s_add_u32 s20, s18, 0xffbfc080
	s_addc_u32 s21, s19, -1
	s_cmpk_eq_i32 s59, 0xfc
	s_cselect_b32 s23, s7, s21
	s_cselect_b32 s22, s6, s20
	s_cselect_b32 s21, s17, s58
	s_cselect_b32 s20, s16, s57
	ds_read_b128 v[182:185], v158
	ds_read_b128 v[186:189], v158 offset:1024
	ds_read_b128 v[190:193], v158 offset:2048
	ds_read_b128 v[194:197], v158 offset:3072
	ds_read_b128 v[198:201], v158 offset:4096
	ds_read_b128 v[202:205], v158 offset:5120
	ds_read_b128 v[206:209], v158 offset:6144
	ds_read_b128 v[210:213], v158 offset:7168
	s_add_i32 m0, s24, 0xc000
	s_nop 0
	global_load_lds_dwordx4 v136, s[18:19]
	s_add_i32 m0, s24, 0xe000
	s_nop 0
	global_load_lds_dwordx4 v140, s[18:19]
	s_waitcnt lgkmcnt(0)
	s_setprio 1
	v_mfma_f32_16x16x32_bf16 v[124:127], v[128:131], v[182:185], v[124:127]
	v_mfma_f32_16x16x32_bf16 v[124:127], v[132:135], v[186:189], v[124:127]
	v_mfma_f32_16x16x32_bf16 v[120:123], v[150:153], v[182:185], v[120:123]
	v_mfma_f32_16x16x32_bf16 v[120:123], v[162:165], v[186:189], v[120:123]
	v_mfma_f32_16x16x32_bf16 v[68:71], v[166:169], v[182:185], v[68:71]
	v_mfma_f32_16x16x32_bf16 v[68:71], v[170:173], v[186:189], v[68:71]
	v_mfma_f32_16x16x32_bf16 v[64:67], v[174:177], v[182:185], v[64:67]
	v_mfma_f32_16x16x32_bf16 v[64:67], v[178:181], v[186:189], v[64:67]
	v_mfma_f32_16x16x32_bf16 v[116:119], v[128:131], v[190:193], v[116:119]
	v_mfma_f32_16x16x32_bf16 v[116:119], v[132:135], v[194:197], v[116:119]
	v_mfma_f32_16x16x32_bf16 v[112:115], v[150:153], v[190:193], v[112:115]
	v_mfma_f32_16x16x32_bf16 v[112:115], v[162:165], v[194:197], v[112:115]
	v_mfma_f32_16x16x32_bf16 v[52:55], v[166:169], v[190:193], v[52:55]
	v_mfma_f32_16x16x32_bf16 v[52:55], v[170:173], v[194:197], v[52:55]
	v_mfma_f32_16x16x32_bf16 v[48:51], v[174:177], v[190:193], v[48:51]
	v_mfma_f32_16x16x32_bf16 v[48:51], v[178:181], v[194:197], v[48:51]
	v_mfma_f32_16x16x32_bf16 v[108:111], v[128:131], v[198:201], v[108:111]
	v_mfma_f32_16x16x32_bf16 v[108:111], v[132:135], v[202:205], v[108:111]
	v_mfma_f32_16x16x32_bf16 v[104:107], v[150:153], v[198:201], v[104:107]
	v_mfma_f32_16x16x32_bf16 v[104:107], v[162:165], v[202:205], v[104:107]
	v_mfma_f32_16x16x32_bf16 v[44:47], v[166:169], v[198:201], v[44:47]
	v_mfma_f32_16x16x32_bf16 v[44:47], v[170:173], v[202:205], v[44:47]
	v_mfma_f32_16x16x32_bf16 v[40:43], v[174:177], v[198:201], v[40:43]
	v_mfma_f32_16x16x32_bf16 v[40:43], v[178:181], v[202:205], v[40:43]
	v_mfma_f32_16x16x32_bf16 v[100:103], v[128:131], v[206:209], v[100:103]
	v_mfma_f32_16x16x32_bf16 v[100:103], v[132:135], v[210:213], v[100:103]
	v_mfma_f32_16x16x32_bf16 v[96:99], v[150:153], v[206:209], v[96:99]
	v_mfma_f32_16x16x32_bf16 v[96:99], v[162:165], v[210:213], v[96:99]
	v_mfma_f32_16x16x32_bf16 v[36:39], v[166:169], v[206:209], v[36:39]
	v_mfma_f32_16x16x32_bf16 v[36:39], v[170:173], v[210:213], v[36:39]
	v_mfma_f32_16x16x32_bf16 v[32:35], v[174:177], v[206:209], v[32:35]
	v_mfma_f32_16x16x32_bf16 v[32:35], v[178:181], v[210:213], v[32:35]
	s_setprio 0
	s_waitcnt vmcnt(8)
	s_barrier
	ds_read_b128 v[182:185], v158 offset:16384
	ds_read_b128 v[186:189], v158 offset:17408
	ds_read_b128 v[190:193], v158 offset:18432
	ds_read_b128 v[194:197], v158 offset:19456
	ds_read_b128 v[198:201], v158 offset:20480
	ds_read_b128 v[202:205], v158 offset:21504
	ds_read_b128 v[206:209], v158 offset:22528
	ds_read_b128 v[210:213], v158 offset:23552
	s_add_u32 vcc_lo, s20, 0x404000
	s_addc_u32 vcc_hi, s21, 0
	s_add_i32 m0, s24, 0x10000
	s_nop 0
	global_load_lds_dwordx4 v138, s[20:21]
	s_add_i32 m0, s24, 0x12000
	s_nop 0
	global_load_lds_dwordx4 v142, s[20:21]
	s_add_i32 m0, s24, 0x14000
	s_nop 0
	global_load_lds_dwordx4 v138, vcc
	s_add_i32 m0, s24, 0x16000
	s_nop 0
	global_load_lds_dwordx4 v142, vcc
	s_mov_b32 m0, s24
	s_nop 0
	global_load_lds_dwordx4 v136, s[22:23]
	s_add_i32 m0, s24, 0x2000
	s_nop 0
	global_load_lds_dwordx4 v140, s[22:23]
	s_waitcnt lgkmcnt(0)
	s_setprio 1
	v_mfma_f32_16x16x32_bf16 v[92:95], v[128:131], v[182:185], v[92:95]
	v_mfma_f32_16x16x32_bf16 v[92:95], v[132:135], v[186:189], v[92:95]
	v_mfma_f32_16x16x32_bf16 v[88:91], v[150:153], v[182:185], v[88:91]
	v_mfma_f32_16x16x32_bf16 v[88:91], v[162:165], v[186:189], v[88:91]
	v_mfma_f32_16x16x32_bf16 v[28:31], v[166:169], v[182:185], v[28:31]
	v_mfma_f32_16x16x32_bf16 v[28:31], v[170:173], v[186:189], v[28:31]
	v_mfma_f32_16x16x32_bf16 v[24:27], v[174:177], v[182:185], v[24:27]
	v_mfma_f32_16x16x32_bf16 v[24:27], v[178:181], v[186:189], v[24:27]
	v_mfma_f32_16x16x32_bf16 v[84:87], v[128:131], v[190:193], v[84:87]
	v_mfma_f32_16x16x32_bf16 v[84:87], v[132:135], v[194:197], v[84:87]
	v_mfma_f32_16x16x32_bf16 v[80:83], v[150:153], v[190:193], v[80:83]
	v_mfma_f32_16x16x32_bf16 v[80:83], v[162:165], v[194:197], v[80:83]
	v_mfma_f32_16x16x32_bf16 v[20:23], v[166:169], v[190:193], v[20:23]
	v_mfma_f32_16x16x32_bf16 v[20:23], v[170:173], v[194:197], v[20:23]
	v_mfma_f32_16x16x32_bf16 v[16:19], v[174:177], v[190:193], v[16:19]
	v_mfma_f32_16x16x32_bf16 v[16:19], v[178:181], v[194:197], v[16:19]
	v_mfma_f32_16x16x32_bf16 v[76:79], v[128:131], v[198:201], v[76:79]
	v_mfma_f32_16x16x32_bf16 v[76:79], v[132:135], v[202:205], v[76:79]
	v_mfma_f32_16x16x32_bf16 v[72:75], v[150:153], v[198:201], v[72:75]
	v_mfma_f32_16x16x32_bf16 v[72:75], v[162:165], v[202:205], v[72:75]
	v_mfma_f32_16x16x32_bf16 v[12:15], v[166:169], v[198:201], v[12:15]
	v_mfma_f32_16x16x32_bf16 v[12:15], v[170:173], v[202:205], v[12:15]
	v_mfma_f32_16x16x32_bf16 v[8:11], v[174:177], v[198:201], v[8:11]
	v_mfma_f32_16x16x32_bf16 v[8:11], v[178:181], v[202:205], v[8:11]
	v_mfma_f32_16x16x32_bf16 v[60:63], v[128:131], v[206:209], v[60:63]
	v_mfma_f32_16x16x32_bf16 v[60:63], v[132:135], v[210:213], v[60:63]
	v_mfma_f32_16x16x32_bf16 v[56:59], v[150:153], v[206:209], v[56:59]
	v_mfma_f32_16x16x32_bf16 v[56:59], v[162:165], v[210:213], v[56:59]
	v_mfma_f32_16x16x32_bf16 v[4:7], v[166:169], v[206:209], v[4:7]
	v_mfma_f32_16x16x32_bf16 v[4:7], v[170:173], v[210:213], v[4:7]
	v_mfma_f32_16x16x32_bf16 v[0:3], v[174:177], v[206:209], v[0:3]
	v_mfma_f32_16x16x32_bf16 v[0:3], v[178:181], v[210:213], v[0:3]
	s_setprio 0
	s_waitcnt vmcnt(8)
	s_barrier
; #define PG8_BAR __builtin_amdgcn_s_barrier()
; template <class Epi, class Sched, bool ALIGN_EPI = false, bool SP2 = false>
; __device__ __forceinline__ void gemm_phase(PG8_LAS unsigned char* lds, const Gemm g, const Sched& S, const Epi& E) {
;     ...
;     Unit cur, nxt; int ui = 0;
;     if (!S.next(0, cur)) return;
;     f32x4 acc[2][2][4][2];
; #pragma unroll
;     for (int a = 0; a < 2; ++a)
; #pragma unroll
;         for (int b = 0; b < 2; ++b)
; #pragma unroll
;             for (int m = 0; m < 4; ++m)
; #pragma unroll
;                 for (int n = 0; n < 2; ++n) acc[a][b][m][n] = (f32x4){0.f, 0.f, 0.f, 0.f};
;     bf16x8 At[4][2], B0[2][2], B1[2][2];
;     const char* cA; const char* cB; S.bases(cur, g, tstep, cA, cB);
;     S.a_ready(cur);
;     if constexpr (SP2) {
;         PG8_STAGE(PG8_SB(0, 0), cB, voffB); PG8_STAGE(PG8_SB(0, 1), cB + hstep, voffB); PG8_STAGE(PG8_SA(0, 0), cA, voffA); PG8_STAGE(PG8_SA(0, 1), cA + hstep, voffA);
;         if (wr == 1) PG8_BAR;
;         PG8_WAIT_V(2); PG8_BAR;
;         PG8_STAGE(PG8_SB(1, 0), cB + kstep, voffB); PG8_STAGE(PG8_SA(1, 0), cA + kstep, voffA); PG8_STAGE(PG8_SB(1, 1), cB + hstep + kstep, voffB);
;         PG8_WAIT_V(6); PG8_BAR;
;     } else {
;         PG8_STAGE(PG8_SB(0, 0), cB, voffB); PG8_STAGE(PG8_SA(0, 0), cA, voffA); PG8_STAGE(PG8_SB(0, 1), cB + hstep, voffB); PG8_STAGE(PG8_SA(0, 1), cA + hstep, voffA);
;         if (wr == 1) PG8_BAR;
;         PG8_WAIT_V(4); PG8_BAR;
;         PG8_STAGE(PG8_SB(1, 0), cB + kstep, voffB); PG8_STAGE(PG8_SA(1, 0), cA + kstep, voffA); PG8_STAGE(PG8_SB(1, 1), cB + hstep + kstep, voffB);
;         PG8_WAIT_V(6); PG8_BAR;
;     }
;     for (;;) {
;         const bool has_next = S.next(ui + 1, nxt);
;         const char* nA = cA; const char* nB = cB; if (has_next) S.bases(nxt, g, tstep, nA, nB);
;         for (int t = 0; t < nt; t += 2) {
;             const bool last = (t == nt - 2);
;             const char* a1 = cA + (size_t)(t + 1) * kstep;
;             const char* a2 = last ? nA : cA + (size_t)(t + 2) * kstep; const char* b2 = last ? nB : cB + (size_t)(t + 2) * kstep;
;             const char* a3 = a2 + kstep; const char* b3 = b2 + kstep;
;             if (last && has_next) S.a_ready(nxt);
;             if constexpr (Epi::MIDK) { if (t == (nt >> 1)) { E.midk(acc, wr, fr); asm volatile("s_waitcnt lgkmcnt(0)" ::: "memory"); } }
;             if constexpr (SP2) {
	ds_read_b128 v[128:131], v159
	ds_read_b128 v[132:135], v159 offset:1024
	ds_read_b128 v[150:153], v159 offset:2048
	ds_read_b128 v[162:165], v159 offset:3072
	ds_read_b128 v[166:169], v160
	ds_read_b128 v[170:173], v160 offset:1024
	ds_read_b128 v[174:177], v160 offset:2048
	ds_read_b128 v[178:181], v160 offset:3072
	ds_read_b128 v[182:185], v158 offset:32768
	ds_read_b128 v[186:189], v158 offset:33792
	ds_read_b128 v[190:193], v158 offset:34816
	ds_read_b128 v[194:197], v158 offset:35840
	ds_read_b128 v[198:201], v158 offset:36864
	ds_read_b128 v[202:205], v158 offset:37888
	ds_read_b128 v[206:209], v158 offset:38912
	ds_read_b128 v[210:213], v158 offset:39936
	s_add_u32 vcc_lo, s22, 0x404000
	s_addc_u32 vcc_hi, s23, 0
	s_add_i32 m0, s24, 0x4000
	s_nop 0
	global_load_lds_dwordx4 v136, vcc
	s_add_i32 m0, s24, 0x6000
	s_nop 0
	global_load_lds_dwordx4 v140, vcc
	s_waitcnt lgkmcnt(0)
	s_setprio 1
	v_mfma_f32_16x16x32_bf16 v[124:127], v[128:131], v[182:185], v[124:127]
	v_mfma_f32_16x16x32_bf16 v[124:127], v[132:135], v[186:189], v[124:127]
	v_mfma_f32_16x16x32_bf16 v[120:123], v[150:153], v[182:185], v[120:123]
	v_mfma_f32_16x16x32_bf16 v[120:123], v[162:165], v[186:189], v[120:123]
	v_mfma_f32_16x16x32_bf16 v[68:71], v[166:169], v[182:185], v[68:71]
	v_mfma_f32_16x16x32_bf16 v[68:71], v[170:173], v[186:189], v[68:71]
	v_mfma_f32_16x16x32_bf16 v[64:67], v[174:177], v[182:185], v[64:67]
	v_mfma_f32_16x16x32_bf16 v[64:67], v[178:181], v[186:189], v[64:67]
	v_mfma_f32_16x16x32_bf16 v[116:119], v[128:131], v[190:193], v[116:119]
	v_mfma_f32_16x16x32_bf16 v[116:119], v[132:135], v[194:197], v[116:119]
	v_mfma_f32_16x16x32_bf16 v[112:115], v[150:153], v[190:193], v[112:115]
	v_mfma_f32_16x16x32_bf16 v[112:115], v[162:165], v[194:197], v[112:115]
	v_mfma_f32_16x16x32_bf16 v[52:55], v[166:169], v[190:193], v[52:55]
	v_mfma_f32_16x16x32_bf16 v[52:55], v[170:173], v[194:197], v[52:55]
	v_mfma_f32_16x16x32_bf16 v[48:51], v[174:177], v[190:193], v[48:51]
	v_mfma_f32_16x16x32_bf16 v[48:51], v[178:181], v[194:197], v[48:51]
	v_mfma_f32_16x16x32_bf16 v[108:111], v[128:131], v[198:201], v[108:111]
	v_mfma_f32_16x16x32_bf16 v[108:111], v[132:135], v[202:205], v[108:111]
	v_mfma_f32_16x16x32_bf16 v[104:107], v[150:153], v[198:201], v[104:107]
	v_mfma_f32_16x16x32_bf16 v[104:107], v[162:165], v[202:205], v[104:107]
	v_mfma_f32_16x16x32_bf16 v[44:47], v[166:169], v[198:201], v[44:47]
	v_mfma_f32_16x16x32_bf16 v[44:47], v[170:173], v[202:205], v[44:47]
	v_mfma_f32_16x16x32_bf16 v[40:43], v[174:177], v[198:201], v[40:43]
	v_mfma_f32_16x16x32_bf16 v[40:43], v[178:181], v[202:205], v[40:43]
	v_mfma_f32_16x16x32_bf16 v[100:103], v[128:131], v[206:209], v[100:103]
	v_mfma_f32_16x16x32_bf16 v[100:103], v[132:135], v[210:213], v[100:103]
	v_mfma_f32_16x16x32_bf16 v[96:99], v[150:153], v[206:209], v[96:99]
	v_mfma_f32_16x16x32_bf16 v[96:99], v[162:165], v[210:213], v[96:99]
	v_mfma_f32_16x16x32_bf16 v[36:39], v[166:169], v[206:209], v[36:39]
	v_mfma_f32_16x16x32_bf16 v[36:39], v[170:173], v[210:213], v[36:39]
	v_mfma_f32_16x16x32_bf16 v[32:35], v[174:177], v[206:209], v[32:35]
	v_mfma_f32_16x16x32_bf16 v[32:35], v[178:181], v[210:213], v[32:35]
	s_setprio 0
	s_waitcnt vmcnt(8)
	s_barrier
	ds_read_b128 v[182:185], v158 offset:49152
	ds_read_b128 v[186:189], v158 offset:50176
	ds_read_b128 v[190:193], v158 offset:51200
	ds_read_b128 v[194:197], v158 offset:52224
	ds_read_b128 v[198:201], v158 offset:53248
	ds_read_b128 v[202:205], v158 offset:54272
	ds_read_b128 v[206:209], v158 offset:55296
	ds_read_b128 v[210:213], v158 offset:56320
	s_add_u32 s60, s20, 0x80
	s_addc_u32 s61, s21, 0
	s_add_u32 vcc_lo, s60, 0x404000
	s_addc_u32 vcc_hi, s61, 0
	s_add_i32 m0, s24, 0x18000
	s_nop 0
	global_load_lds_dwordx4 v138, s[60:61]
	s_add_i32 m0, s24, 0x1a000
	s_nop 0
	global_load_lds_dwordx4 v142, s[60:61]
	s_add_i32 m0, s24, 0x1c000
	s_nop 0
	global_load_lds_dwordx4 v138, vcc
	s_add_i32 m0, s24, 0x1e000
	s_nop 0
	global_load_lds_dwordx4 v142, vcc
	s_add_u32 s60, s22, 0x80
	s_addc_u32 s61, s23, 0
	s_add_i32 m0, s24, 0x8000
	s_nop 0
	global_load_lds_dwordx4 v136, s[60:61]
	s_add_i32 m0, s24, 0xa000
	s_nop 0
	global_load_lds_dwordx4 v140, s[60:61]
	s_waitcnt lgkmcnt(0)
	s_setprio 1
	v_mfma_f32_16x16x32_bf16 v[92:95], v[128:131], v[182:185], v[92:95]
	v_mfma_f32_16x16x32_bf16 v[92:95], v[132:135], v[186:189], v[92:95]
	v_mfma_f32_16x16x32_bf16 v[88:91], v[150:153], v[182:185], v[88:91]
	v_mfma_f32_16x16x32_bf16 v[88:91], v[162:165], v[186:189], v[88:91]
	v_mfma_f32_16x16x32_bf16 v[28:31], v[166:169], v[182:185], v[28:31]
	v_mfma_f32_16x16x32_bf16 v[28:31], v[170:173], v[186:189], v[28:31]
	v_mfma_f32_16x16x32_bf16 v[24:27], v[174:177], v[182:185], v[24:27]
	v_mfma_f32_16x16x32_bf16 v[24:27], v[178:181], v[186:189], v[24:27]
	v_mfma_f32_16x16x32_bf16 v[84:87], v[128:131], v[190:193], v[84:87]
	v_mfma_f32_16x16x32_bf16 v[84:87], v[132:135], v[194:197], v[84:87]
	v_mfma_f32_16x16x32_bf16 v[80:83], v[150:153], v[190:193], v[80:83]
	v_mfma_f32_16x16x32_bf16 v[80:83], v[162:165], v[194:197], v[80:83]
	v_mfma_f32_16x16x32_bf16 v[20:23], v[166:169], v[190:193], v[20:23]
	v_mfma_f32_16x16x32_bf16 v[20:23], v[170:173], v[194:197], v[20:23]
	v_mfma_f32_16x16x32_bf16 v[16:19], v[174:177], v[190:193], v[16:19]
	v_mfma_f32_16x16x32_bf16 v[16:19], v[178:181], v[194:197], v[16:19]
	v_mfma_f32_16x16x32_bf16 v[76:79], v[128:131], v[198:201], v[76:79]
	v_mfma_f32_16x16x32_bf16 v[76:79], v[132:135], v[202:205], v[76:79]
	v_mfma_f32_16x16x32_bf16 v[72:75], v[150:153], v[198:201], v[72:75]
	v_mfma_f32_16x16x32_bf16 v[72:75], v[162:165], v[202:205], v[72:75]
	v_mfma_f32_16x16x32_bf16 v[12:15], v[166:169], v[198:201], v[12:15]
	v_mfma_f32_16x16x32_bf16 v[12:15], v[170:173], v[202:205], v[12:15]
	v_mfma_f32_16x16x32_bf16 v[8:11], v[174:177], v[198:201], v[8:11]
	v_mfma_f32_16x16x32_bf16 v[8:11], v[178:181], v[202:205], v[8:11]
	v_mfma_f32_16x16x32_bf16 v[60:63], v[128:131], v[206:209], v[60:63]
	v_mfma_f32_16x16x32_bf16 v[60:63], v[132:135], v[210:213], v[60:63]
	v_mfma_f32_16x16x32_bf16 v[56:59], v[150:153], v[206:209], v[56:59]
	v_mfma_f32_16x16x32_bf16 v[56:59], v[162:165], v[210:213], v[56:59]
	v_mfma_f32_16x16x32_bf16 v[4:7], v[166:169], v[206:209], v[4:7]
	v_mfma_f32_16x16x32_bf16 v[4:7], v[170:173], v[210:213], v[4:7]
	v_mfma_f32_16x16x32_bf16 v[0:3], v[174:177], v[206:209], v[0:3]
	v_mfma_f32_16x16x32_bf16 v[0:3], v[178:181], v[210:213], v[0:3]
	s_setprio 0
	s_waitcnt vmcnt(8)
	s_barrier
	s_add_i32 s59, s59, 2
	s_add_u32 s18, s18, 0x100
	s_addc_u32 s19, s19, 0
	s_add_u32 s57, s57, 0x100
	s_addc_u32 s58, s58, 0
	s_cmpk_gt_u32 s59, 0xfd
	s_cbranch_scc0 .LBB0_1321
	s_branch .Lf2_exit
; #define PG8_BAR __builtin_amdgcn_s_barrier()
; template <class Epi, class Sched, bool ALIGN_EPI = false, bool SP2 = false>
; __device__ __forceinline__ void gemm_phase(PG8_LAS unsigned char* lds, const Gemm g, const Sched& S, const Epi& E) {
;     ...
;     Unit cur, nxt; int ui = 0;
;     if (!S.next(0, cur)) return;
;     f32x4 acc[2][2][4][2];
; #pragma unroll
;     for (int a = 0; a < 2; ++a)
; #pragma unroll
;         for (int b = 0; b < 2; ++b)
; #pragma unroll
;             for (int m = 0; m < 4; ++m)
; #pragma unroll
;                 for (int n = 0; n < 2; ++n) acc[a][b][m][n] = (f32x4){0.f, 0.f, 0.f, 0.f};
;     bf16x8 At[4][2], B0[2][2], B1[2][2];
;     const char* cA; const char* cB; S.bases(cur, g, tstep, cA, cB);
;     S.a_ready(cur);
;     if constexpr (SP2) {
;         PG8_STAGE(PG8_SB(0, 0), cB, voffB); PG8_STAGE(PG8_SB(0, 1), cB + hstep, voffB); PG8_STAGE(PG8_SA(0, 0), cA, voffA); PG8_STAGE(PG8_SA(0, 1), cA + hstep, voffA);
;         if (wr == 1) PG8_BAR;
;         PG8_WAIT_V(2); PG8_BAR;
;         PG8_STAGE(PG8_SB(1, 0), cB + kstep, voffB); PG8_STAGE(PG8_SA(1, 0), cA + kstep, voffA); PG8_STAGE(PG8_SB(1, 1), cB + hstep + kstep, voffB);
;         PG8_WAIT_V(6); PG8_BAR;
;     } else {
;         PG8_STAGE(PG8_SB(0, 0), cB, voffB); PG8_STAGE(PG8_SA(0, 0), cA, voffA); PG8_STAGE(PG8_SB(0, 1), cB + hstep, voffB); PG8_STAGE(PG8_SA(0, 1), cA + hstep, voffA);
;         if (wr == 1) PG8_BAR;
;         PG8_WAIT_V(4); PG8_BAR;
;         PG8_STAGE(PG8_SB(1, 0), cB + kstep, voffB); PG8_STAGE(PG8_SA(1, 0), cA + kstep, voffA); PG8_STAGE(PG8_SB(1, 1), cB + hstep + kstep, voffB);
;         PG8_WAIT_V(6); PG8_BAR;
;     }
;     for (;;) {
;         const bool has_next = S.next(ui + 1, nxt);
;         const char* nA = cA; const char* nB = cB; if (has_next) S.bases(nxt, g, tstep, nA, nB);
;         for (int t = 0; t < nt; t += 2) {
;             const bool last = (t == nt - 2);
;             const char* a1 = cA + (size_t)(t + 1) * kstep;
;             const char* a2 = last ? nA : cA + (size_t)(t + 2) * kstep; const char* b2 = last ? nB : cB + (size_t)(t + 2) * kstep;
;             const char* a3 = a2 + kstep; const char* b3 = b2 + kstep;
;             if (last && has_next) S.a_ready(nxt);
;             if constexpr (Epi::MIDK) { if (t == (nt >> 1)) { E.midk(acc, wr, fr); asm volatile("s_waitcnt lgkmcnt(0)" ::: "memory"); } }
;             if constexpr (SP2) {
.Lf2_h1:
	ds_read_b128 v[128:131], v156
	ds_read_b128 v[132:135], v156 offset:1024
	ds_read_b128 v[150:153], v156 offset:2048
	ds_read_b128 v[162:165], v156 offset:3072
	ds_read_b128 v[166:169], v157
	ds_read_b128 v[170:173], v157 offset:1024
	ds_read_b128 v[174:177], v157 offset:2048
	ds_read_b128 v[178:181], v157 offset:3072
	s_add_u32 s20, s18, 0xffbfc080
	s_addc_u32 s21, s19, -1
	s_cmpk_eq_i32 s59, 0xfc
	s_cselect_b32 s23, s7, s21
	s_cselect_b32 s22, s6, s20
	s_cselect_b32 s21, s17, s58
	s_cselect_b32 s20, s16, s57
	ds_read_b128 v[182:185], v158
	ds_read_b128 v[186:189], v158 offset:1024
	ds_read_b128 v[190:193], v158 offset:2048
	ds_read_b128 v[194:197], v158 offset:3072
	ds_read_b128 v[198:201], v158 offset:4096
	ds_read_b128 v[202:205], v158 offset:5120
	ds_read_b128 v[206:209], v158 offset:6144
	ds_read_b128 v[210:213], v158 offset:7168
	s_add_i32 m0, s24, 0xc000
	s_nop 0
	global_load_lds_dwordx4 v136, s[18:19]
	s_add_i32 m0, s24, 0xe000
	s_nop 0
	global_load_lds_dwordx4 v140, s[18:19]
	s_sleep 2
	s_waitcnt lgkmcnt(0)
	s_waitcnt vmcnt(8)
	s_barrier
	s_setprio 2
	v_mfma_f32_16x16x32_bf16 v[124:127], v[128:131], v[182:185], v[124:127]
	v_mfma_f32_16x16x32_bf16 v[124:127], v[132:135], v[186:189], v[124:127]
	v_mfma_f32_16x16x32_bf16 v[120:123], v[150:153], v[182:185], v[120:123]
	v_mfma_f32_16x16x32_bf16 v[120:123], v[162:165], v[186:189], v[120:123]
	v_mfma_f32_16x16x32_bf16 v[68:71], v[166:169], v[182:185], v[68:71]
	v_mfma_f32_16x16x32_bf16 v[68:71], v[170:173], v[186:189], v[68:71]
	v_mfma_f32_16x16x32_bf16 v[64:67], v[174:177], v[182:185], v[64:67]
	v_mfma_f32_16x16x32_bf16 v[64:67], v[178:181], v[186:189], v[64:67]
	v_mfma_f32_16x16x32_bf16 v[116:119], v[128:131], v[190:193], v[116:119]
	v_mfma_f32_16x16x32_bf16 v[116:119], v[132:135], v[194:197], v[116:119]
	v_mfma_f32_16x16x32_bf16 v[112:115], v[150:153], v[190:193], v[112:115]
	v_mfma_f32_16x16x32_bf16 v[112:115], v[162:165], v[194:197], v[112:115]
	v_mfma_f32_16x16x32_bf16 v[52:55], v[166:169], v[190:193], v[52:55]
	v_mfma_f32_16x16x32_bf16 v[52:55], v[170:173], v[194:197], v[52:55]
	v_mfma_f32_16x16x32_bf16 v[48:51], v[174:177], v[190:193], v[48:51]
	v_mfma_f32_16x16x32_bf16 v[48:51], v[178:181], v[194:197], v[48:51]
	v_mfma_f32_16x16x32_bf16 v[108:111], v[128:131], v[198:201], v[108:111]
	v_mfma_f32_16x16x32_bf16 v[108:111], v[132:135], v[202:205], v[108:111]
	v_mfma_f32_16x16x32_bf16 v[104:107], v[150:153], v[198:201], v[104:107]
	v_mfma_f32_16x16x32_bf16 v[104:107], v[162:165], v[202:205], v[104:107]
	v_mfma_f32_16x16x32_bf16 v[44:47], v[166:169], v[198:201], v[44:47]
	v_mfma_f32_16x16x32_bf16 v[44:47], v[170:173], v[202:205], v[44:47]
	v_mfma_f32_16x16x32_bf16 v[40:43], v[174:177], v[198:201], v[40:43]
	v_mfma_f32_16x16x32_bf16 v[40:43], v[178:181], v[202:205], v[40:43]
	v_mfma_f32_16x16x32_bf16 v[100:103], v[128:131], v[206:209], v[100:103]
	v_mfma_f32_16x16x32_bf16 v[100:103], v[132:135], v[210:213], v[100:103]
	v_mfma_f32_16x16x32_bf16 v[96:99], v[150:153], v[206:209], v[96:99]
	v_mfma_f32_16x16x32_bf16 v[96:99], v[162:165], v[210:213], v[96:99]
	v_mfma_f32_16x16x32_bf16 v[36:39], v[166:169], v[206:209], v[36:39]
	v_mfma_f32_16x16x32_bf16 v[36:39], v[170:173], v[210:213], v[36:39]
	v_mfma_f32_16x16x32_bf16 v[32:35], v[174:177], v[206:209], v[32:35]
	v_mfma_f32_16x16x32_bf16 v[32:35], v[178:181], v[210:213], v[32:35]
	s_setprio 0
	ds_read_b128 v[182:185], v158 offset:16384
	ds_read_b128 v[186:189], v158 offset:17408
	ds_read_b128 v[190:193], v158 offset:18432
	ds_read_b128 v[194:197], v158 offset:19456
	ds_read_b128 v[198:201], v158 offset:20480
	ds_read_b128 v[202:205], v158 offset:21504
	ds_read_b128 v[206:209], v158 offset:22528
	ds_read_b128 v[210:213], v158 offset:23552
	s_add_u32 vcc_lo, s20, 0x404000
	s_addc_u32 vcc_hi, s21, 0
	s_add_i32 m0, s24, 0x10000
	s_nop 0
	global_load_lds_dwordx4 v138, s[20:21]
	s_add_i32 m0, s24, 0x12000
	s_nop 0
	global_load_lds_dwordx4 v142, s[20:21]
	s_add_i32 m0, s24, 0x14000
	s_nop 0
	global_load_lds_dwordx4 v138, vcc
	s_add_i32 m0, s24, 0x16000
	s_nop 0
	global_load_lds_dwordx4 v142, vcc
	s_mov_b32 m0, s24
	s_nop 0
	global_load_lds_dwordx4 v136, s[22:23]
	s_add_i32 m0, s24, 0x2000
	s_nop 0
	global_load_lds_dwordx4 v140, s[22:23]
	s_sleep 2
	s_waitcnt lgkmcnt(0)
	s_waitcnt vmcnt(8)
	s_barrier
; #define PG8_BAR __builtin_amdgcn_s_barrier()
; template <class Epi, class Sched, bool ALIGN_EPI = false, bool SP2 = false>
; __device__ __forceinline__ void gemm_phase(PG8_LAS unsigned char* lds, const Gemm g, const Sched& S, const Epi& E) {
;     ...
;     Unit cur, nxt; int ui = 0;
;     if (!S.next(0, cur)) return;
;     f32x4 acc[2][2][4][2];
; #pragma unroll
;     for (int a = 0; a < 2; ++a)
; #pragma unroll
;         for (int b = 0; b < 2; ++b)
; #pragma unroll
;             for (int m = 0; m < 4; ++m)
; #pragma unroll
;                 for (int n = 0; n < 2; ++n) acc[a][b][m][n] = (f32x4){0.f, 0.f, 0.f, 0.f};
;     bf16x8 At[4][2], B0[2][2], B1[2][2];
;     const char* cA; const char* cB; S.bases(cur, g, tstep, cA, cB);
;     S.a_ready(cur);
;     if constexpr (SP2) {
;         PG8_STAGE(PG8_SB(0, 0), cB, voffB); PG8_STAGE(PG8_SB(0, 1), cB + hstep, voffB); PG8_STAGE(PG8_SA(0, 0), cA, voffA); PG8_STAGE(PG8_SA(0, 1), cA + hstep, voffA);
;         if (wr == 1) PG8_BAR;
;         PG8_WAIT_V(2); PG8_BAR;
;         PG8_STAGE(PG8_SB(1, 0), cB + kstep, voffB); PG8_STAGE(PG8_SA(1, 0), cA + kstep, voffA); PG8_STAGE(PG8_SB(1, 1), cB + hstep + kstep, voffB);
;         PG8_WAIT_V(6); PG8_BAR;
;     } else {
;         PG8_STAGE(PG8_SB(0, 0), cB, voffB); PG8_STAGE(PG8_SA(0, 0), cA, voffA); PG8_STAGE(PG8_SB(0, 1), cB + hstep, voffB); PG8_STAGE(PG8_SA(0, 1), cA + hstep, voffA);
;         if (wr == 1) PG8_BAR;
;         PG8_WAIT_V(4); PG8_BAR;
;         PG8_STAGE(PG8_SB(1, 0), cB + kstep, voffB); PG8_STAGE(PG8_SA(1, 0), cA + kstep, voffA); PG8_STAGE(PG8_SB(1, 1), cB + hstep + kstep, voffB);
;         PG8_WAIT_V(6); PG8_BAR;
;     }
;     for (;;) {
;         const bool has_next = S.next(ui + 1, nxt);
;         const char* nA = cA; const char* nB = cB; if (has_next) S.bases(nxt, g, tstep, nA, nB);
;         for (int t = 0; t < nt; t += 2) {
;             const bool last = (t == nt - 2);
;             const char* a1 = cA + (size_t)(t + 1) * kstep;
;             const char* a2 = last ? nA : cA + (size_t)(t + 2) * kstep; const char* b2 = last ? nB : cB + (size_t)(t + 2) * kstep;
;             const char* a3 = a2 + kstep; const char* b3 = b2 + kstep;
;             if (last && has_next) S.a_ready(nxt);
;             if constexpr (Epi::MIDK) { if (t == (nt >> 1)) { E.midk(acc, wr, fr); asm volatile("s_waitcnt lgkmcnt(0)" ::: "memory"); } }
;             if constexpr (SP2) {
	s_setprio 2
	v_mfma_f32_16x16x32_bf16 v[92:95], v[128:131], v[182:185], v[92:95]
	v_mfma_f32_16x16x32_bf16 v[92:95], v[132:135], v[186:189], v[92:95]
	v_mfma_f32_16x16x32_bf16 v[88:91], v[150:153], v[182:185], v[88:91]
	v_mfma_f32_16x16x32_bf16 v[88:91], v[162:165], v[186:189], v[88:91]
	v_mfma_f32_16x16x32_bf16 v[28:31], v[166:169], v[182:185], v[28:31]
	v_mfma_f32_16x16x32_bf16 v[28:31], v[170:173], v[186:189], v[28:31]
	v_mfma_f32_16x16x32_bf16 v[24:27], v[174:177], v[182:185], v[24:27]
	v_mfma_f32_16x16x32_bf16 v[24:27], v[178:181], v[186:189], v[24:27]
	v_mfma_f32_16x16x32_bf16 v[84:87], v[128:131], v[190:193], v[84:87]
	v_mfma_f32_16x16x32_bf16 v[84:87], v[132:135], v[194:197], v[84:87]
	v_mfma_f32_16x16x32_bf16 v[80:83], v[150:153], v[190:193], v[80:83]
	v_mfma_f32_16x16x32_bf16 v[80:83], v[162:165], v[194:197], v[80:83]
	v_mfma_f32_16x16x32_bf16 v[20:23], v[166:169], v[190:193], v[20:23]
	v_mfma_f32_16x16x32_bf16 v[20:23], v[170:173], v[194:197], v[20:23]
	v_mfma_f32_16x16x32_bf16 v[16:19], v[174:177], v[190:193], v[16:19]
	v_mfma_f32_16x16x32_bf16 v[16:19], v[178:181], v[194:197], v[16:19]
	v_mfma_f32_16x16x32_bf16 v[76:79], v[128:131], v[198:201], v[76:79]
	v_mfma_f32_16x16x32_bf16 v[76:79], v[132:135], v[202:205], v[76:79]
	v_mfma_f32_16x16x32_bf16 v[72:75], v[150:153], v[198:201], v[72:75]
	v_mfma_f32_16x16x32_bf16 v[72:75], v[162:165], v[202:205], v[72:75]
	v_mfma_f32_16x16x32_bf16 v[12:15], v[166:169], v[198:201], v[12:15]
	v_mfma_f32_16x16x32_bf16 v[12:15], v[170:173], v[202:205], v[12:15]
	v_mfma_f32_16x16x32_bf16 v[8:11], v[174:177], v[198:201], v[8:11]
	v_mfma_f32_16x16x32_bf16 v[8:11], v[178:181], v[202:205], v[8:11]
	v_mfma_f32_16x16x32_bf16 v[60:63], v[128:131], v[206:209], v[60:63]
	v_mfma_f32_16x16x32_bf16 v[60:63], v[132:135], v[210:213], v[60:63]
	v_mfma_f32_16x16x32_bf16 v[56:59], v[150:153], v[206:209], v[56:59]
	v_mfma_f32_16x16x32_bf16 v[56:59], v[162:165], v[210:213], v[56:59]
	v_mfma_f32_16x16x32_bf16 v[4:7], v[166:169], v[206:209], v[4:7]
	v_mfma_f32_16x16x32_bf16 v[4:7], v[170:173], v[210:213], v[4:7]
	v_mfma_f32_16x16x32_bf16 v[0:3], v[174:177], v[206:209], v[0:3]
	v_mfma_f32_16x16x32_bf16 v[0:3], v[178:181], v[210:213], v[0:3]
	s_setprio 0
	ds_read_b128 v[128:131], v159
	ds_read_b128 v[132:135], v159 offset:1024
	ds_read_b128 v[150:153], v159 offset:2048
	ds_read_b128 v[162:165], v159 offset:3072
	ds_read_b128 v[166:169], v160
	ds_read_b128 v[170:173], v160 offset:1024
	ds_read_b128 v[174:177], v160 offset:2048
	ds_read_b128 v[178:181], v160 offset:3072
	ds_read_b128 v[182:185], v158 offset:32768
	ds_read_b128 v[186:189], v158 offset:33792
	ds_read_b128 v[190:193], v158 offset:34816
	ds_read_b128 v[194:197], v158 offset:35840
	ds_read_b128 v[198:201], v158 offset:36864
	ds_read_b128 v[202:205], v158 offset:37888
	ds_read_b128 v[206:209], v158 offset:38912
	ds_read_b128 v[210:213], v158 offset:39936
	s_add_u32 vcc_lo, s22, 0x404000
	s_addc_u32 vcc_hi, s23, 0
	s_add_i32 m0, s24, 0x4000
	s_nop 0
	global_load_lds_dwordx4 v136, vcc
	s_add_i32 m0, s24, 0x6000
	s_nop 0
	global_load_lds_dwordx4 v140, vcc
	s_sleep 2
	s_waitcnt lgkmcnt(0)
	s_waitcnt vmcnt(8)
	s_barrier
; #define PG8_BAR __builtin_amdgcn_s_barrier()
; template <class Epi, class Sched, bool ALIGN_EPI = false, bool SP2 = false>
; __device__ __forceinline__ void gemm_phase(PG8_LAS unsigned char* lds, const Gemm g, const Sched& S, const Epi& E) {
;     ...
;     Unit cur, nxt; int ui = 0;
;     if (!S.next(0, cur)) return;
;     f32x4 acc[2][2][4][2];
; #pragma unroll
;     for (int a = 0; a < 2; ++a)
; #pragma unroll
;         for (int b = 0; b < 2; ++b)
; #pragma unroll
;             for (int m = 0; m < 4; ++m)
; #pragma unroll
;                 for (int n = 0; n < 2; ++n) acc[a][b][m][n] = (f32x4){0.f, 0.f, 0.f, 0.f};
;     bf16x8 At[4][2], B0[2][2], B1[2][2];
;     const char* cA; const char* cB; S.bases(cur, g, tstep, cA, cB);
;     S.a_ready(cur);
;     if constexpr (SP2) {
;         PG8_STAGE(PG8_SB(0, 0), cB, voffB); PG8_STAGE(PG8_SB(0, 1), cB + hstep, voffB); PG8_STAGE(PG8_SA(0, 0), cA, voffA); PG8_STAGE(PG8_SA(0, 1), cA + hstep, voffA);
;         if (wr == 1) PG8_BAR;
;         PG8_WAIT_V(2); PG8_BAR;
;         PG8_STAGE(PG8_SB(1, 0), cB + kstep, voffB); PG8_STAGE(PG8_SA(1, 0), cA + kstep, voffA); PG8_STAGE(PG8_SB(1, 1), cB + hstep + kstep, voffB);
;         PG8_WAIT_V(6); PG8_BAR;
;     } else {
;         PG8_STAGE(PG8_SB(0, 0), cB, voffB); PG8_STAGE(PG8_SA(0, 0), cA, voffA); PG8_STAGE(PG8_SB(0, 1), cB + hstep, voffB); PG8_STAGE(PG8_SA(0, 1), cA + hstep, voffA);
;         if (wr == 1) PG8_BAR;
;         PG8_WAIT_V(4); PG8_BAR;
;         PG8_STAGE(PG8_SB(1, 0), cB + kstep, voffB); PG8_STAGE(PG8_SA(1, 0), cA + kstep, voffA); PG8_STAGE(PG8_SB(1, 1), cB + hstep + kstep, voffB);
;         PG8_WAIT_V(6); PG8_BAR;
;     }
;     for (;;) {
;         const bool has_next = S.next(ui + 1, nxt);
;         const char* nA = cA; const char* nB = cB; if (has_next) S.bases(nxt, g, tstep, nA, nB);
;         for (int t = 0; t < nt; t += 2) {
;             const bool last = (t == nt - 2);
;             const char* a1 = cA + (size_t)(t + 1) * kstep;
;             const char* a2 = last ? nA : cA + (size_t)(t + 2) * kstep; const char* b2 = last ? nB : cB + (size_t)(t + 2) * kstep;
;             const char* a3 = a2 + kstep; const char* b3 = b2 + kstep;
;             if (last && has_next) S.a_ready(nxt);
;             if constexpr (Epi::MIDK) { if (t == (nt >> 1)) { E.midk(acc, wr, fr); asm volatile("s_waitcnt lgkmcnt(0)" ::: "memory"); } }
;             if constexpr (SP2) {
	s_setprio 2
	v_mfma_f32_16x16x32_bf16 v[124:127], v[128:131], v[182:185], v[124:127]
	v_mfma_f32_16x16x32_bf16 v[124:127], v[132:135], v[186:189], v[124:127]
	v_mfma_f32_16x16x32_bf16 v[120:123], v[150:153], v[182:185], v[120:123]
	v_mfma_f32_16x16x32_bf16 v[120:123], v[162:165], v[186:189], v[120:123]
	v_mfma_f32_16x16x32_bf16 v[68:71], v[166:169], v[182:185], v[68:71]
	v_mfma_f32_16x16x32_bf16 v[68:71], v[170:173], v[186:189], v[68:71]
	v_mfma_f32_16x16x32_bf16 v[64:67], v[174:177], v[182:185], v[64:67]
	v_mfma_f32_16x16x32_bf16 v[64:67], v[178:181], v[186:189], v[64:67]
	v_mfma_f32_16x16x32_bf16 v[116:119], v[128:131], v[190:193], v[116:119]
	v_mfma_f32_16x16x32_bf16 v[116:119], v[132:135], v[194:197], v[116:119]
	v_mfma_f32_16x16x32_bf16 v[112:115], v[150:153], v[190:193], v[112:115]
	v_mfma_f32_16x16x32_bf16 v[112:115], v[162:165], v[194:197], v[112:115]
	v_mfma_f32_16x16x32_bf16 v[52:55], v[166:169], v[190:193], v[52:55]
	v_mfma_f32_16x16x32_bf16 v[52:55], v[170:173], v[194:197], v[52:55]
	v_mfma_f32_16x16x32_bf16 v[48:51], v[174:177], v[190:193], v[48:51]
	v_mfma_f32_16x16x32_bf16 v[48:51], v[178:181], v[194:197], v[48:51]
	v_mfma_f32_16x16x32_bf16 v[108:111], v[128:131], v[198:201], v[108:111]
	v_mfma_f32_16x16x32_bf16 v[108:111], v[132:135], v[202:205], v[108:111]
	v_mfma_f32_16x16x32_bf16 v[104:107], v[150:153], v[198:201], v[104:107]
	v_mfma_f32_16x16x32_bf16 v[104:107], v[162:165], v[202:205], v[104:107]
	v_mfma_f32_16x16x32_bf16 v[44:47], v[166:169], v[198:201], v[44:47]
	v_mfma_f32_16x16x32_bf16 v[44:47], v[170:173], v[202:205], v[44:47]
	v_mfma_f32_16x16x32_bf16 v[40:43], v[174:177], v[198:201], v[40:43]
	v_mfma_f32_16x16x32_bf16 v[40:43], v[178:181], v[202:205], v[40:43]
	v_mfma_f32_16x16x32_bf16 v[100:103], v[128:131], v[206:209], v[100:103]
	v_mfma_f32_16x16x32_bf16 v[100:103], v[132:135], v[210:213], v[100:103]
	v_mfma_f32_16x16x32_bf16 v[96:99], v[150:153], v[206:209], v[96:99]
	v_mfma_f32_16x16x32_bf16 v[96:99], v[162:165], v[210:213], v[96:99]
	v_mfma_f32_16x16x32_bf16 v[36:39], v[166:169], v[206:209], v[36:39]
	v_mfma_f32_16x16x32_bf16 v[36:39], v[170:173], v[210:213], v[36:39]
	v_mfma_f32_16x16x32_bf16 v[32:35], v[174:177], v[206:209], v[32:35]
	v_mfma_f32_16x16x32_bf16 v[32:35], v[178:181], v[210:213], v[32:35]
	s_setprio 0
	ds_read_b128 v[182:185], v158 offset:49152
	ds_read_b128 v[186:189], v158 offset:50176
	ds_read_b128 v[190:193], v158 offset:51200
	ds_read_b128 v[194:197], v158 offset:52224
	ds_read_b128 v[198:201], v158 offset:53248
	ds_read_b128 v[202:205], v158 offset:54272
	ds_read_b128 v[206:209], v158 offset:55296
	ds_read_b128 v[210:213], v158 offset:56320
	s_add_u32 s60, s20, 0x80
	s_addc_u32 s61, s21, 0
	s_add_u32 vcc_lo, s60, 0x404000
	s_addc_u32 vcc_hi, s61, 0
	s_add_i32 m0, s24, 0x18000
	s_nop 0
	global_load_lds_dwordx4 v138, s[60:61]
	s_add_i32 m0, s24, 0x1a000
	s_nop 0
	global_load_lds_dwordx4 v142, s[60:61]
	s_add_i32 m0, s24, 0x1c000
	s_nop 0
	global_load_lds_dwordx4 v138, vcc
	s_add_i32 m0, s24, 0x1e000
	s_nop 0
	global_load_lds_dwordx4 v142, vcc
	s_add_u32 s60, s22, 0x80
	s_addc_u32 s61, s23, 0
	s_add_i32 m0, s24, 0x8000
	s_nop 0
	global_load_lds_dwordx4 v136, s[60:61]
	s_add_i32 m0, s24, 0xa000
	s_nop 0
	global_load_lds_dwordx4 v140, s[60:61]
	s_sleep 2
	s_waitcnt lgkmcnt(0)
	s_waitcnt vmcnt(8)
	s_barrier
	s_setprio 2
	v_mfma_f32_16x16x32_bf16 v[92:95], v[128:131], v[182:185], v[92:95]
	v_mfma_f32_16x16x32_bf16 v[92:95], v[132:135], v[186:189], v[92:95]
	v_mfma_f32_16x16x32_bf16 v[88:91], v[150:153], v[182:185], v[88:91]
	v_mfma_f32_16x16x32_bf16 v[88:91], v[162:165], v[186:189], v[88:91]
	v_mfma_f32_16x16x32_bf16 v[28:31], v[166:169], v[182:185], v[28:31]
	v_mfma_f32_16x16x32_bf16 v[28:31], v[170:173], v[186:189], v[28:31]
	v_mfma_f32_16x16x32_bf16 v[24:27], v[174:177], v[182:185], v[24:27]
	v_mfma_f32_16x16x32_bf16 v[24:27], v[178:181], v[186:189], v[24:27]
	v_mfma_f32_16x16x32_bf16 v[84:87], v[128:131], v[190:193], v[84:87]
	v_mfma_f32_16x16x32_bf16 v[84:87], v[132:135], v[194:197], v[84:87]
	v_mfma_f32_16x16x32_bf16 v[80:83], v[150:153], v[190:193], v[80:83]
	v_mfma_f32_16x16x32_bf16 v[80:83], v[162:165], v[194:197], v[80:83]
	v_mfma_f32_16x16x32_bf16 v[20:23], v[166:169], v[190:193], v[20:23]
	v_mfma_f32_16x16x32_bf16 v[20:23], v[170:173], v[194:197], v[20:23]
	v_mfma_f32_16x16x32_bf16 v[16:19], v[174:177], v[190:193], v[16:19]
	v_mfma_f32_16x16x32_bf16 v[16:19], v[178:181], v[194:197], v[16:19]
	v_mfma_f32_16x16x32_bf16 v[76:79], v[128:131], v[198:201], v[76:79]
	v_mfma_f32_16x16x32_bf16 v[76:79], v[132:135], v[202:205], v[76:79]
	v_mfma_f32_16x16x32_bf16 v[72:75], v[150:153], v[198:201], v[72:75]
	v_mfma_f32_16x16x32_bf16 v[72:75], v[162:165], v[202:205], v[72:75]
	v_mfma_f32_16x16x32_bf16 v[12:15], v[166:169], v[198:201], v[12:15]
	v_mfma_f32_16x16x32_bf16 v[12:15], v[170:173], v[202:205], v[12:15]
	v_mfma_f32_16x16x32_bf16 v[8:11], v[174:177], v[198:201], v[8:11]
	v_mfma_f32_16x16x32_bf16 v[8:11], v[178:181], v[202:205], v[8:11]
	v_mfma_f32_16x16x32_bf16 v[60:63], v[128:131], v[206:209], v[60:63]
	v_mfma_f32_16x16x32_bf16 v[60:63], v[132:135], v[210:213], v[60:63]
	v_mfma_f32_16x16x32_bf16 v[56:59], v[150:153], v[206:209], v[56:59]
	v_mfma_f32_16x16x32_bf16 v[56:59], v[162:165], v[210:213], v[56:59]
	v_mfma_f32_16x16x32_bf16 v[4:7], v[166:169], v[206:209], v[4:7]
	v_mfma_f32_16x16x32_bf16 v[4:7], v[170:173], v[210:213], v[4:7]
	v_mfma_f32_16x16x32_bf16 v[0:3], v[174:177], v[206:209], v[0:3]
	v_mfma_f32_16x16x32_bf16 v[0:3], v[178:181], v[210:213], v[0:3]
	s_setprio 0
	s_add_i32 s59, s59, 2
	s_add_u32 s18, s18, 0x100
	s_addc_u32 s19, s19, 0
	s_add_u32 s57, s57, 0x100
	s_addc_u32 s58, s58, 0
	s_cmpk_gt_u32 s59, 0xfd
	s_cbranch_scc0 .Lf2_h1
